# GEMM K-loops: removed the mid-segment s_setprio 0 / s_setprio 1 pair between the two 16-MFMA runs (36 sites), boundary priority changes kept
# baseline (speedup 1.0000x reference)
; #define PG8_STAGE(bufoff, gbase, voff) do { _Pragma("unroll") for (int _i = 0; _i < 2; ++_i) \
;         __builtin_amdgcn_global_load_lds((const unsigned*)((const char*)(gbase) + (voff)[_i]), (PG8_LAS unsigned*)(lds + (bufoff) + ldsw + _i * 8192), 16, 0, 0); } while (0)
; #define PG8_LDA(dst, b, h) do { _Pragma("unroll") for (int m = 0; m < 4; ++m) _Pragma("unroll") for (int k = 0; k < 2; ++k) dst[m][k] = *(const PG8_LAS bf16x8*)(lds + PG8_SA(b, h) + aoff + m * 2048 + k * 1024); } while (0)
; #define PG8_LDB(dst, b, h) do { _Pragma("unroll") for (int n = 0; n < 2; ++n) _Pragma("unroll") for (int k = 0; k < 2; ++k) dst[n][k] = *(const PG8_LAS bf16x8*)(lds + PG8_SB(b, h) + boff + n * 2048 + k * 1024); } while (0)
; #define PG8_MMA(ai, bj, At, Bt) do { __builtin_amdgcn_s_setprio(1); _Pragma("unroll") for (int m = 0; m < 4; ++m) _Pragma("unroll") for (int n = 0; n < 2; ++n) _Pragma("unroll") for (int k = 0; k < 2; ++k) \
;         acc[ai][bj][m][n] = __builtin_amdgcn_mfma_f32_16x16x32_bf16(Bt[n][k], At[m][k], acc[ai][bj][m][n], 0, 0, 0); __builtin_amdgcn_s_setprio(0); } while (0)
; #define PG8_WAIT_V(n) asm volatile("s_waitcnt vmcnt(" #n ")" ::: "memory")
; #define PG8_WAIT_L(n) asm volatile("s_waitcnt lgkmcnt(" #n ")" ::: "memory")
; #define PG8_BAR __builtin_amdgcn_s_barrier()
; #define PG8_SCHED __builtin_amdgcn_sched_barrier(0)
; template <class Epi, class Sched, bool ALIGN_EPI = false, bool SP2 = false>
; __device__ __forceinline__ void gemm_phase(PG8_LAS unsigned char* lds, const Gemm g, const Sched& S, const Epi& E) {
;     ...
;             PG8_LDB(B0, 0, 0); PG8_LDB(B1, 0, 1); PG8_SCHED; PG8_LDA(At, 0, 0); PG8_STAGE(PG8_SA(1, 1), a1 + hstep, voffA);
;             PG8_WAIT_V(8); PG8_WAIT_L(0); PG8_BAR; PG8_MMA(0, 0, At, B0); PG8_MMA(0, 1, At, B1); PG8_BAR; PG8_SCHED;
;             PG8_LDA(At, 0, 1); PG8_STAGE(PG8_SB(0, 0), b2, voffB); PG8_STAGE(PG8_SB(0, 1), b2 + hstep, voffB); PG8_STAGE(PG8_SA(0, 0), a2, voffA);
.LBB0_95:
	ds_read_b128 v[144:147], v155
	ds_read_b128 v[148:151], v155 offset:1024
	ds_read_b128 v[158:161], v155 offset:2048
	ds_read_b128 v[162:165], v155 offset:3072
	ds_read_b128 v[166:169], v156
	ds_read_b128 v[170:173], v156 offset:1024
	ds_read_b128 v[174:177], v156 offset:2048
	ds_read_b128 v[178:181], v156 offset:3072
	s_add_u32 s0, s80, 0xfff80080
	s_addc_u32 s1, s81, -1
	s_cmp_eq_u32 s56, 28
	s_cselect_b32 s83, s23, s1
	s_cselect_b32 s82, s52, s0
	s_cselect_b32 s1, s21, s55
	s_cselect_b32 s0, s53, s54
	v_lshl_add_u64 v[214:215], s[80:81], 0, v[136:137]
	s_add_i32 m0, s36, 0xc000
	ds_read_b128 v[182:185], v157
	ds_read_b128 v[186:189], v157 offset:1024
	ds_read_b128 v[190:193], v157 offset:2048
	ds_read_b128 v[194:197], v157 offset:3072
	ds_read_b128 v[198:201], v157 offset:4096
	ds_read_b128 v[202:205], v157 offset:5120
	ds_read_b128 v[206:209], v157 offset:6144
	ds_read_b128 v[210:213], v157 offset:7168
	global_load_lds_dwordx4 v[214:215], off
	v_lshl_add_u64 v[214:215], s[80:81], 0, v[138:139]
	s_add_i32 m0, s36, 0xe000
	s_nop 0
	global_load_lds_dwordx4 v[214:215], off
	s_waitcnt vmcnt(8)
	s_waitcnt lgkmcnt(0)
	s_barrier
	s_setprio 1
	s_waitcnt lgkmcnt(0)
	v_mfma_f32_16x16x32_bf16 v[124:127], v[144:147], v[182:185], v[124:127]
	v_mfma_f32_16x16x32_bf16 v[120:123], v[158:161], v[182:185], v[120:123]
	v_mfma_f32_16x16x32_bf16 v[108:111], v[144:147], v[190:193], v[108:111]
	v_mfma_f32_16x16x32_bf16 v[104:107], v[158:161], v[190:193], v[104:107]
	v_mfma_f32_16x16x32_bf16 v[92:95], v[144:147], v[198:201], v[92:95]
	v_mfma_f32_16x16x32_bf16 v[88:91], v[158:161], v[198:201], v[88:91]
	v_mfma_f32_16x16x32_bf16 v[76:79], v[144:147], v[206:209], v[76:79]
	v_mfma_f32_16x16x32_bf16 v[72:75], v[158:161], v[206:209], v[72:75]
	v_mfma_f32_16x16x32_bf16 v[124:127], v[148:151], v[186:189], v[124:127]
	v_mfma_f32_16x16x32_bf16 v[120:123], v[162:165], v[186:189], v[120:123]
	v_mfma_f32_16x16x32_bf16 v[108:111], v[148:151], v[194:197], v[108:111]
	v_mfma_f32_16x16x32_bf16 v[104:107], v[162:165], v[194:197], v[104:107]
	v_mfma_f32_16x16x32_bf16 v[92:95], v[148:151], v[202:205], v[92:95]
	v_mfma_f32_16x16x32_bf16 v[88:91], v[162:165], v[202:205], v[88:91]
	v_mfma_f32_16x16x32_bf16 v[76:79], v[148:151], v[210:213], v[76:79]
	v_mfma_f32_16x16x32_bf16 v[72:75], v[162:165], v[210:213], v[72:75]
	v_mfma_f32_16x16x32_bf16 v[116:119], v[166:169], v[182:185], v[116:119]
	v_mfma_f32_16x16x32_bf16 v[112:115], v[174:177], v[182:185], v[112:115]
	v_mfma_f32_16x16x32_bf16 v[100:103], v[166:169], v[190:193], v[100:103]
	v_mfma_f32_16x16x32_bf16 v[96:99], v[174:177], v[190:193], v[96:99]
	v_mfma_f32_16x16x32_bf16 v[84:87], v[166:169], v[198:201], v[84:87]
	v_mfma_f32_16x16x32_bf16 v[80:83], v[174:177], v[198:201], v[80:83]
	v_mfma_f32_16x16x32_bf16 v[68:71], v[166:169], v[206:209], v[68:71]
	v_mfma_f32_16x16x32_bf16 v[64:67], v[174:177], v[206:209], v[64:67]
	v_mfma_f32_16x16x32_bf16 v[116:119], v[170:173], v[186:189], v[116:119]
	v_mfma_f32_16x16x32_bf16 v[112:115], v[178:181], v[186:189], v[112:115]
	v_mfma_f32_16x16x32_bf16 v[100:103], v[170:173], v[194:197], v[100:103]
	v_mfma_f32_16x16x32_bf16 v[96:99], v[178:181], v[194:197], v[96:99]
	v_mfma_f32_16x16x32_bf16 v[84:87], v[170:173], v[202:205], v[84:87]
	v_mfma_f32_16x16x32_bf16 v[80:83], v[178:181], v[202:205], v[80:83]
	v_mfma_f32_16x16x32_bf16 v[68:71], v[170:173], v[210:213], v[68:71]
	v_mfma_f32_16x16x32_bf16 v[64:67], v[178:181], v[210:213], v[64:67]
	s_setprio 0
	s_barrier
	s_add_i32 s57, s45, s3
	v_lshl_add_u64 v[214:215], s[0:1], 0, v[132:133]
	s_mov_b32 m0, s57
	ds_read_b128 v[182:185], v157 offset:16384
	ds_read_b128 v[186:189], v157 offset:17408
	ds_read_b128 v[190:193], v157 offset:18432
	ds_read_b128 v[194:197], v157 offset:19456
	ds_read_b128 v[198:201], v157 offset:20480
	ds_read_b128 v[202:205], v157 offset:21504
	ds_read_b128 v[206:209], v157 offset:22528
	ds_read_b128 v[210:213], v157 offset:23552
	global_load_lds_dwordx4 v[214:215], off
	s_add_i32 m0, s57, 0x2000
	s_add_u32 s58, s0, 0x80000
	v_lshl_add_u64 v[216:217], s[0:1], 0, v[128:129]
	s_addc_u32 s59, s1, 0
	s_add_i32 s57, s46, s3
	global_load_lds_dwordx4 v[216:217], off
	v_lshl_add_u64 v[218:219], s[58:59], 0, v[132:133]
	s_mov_b32 m0, s57
	v_lshl_add_u64 v[220:221], s[82:83], 0, v[130:131]
	global_load_lds_dwordx4 v[218:219], off
	v_lshl_add_u64 v[218:219], s[58:59], 0, v[128:129]
	s_add_i32 m0, s57, 0x2000
	s_nop 0
	global_load_lds_dwordx4 v[218:219], off
	v_lshl_add_u64 v[218:219], s[82:83], 0, v[134:135]
	s_mov_b32 m0, s36
	s_nop 0
	global_load_lds_dwordx4 v[218:219], off
	s_mov_b32 m0, s37
	s_nop 0
	global_load_lds_dwordx4 v[220:221], off
	s_waitcnt vmcnt(8)
	s_waitcnt lgkmcnt(0)
	s_barrier
; #define PG8_STAGE(bufoff, gbase, voff) do { _Pragma("unroll") for (int _i = 0; _i < 2; ++_i) \
;         __builtin_amdgcn_global_load_lds((const unsigned*)((const char*)(gbase) + (voff)[_i]), (PG8_LAS unsigned*)(lds + (bufoff) + ldsw + _i * 8192), 16, 0, 0); } while (0)
; #define PG8_LDA(dst, b, h) do { _Pragma("unroll") for (int m = 0; m < 4; ++m) _Pragma("unroll") for (int k = 0; k < 2; ++k) dst[m][k] = *(const PG8_LAS bf16x8*)(lds + PG8_SA(b, h) + aoff + m * 2048 + k * 1024); } while (0)
; #define PG8_LDB(dst, b, h) do { _Pragma("unroll") for (int n = 0; n < 2; ++n) _Pragma("unroll") for (int k = 0; k < 2; ++k) dst[n][k] = *(const PG8_LAS bf16x8*)(lds + PG8_SB(b, h) + boff + n * 2048 + k * 1024); } while (0)
; #define PG8_MMA(ai, bj, At, Bt) do { __builtin_amdgcn_s_setprio(1); _Pragma("unroll") for (int m = 0; m < 4; ++m) _Pragma("unroll") for (int n = 0; n < 2; ++n) _Pragma("unroll") for (int k = 0; k < 2; ++k) \
;         acc[ai][bj][m][n] = __builtin_amdgcn_mfma_f32_16x16x32_bf16(Bt[n][k], At[m][k], acc[ai][bj][m][n], 0, 0, 0); __builtin_amdgcn_s_setprio(0); } while (0)
; #define PG8_WAIT_V(n) asm volatile("s_waitcnt vmcnt(" #n ")" ::: "memory")
; #define PG8_WAIT_L(n) asm volatile("s_waitcnt lgkmcnt(" #n ")" ::: "memory")
; #define PG8_BAR __builtin_amdgcn_s_barrier()
; #define PG8_SCHED __builtin_amdgcn_sched_barrier(0)
; template <class Epi, class Sched, bool ALIGN_EPI = false, bool SP2 = false>
; __device__ __forceinline__ void gemm_phase(PG8_LAS unsigned char* lds, const Gemm g, const Sched& S, const Epi& E) {
;     ...
;             PG8_WAIT_V(8); PG8_WAIT_L(0); PG8_BAR; PG8_MMA(1, 0, At, B0); PG8_MMA(1, 1, At, B1); PG8_BAR; PG8_SCHED;
;             PG8_LDB(B0, 1, 0); PG8_LDB(B1, 1, 1); PG8_SCHED; PG8_LDA(At, 1, 0); PG8_STAGE(PG8_SA(0, 1), a2 + hstep, voffA);
;             PG8_WAIT_V(8); PG8_WAIT_L(0); PG8_BAR; PG8_MMA(0, 0, At, B0); PG8_MMA(0, 1, At, B1); PG8_BAR; PG8_SCHED;
	s_setprio 1
	s_waitcnt lgkmcnt(0)
	v_mfma_f32_16x16x32_bf16 v[60:63], v[144:147], v[182:185], v[60:63]
	v_mfma_f32_16x16x32_bf16 v[56:59], v[158:161], v[182:185], v[56:59]
	v_mfma_f32_16x16x32_bf16 v[44:47], v[144:147], v[190:193], v[44:47]
	v_mfma_f32_16x16x32_bf16 v[40:43], v[158:161], v[190:193], v[40:43]
	v_mfma_f32_16x16x32_bf16 v[28:31], v[144:147], v[198:201], v[28:31]
	v_mfma_f32_16x16x32_bf16 v[24:27], v[158:161], v[198:201], v[24:27]
	v_mfma_f32_16x16x32_bf16 v[12:15], v[144:147], v[206:209], v[12:15]
	v_mfma_f32_16x16x32_bf16 v[8:11], v[158:161], v[206:209], v[8:11]
	v_mfma_f32_16x16x32_bf16 v[60:63], v[148:151], v[186:189], v[60:63]
	v_mfma_f32_16x16x32_bf16 v[56:59], v[162:165], v[186:189], v[56:59]
	v_mfma_f32_16x16x32_bf16 v[44:47], v[148:151], v[194:197], v[44:47]
	v_mfma_f32_16x16x32_bf16 v[40:43], v[162:165], v[194:197], v[40:43]
	v_mfma_f32_16x16x32_bf16 v[28:31], v[148:151], v[202:205], v[28:31]
	v_mfma_f32_16x16x32_bf16 v[24:27], v[162:165], v[202:205], v[24:27]
	v_mfma_f32_16x16x32_bf16 v[12:15], v[148:151], v[210:213], v[12:15]
	v_mfma_f32_16x16x32_bf16 v[8:11], v[162:165], v[210:213], v[8:11]
	v_mfma_f32_16x16x32_bf16 v[52:55], v[166:169], v[182:185], v[52:55]
	v_mfma_f32_16x16x32_bf16 v[48:51], v[174:177], v[182:185], v[48:51]
	v_mfma_f32_16x16x32_bf16 v[36:39], v[166:169], v[190:193], v[36:39]
	v_mfma_f32_16x16x32_bf16 v[32:35], v[174:177], v[190:193], v[32:35]
	v_mfma_f32_16x16x32_bf16 v[20:23], v[166:169], v[198:201], v[20:23]
	v_mfma_f32_16x16x32_bf16 v[16:19], v[174:177], v[198:201], v[16:19]
	v_mfma_f32_16x16x32_bf16 v[4:7], v[166:169], v[206:209], v[4:7]
	v_mfma_f32_16x16x32_bf16 v[0:3], v[174:177], v[206:209], v[0:3]
	v_mfma_f32_16x16x32_bf16 v[52:55], v[170:173], v[186:189], v[52:55]
	v_mfma_f32_16x16x32_bf16 v[48:51], v[178:181], v[186:189], v[48:51]
	v_mfma_f32_16x16x32_bf16 v[36:39], v[170:173], v[194:197], v[36:39]
	v_mfma_f32_16x16x32_bf16 v[32:35], v[178:181], v[194:197], v[32:35]
	v_mfma_f32_16x16x32_bf16 v[20:23], v[170:173], v[202:205], v[20:23]
	v_mfma_f32_16x16x32_bf16 v[16:19], v[178:181], v[202:205], v[16:19]
	v_mfma_f32_16x16x32_bf16 v[4:7], v[170:173], v[210:213], v[4:7]
	v_mfma_f32_16x16x32_bf16 v[0:3], v[178:181], v[210:213], v[0:3]
	s_setprio 0
	s_barrier
	s_add_i32 s57, 0, 0x18000
	s_add_i32 s65, 0, 0x1c000
	v_add_u32_e32 v162, s57, v153
	v_add_u32_e32 v178, s65, v153
	ds_read_b128 v[144:147], v162
	ds_read_b128 v[148:151], v162 offset:1024
	ds_read_b128 v[158:161], v162 offset:2048
	ds_read_b128 v[162:165], v162 offset:3072
	ds_read_b128 v[166:169], v178
	ds_read_b128 v[170:173], v178 offset:1024
	ds_read_b128 v[174:177], v178 offset:2048
	ds_read_b128 v[178:181], v178 offset:3072
	s_add_u32 s58, s82, 0x80000
	s_addc_u32 s59, s83, 0
	s_mov_b32 m0, s38
	v_lshl_add_u64 v[228:229], s[58:59], 0, v[134:135]
	ds_read_b128 v[182:185], v157 offset:32768
	ds_read_b128 v[186:189], v157 offset:33792
	ds_read_b128 v[190:193], v157 offset:34816
	ds_read_b128 v[194:197], v157 offset:35840
	ds_read_b128 v[198:201], v157 offset:36864
	ds_read_b128 v[202:205], v157 offset:37888
	ds_read_b128 v[206:209], v157 offset:38912
	ds_read_b128 v[210:213], v157 offset:39936
	global_load_lds_dwordx4 v[228:229], off
	v_lshl_add_u64 v[228:229], s[58:59], 0, v[130:131]
	s_mov_b32 m0, s39
	s_nop 0
	global_load_lds_dwordx4 v[228:229], off
	s_waitcnt vmcnt(8)
	s_waitcnt lgkmcnt(0)
	s_barrier
	s_setprio 1
	s_waitcnt lgkmcnt(0)
	v_mfma_f32_16x16x32_bf16 v[124:127], v[144:147], v[182:185], v[124:127]
	v_mfma_f32_16x16x32_bf16 v[120:123], v[158:161], v[182:185], v[120:123]
	v_mfma_f32_16x16x32_bf16 v[108:111], v[144:147], v[190:193], v[108:111]
	v_mfma_f32_16x16x32_bf16 v[104:107], v[158:161], v[190:193], v[104:107]
	v_mfma_f32_16x16x32_bf16 v[92:95], v[144:147], v[198:201], v[92:95]
	v_mfma_f32_16x16x32_bf16 v[88:91], v[158:161], v[198:201], v[88:91]
	v_mfma_f32_16x16x32_bf16 v[76:79], v[144:147], v[206:209], v[76:79]
	v_mfma_f32_16x16x32_bf16 v[72:75], v[158:161], v[206:209], v[72:75]
	v_mfma_f32_16x16x32_bf16 v[124:127], v[148:151], v[186:189], v[124:127]
	v_mfma_f32_16x16x32_bf16 v[120:123], v[162:165], v[186:189], v[120:123]
	v_mfma_f32_16x16x32_bf16 v[108:111], v[148:151], v[194:197], v[108:111]
	v_mfma_f32_16x16x32_bf16 v[104:107], v[162:165], v[194:197], v[104:107]
	v_mfma_f32_16x16x32_bf16 v[92:95], v[148:151], v[202:205], v[92:95]
	v_mfma_f32_16x16x32_bf16 v[88:91], v[162:165], v[202:205], v[88:91]
	v_mfma_f32_16x16x32_bf16 v[76:79], v[148:151], v[210:213], v[76:79]
	v_mfma_f32_16x16x32_bf16 v[72:75], v[162:165], v[210:213], v[72:75]
	v_mfma_f32_16x16x32_bf16 v[116:119], v[166:169], v[182:185], v[116:119]
	v_mfma_f32_16x16x32_bf16 v[112:115], v[174:177], v[182:185], v[112:115]
	v_mfma_f32_16x16x32_bf16 v[100:103], v[166:169], v[190:193], v[100:103]
	v_mfma_f32_16x16x32_bf16 v[96:99], v[174:177], v[190:193], v[96:99]
	v_mfma_f32_16x16x32_bf16 v[84:87], v[166:169], v[198:201], v[84:87]
	v_mfma_f32_16x16x32_bf16 v[80:83], v[174:177], v[198:201], v[80:83]
	v_mfma_f32_16x16x32_bf16 v[68:71], v[166:169], v[206:209], v[68:71]
	v_mfma_f32_16x16x32_bf16 v[64:67], v[174:177], v[206:209], v[64:67]
	v_mfma_f32_16x16x32_bf16 v[116:119], v[170:173], v[186:189], v[116:119]
	v_mfma_f32_16x16x32_bf16 v[112:115], v[178:181], v[186:189], v[112:115]
	v_mfma_f32_16x16x32_bf16 v[100:103], v[170:173], v[194:197], v[100:103]
	v_mfma_f32_16x16x32_bf16 v[96:99], v[178:181], v[194:197], v[96:99]
	v_mfma_f32_16x16x32_bf16 v[84:87], v[170:173], v[202:205], v[84:87]
	v_mfma_f32_16x16x32_bf16 v[80:83], v[178:181], v[202:205], v[80:83]
	v_mfma_f32_16x16x32_bf16 v[68:71], v[170:173], v[210:213], v[68:71]
	v_mfma_f32_16x16x32_bf16 v[64:67], v[178:181], v[210:213], v[64:67]
	s_setprio 0
	s_barrier
; #define PG8_STAGE(bufoff, gbase, voff) do { _Pragma("unroll") for (int _i = 0; _i < 2; ++_i) \
;         __builtin_amdgcn_global_load_lds((const unsigned*)((const char*)(gbase) + (voff)[_i]), (PG8_LAS unsigned*)(lds + (bufoff) + ldsw + _i * 8192), 16, 0, 0); } while (0)
; #define PG8_LDA(dst, b, h) do { _Pragma("unroll") for (int m = 0; m < 4; ++m) _Pragma("unroll") for (int k = 0; k < 2; ++k) dst[m][k] = *(const PG8_LAS bf16x8*)(lds + PG8_SA(b, h) + aoff + m * 2048 + k * 1024); } while (0)
; #define PG8_MMA(ai, bj, At, Bt) do { __builtin_amdgcn_s_setprio(1); _Pragma("unroll") for (int m = 0; m < 4; ++m) _Pragma("unroll") for (int n = 0; n < 2; ++n) _Pragma("unroll") for (int k = 0; k < 2; ++k) \
;         acc[ai][bj][m][n] = __builtin_amdgcn_mfma_f32_16x16x32_bf16(Bt[n][k], At[m][k], acc[ai][bj][m][n], 0, 0, 0); __builtin_amdgcn_s_setprio(0); } while (0)
; #define PG8_WAIT_V(n) asm volatile("s_waitcnt vmcnt(" #n ")" ::: "memory")
; #define PG8_WAIT_L(n) asm volatile("s_waitcnt lgkmcnt(" #n ")" ::: "memory")
; #define PG8_BAR __builtin_amdgcn_s_barrier()
; #define PG8_SCHED __builtin_amdgcn_sched_barrier(0)
; template <class Epi, class Sched, bool ALIGN_EPI = false, bool SP2 = false>
; __device__ __forceinline__ void gemm_phase(PG8_LAS unsigned char* lds, const Gemm g, const Sched& S, const Epi& E) {
;     ...
;             PG8_LDA(At, 1, 1); PG8_STAGE(PG8_SB(1, 0), b3, voffB); PG8_STAGE(PG8_SB(1, 1), b3 + hstep, voffB); PG8_STAGE(PG8_SA(1, 0), a3, voffA);
;             PG8_WAIT_V(8); PG8_WAIT_L(0); PG8_BAR; PG8_MMA(1, 0, At, B0); PG8_MMA(1, 1, At, B1); PG8_BAR; PG8_SCHED;
;     ...
;         if constexpr (ALIGN_EPI) { if (wr == 0) PG8_BAR; }
	s_add_i32 s57, s57, s3
	v_lshl_add_u64 v[214:215], v[214:215], 0, s[12:13]
	s_mov_b32 m0, s57
	ds_read_b128 v[182:185], v157 offset:49152
	ds_read_b128 v[186:189], v157 offset:50176
	ds_read_b128 v[190:193], v157 offset:51200
	ds_read_b128 v[194:197], v157 offset:52224
	ds_read_b128 v[198:201], v157 offset:53248
	ds_read_b128 v[202:205], v157 offset:54272
	ds_read_b128 v[206:209], v157 offset:55296
	ds_read_b128 v[210:213], v157 offset:56320
	global_load_lds_dwordx4 v[214:215], off
	s_add_i32 m0, s57, 0x2000
	s_add_u32 s0, s0, 0x80080
	v_lshl_add_u64 v[214:215], v[216:217], 0, s[12:13]
	s_addc_u32 s1, s1, 0
	s_add_i32 s57, s65, s3
	global_load_lds_dwordx4 v[214:215], off
	v_lshl_add_u64 v[214:215], s[0:1], 0, v[132:133]
	s_mov_b32 m0, s57
	s_nop 0
	global_load_lds_dwordx4 v[214:215], off
	v_lshl_add_u64 v[214:215], s[0:1], 0, v[128:129]
	s_add_i32 m0, s57, 0x2000
	s_nop 0
	global_load_lds_dwordx4 v[214:215], off
	v_lshl_add_u64 v[214:215], v[218:219], 0, s[12:13]
	s_mov_b32 m0, s41
	s_nop 0
	global_load_lds_dwordx4 v[214:215], off
	v_lshl_add_u64 v[214:215], v[220:221], 0, s[12:13]
	s_mov_b32 m0, s42
	s_nop 0
	global_load_lds_dwordx4 v[214:215], off
	s_waitcnt vmcnt(8)
	s_waitcnt lgkmcnt(0)
	s_barrier
	s_setprio 1
	s_waitcnt lgkmcnt(0)
	v_mfma_f32_16x16x32_bf16 v[60:63], v[144:147], v[182:185], v[60:63]
	v_mfma_f32_16x16x32_bf16 v[56:59], v[158:161], v[182:185], v[56:59]
	v_mfma_f32_16x16x32_bf16 v[44:47], v[144:147], v[190:193], v[44:47]
	v_mfma_f32_16x16x32_bf16 v[40:43], v[158:161], v[190:193], v[40:43]
	v_mfma_f32_16x16x32_bf16 v[28:31], v[144:147], v[198:201], v[28:31]
	v_mfma_f32_16x16x32_bf16 v[24:27], v[158:161], v[198:201], v[24:27]
	v_mfma_f32_16x16x32_bf16 v[12:15], v[144:147], v[206:209], v[12:15]
	v_mfma_f32_16x16x32_bf16 v[8:11], v[158:161], v[206:209], v[8:11]
	v_mfma_f32_16x16x32_bf16 v[60:63], v[148:151], v[186:189], v[60:63]
	v_mfma_f32_16x16x32_bf16 v[56:59], v[162:165], v[186:189], v[56:59]
	v_mfma_f32_16x16x32_bf16 v[44:47], v[148:151], v[194:197], v[44:47]
	v_mfma_f32_16x16x32_bf16 v[40:43], v[162:165], v[194:197], v[40:43]
	v_mfma_f32_16x16x32_bf16 v[28:31], v[148:151], v[202:205], v[28:31]
	v_mfma_f32_16x16x32_bf16 v[24:27], v[162:165], v[202:205], v[24:27]
	v_mfma_f32_16x16x32_bf16 v[12:15], v[148:151], v[210:213], v[12:15]
	v_mfma_f32_16x16x32_bf16 v[8:11], v[162:165], v[210:213], v[8:11]
	v_mfma_f32_16x16x32_bf16 v[52:55], v[166:169], v[182:185], v[52:55]
	v_mfma_f32_16x16x32_bf16 v[48:51], v[174:177], v[182:185], v[48:51]
	v_mfma_f32_16x16x32_bf16 v[36:39], v[166:169], v[190:193], v[36:39]
	v_mfma_f32_16x16x32_bf16 v[32:35], v[174:177], v[190:193], v[32:35]
	v_mfma_f32_16x16x32_bf16 v[20:23], v[166:169], v[198:201], v[20:23]
	v_mfma_f32_16x16x32_bf16 v[16:19], v[174:177], v[198:201], v[16:19]
	v_mfma_f32_16x16x32_bf16 v[4:7], v[166:169], v[206:209], v[4:7]
	v_mfma_f32_16x16x32_bf16 v[0:3], v[174:177], v[206:209], v[0:3]
	v_mfma_f32_16x16x32_bf16 v[52:55], v[170:173], v[186:189], v[52:55]
	v_mfma_f32_16x16x32_bf16 v[48:51], v[178:181], v[186:189], v[48:51]
	v_mfma_f32_16x16x32_bf16 v[36:39], v[170:173], v[194:197], v[36:39]
	v_mfma_f32_16x16x32_bf16 v[32:35], v[178:181], v[194:197], v[32:35]
	v_mfma_f32_16x16x32_bf16 v[20:23], v[170:173], v[202:205], v[20:23]
	v_mfma_f32_16x16x32_bf16 v[16:19], v[178:181], v[202:205], v[16:19]
	v_mfma_f32_16x16x32_bf16 v[4:7], v[170:173], v[210:213], v[4:7]
	v_mfma_f32_16x16x32_bf16 v[0:3], v[178:181], v[210:213], v[0:3]
	s_setprio 0
	s_barrier
	s_add_i32 s56, s56, 2
	s_add_u32 s80, s80, 0x100
	s_addc_u32 s81, s81, 0
	s_add_u32 s54, s54, 0x100
	s_addc_u32 s55, s55, 0
	s_cmp_gt_u32 s56, 29
	s_cbranch_scc0 .LBB0_95
	s_and_b64 vcc, exec, s[14:15]
	s_cbranch_vccz .LBB0_98
	s_barrier

; #define PG8_STAGE(bufoff, gbase, voff) do { _Pragma("unroll") for (int _i = 0; _i < 2; ++_i) \
;         __builtin_amdgcn_global_load_lds((const unsigned*)((const char*)(gbase) + (voff)[_i]), (PG8_LAS unsigned*)(lds + (bufoff) + ldsw + _i * 8192), 16, 0, 0); } while (0)
; #define PG8_LDA(dst, b, h) do { _Pragma("unroll") for (int m = 0; m < 4; ++m) _Pragma("unroll") for (int k = 0; k < 2; ++k) dst[m][k] = *(const PG8_LAS bf16x8*)(lds + PG8_SA(b, h) + aoff + m * 2048 + k * 1024); } while (0)
; #define PG8_LDB(dst, b, h) do { _Pragma("unroll") for (int n = 0; n < 2; ++n) _Pragma("unroll") for (int k = 0; k < 2; ++k) dst[n][k] = *(const PG8_LAS bf16x8*)(lds + PG8_SB(b, h) + boff + n * 2048 + k * 1024); } while (0)
; #define PG8_MMA(ai, bj, At, Bt) do { __builtin_amdgcn_s_setprio(1); _Pragma("unroll") for (int m = 0; m < 4; ++m) _Pragma("unroll") for (int n = 0; n < 2; ++n) _Pragma("unroll") for (int k = 0; k < 2; ++k) \
;         acc[ai][bj][m][n] = __builtin_amdgcn_mfma_f32_16x16x32_bf16(Bt[n][k], At[m][k], acc[ai][bj][m][n], 0, 0, 0); __builtin_amdgcn_s_setprio(0); } while (0)
; #define PG8_WAIT_V(n) asm volatile("s_waitcnt vmcnt(" #n ")" ::: "memory")
; #define PG8_WAIT_L(n) asm volatile("s_waitcnt lgkmcnt(" #n ")" ::: "memory")
; #define PG8_BAR __builtin_amdgcn_s_barrier()
; #define PG8_SCHED __builtin_amdgcn_sched_barrier(0)
; template <class Epi, class Sched, bool ALIGN_EPI = false, bool SP2 = false>
; __device__ __forceinline__ void gemm_phase(PG8_LAS unsigned char* lds, const Gemm g, const Sched& S, const Epi& E) {
;     ...
;             PG8_LDB(B0, 0, 0); PG8_LDB(B1, 0, 1); PG8_SCHED; PG8_LDA(At, 0, 0); PG8_STAGE(PG8_SA(1, 1), a1 + hstep, voffA);
;             PG8_WAIT_V(8); PG8_WAIT_L(0); PG8_BAR; PG8_MMA(0, 0, At, B0); PG8_MMA(0, 1, At, B1); PG8_BAR; PG8_SCHED;
;             PG8_LDA(At, 0, 1); PG8_STAGE(PG8_SB(0, 0), b2, voffB); PG8_STAGE(PG8_SB(0, 1), b2 + hstep, voffB); PG8_STAGE(PG8_SA(0, 0), a2, voffA);
.LBB0_177:
	ds_read_b128 v[128:131], v203
	ds_read_b128 v[132:135], v203 offset:1024
	ds_read_b128 v[136:139], v203 offset:2048
	ds_read_b128 v[140:143], v203 offset:3072
	ds_read_b128 v[144:147], v204
	ds_read_b128 v[148:151], v204 offset:1024
	ds_read_b128 v[152:155], v204 offset:2048
	ds_read_b128 v[156:159], v204 offset:3072
	s_add_u32 s0, s50, 0x100
	s_addc_u32 s1, s51, 0
	s_cmpk_eq_i32 s56, 0x54
	s_cselect_b32 s81, s11, s1
	s_cselect_b32 s80, s10, s0
	s_cselect_b32 s25, s75, s55
	s_cselect_b32 s24, s74, s54
	v_lshl_add_u64 v[212:213], s[50:51], 0, v[180:181]
	s_add_i32 m0, s33, 0xc000
	ds_read_b128 v[160:163], v205
	ds_read_b128 v[164:167], v205 offset:1024
	ds_read_b128 v[168:171], v205 offset:2048
	ds_read_b128 v[172:175], v205 offset:3072
	ds_read_b128 v[188:191], v205 offset:4096
	ds_read_b128 v[192:195], v205 offset:5120
	ds_read_b128 v[196:199], v205 offset:6144
	ds_read_b128 v[208:211], v205 offset:7168
	global_load_lds_dwordx4 v[212:213], off
	v_lshl_add_u64 v[212:213], s[50:51], 0, v[182:183]
	s_add_i32 m0, s33, 0xe000
	s_nop 0
	global_load_lds_dwordx4 v[212:213], off
	s_waitcnt vmcnt(8)
	s_waitcnt lgkmcnt(0)
	s_barrier
	s_setprio 1
	s_waitcnt lgkmcnt(0)
	v_mfma_f32_16x16x32_bf16 v[124:127], v[128:131], v[160:163], v[124:127]
	v_mfma_f32_16x16x32_bf16 v[120:123], v[136:139], v[160:163], v[120:123]
	v_mfma_f32_16x16x32_bf16 v[108:111], v[128:131], v[168:171], v[108:111]
	v_mfma_f32_16x16x32_bf16 v[104:107], v[136:139], v[168:171], v[104:107]
	v_mfma_f32_16x16x32_bf16 v[92:95], v[128:131], v[188:191], v[92:95]
	v_mfma_f32_16x16x32_bf16 v[88:91], v[136:139], v[188:191], v[88:91]
	v_mfma_f32_16x16x32_bf16 v[76:79], v[128:131], v[196:199], v[76:79]
	v_mfma_f32_16x16x32_bf16 v[72:75], v[136:139], v[196:199], v[72:75]
	v_mfma_f32_16x16x32_bf16 v[124:127], v[132:135], v[164:167], v[124:127]
	v_mfma_f32_16x16x32_bf16 v[120:123], v[140:143], v[164:167], v[120:123]
	v_mfma_f32_16x16x32_bf16 v[108:111], v[132:135], v[172:175], v[108:111]
	v_mfma_f32_16x16x32_bf16 v[104:107], v[140:143], v[172:175], v[104:107]
	v_mfma_f32_16x16x32_bf16 v[92:95], v[132:135], v[192:195], v[92:95]
	v_mfma_f32_16x16x32_bf16 v[88:91], v[140:143], v[192:195], v[88:91]
	v_mfma_f32_16x16x32_bf16 v[76:79], v[132:135], v[208:211], v[76:79]
	v_mfma_f32_16x16x32_bf16 v[72:75], v[140:143], v[208:211], v[72:75]
	v_mfma_f32_16x16x32_bf16 v[116:119], v[144:147], v[160:163], v[116:119]
	v_mfma_f32_16x16x32_bf16 v[112:115], v[152:155], v[160:163], v[112:115]
	v_mfma_f32_16x16x32_bf16 v[100:103], v[144:147], v[168:171], v[100:103]
	v_mfma_f32_16x16x32_bf16 v[96:99], v[152:155], v[168:171], v[96:99]
	v_mfma_f32_16x16x32_bf16 v[84:87], v[144:147], v[188:191], v[84:87]
	v_mfma_f32_16x16x32_bf16 v[80:83], v[152:155], v[188:191], v[80:83]
	v_mfma_f32_16x16x32_bf16 v[68:71], v[144:147], v[196:199], v[68:71]
	v_mfma_f32_16x16x32_bf16 v[64:67], v[152:155], v[196:199], v[64:67]
	v_mfma_f32_16x16x32_bf16 v[116:119], v[148:151], v[164:167], v[116:119]
	v_mfma_f32_16x16x32_bf16 v[112:115], v[156:159], v[164:167], v[112:115]
	v_mfma_f32_16x16x32_bf16 v[100:103], v[148:151], v[172:175], v[100:103]
	v_mfma_f32_16x16x32_bf16 v[96:99], v[156:159], v[172:175], v[96:99]
	v_mfma_f32_16x16x32_bf16 v[84:87], v[148:151], v[192:195], v[84:87]
	v_mfma_f32_16x16x32_bf16 v[80:83], v[156:159], v[192:195], v[80:83]
	v_mfma_f32_16x16x32_bf16 v[68:71], v[148:151], v[208:211], v[68:71]
	v_mfma_f32_16x16x32_bf16 v[64:67], v[156:159], v[208:211], v[64:67]
	s_setprio 0
	s_barrier
	s_add_i32 s50, s44, s3
	v_lshl_add_u64 v[212:213], s[24:25], 0, v[176:177]
	s_mov_b32 m0, s50
	ds_read_b128 v[160:163], v205 offset:16384
	ds_read_b128 v[164:167], v205 offset:17408
	ds_read_b128 v[168:171], v205 offset:18432
	ds_read_b128 v[172:175], v205 offset:19456
	ds_read_b128 v[188:191], v205 offset:20480
	ds_read_b128 v[192:195], v205 offset:21504
	ds_read_b128 v[196:199], v205 offset:22528
	ds_read_b128 v[208:211], v205 offset:23552
	global_load_lds_dwordx4 v[212:213], off
	s_add_i32 m0, s50, 0x2000
	s_add_u32 s50, s24, 0x160000
	v_lshl_add_u64 v[214:215], s[24:25], 0, v[178:179]
	s_addc_u32 s51, s25, 0
	s_add_i32 s57, s45, s3
	global_load_lds_dwordx4 v[214:215], off
	v_lshl_add_u64 v[216:217], s[50:51], 0, v[176:177]
	s_mov_b32 m0, s57
	v_lshl_add_u64 v[218:219], s[80:81], 0, v[178:179]
	global_load_lds_dwordx4 v[216:217], off
	v_lshl_add_u64 v[216:217], s[50:51], 0, v[178:179]
	s_add_i32 m0, s57, 0x2000
	s_nop 0
	global_load_lds_dwordx4 v[216:217], off
	v_lshl_add_u64 v[216:217], s[80:81], 0, v[176:177]
	s_mov_b32 m0, s33
	s_nop 0
	global_load_lds_dwordx4 v[216:217], off
	s_mov_b32 m0, s35
	s_nop 0
	global_load_lds_dwordx4 v[218:219], off
	s_waitcnt vmcnt(8)
	s_waitcnt lgkmcnt(0)
	s_barrier
; #define PG8_STAGE(bufoff, gbase, voff) do { _Pragma("unroll") for (int _i = 0; _i < 2; ++_i) \
;         __builtin_amdgcn_global_load_lds((const unsigned*)((const char*)(gbase) + (voff)[_i]), (PG8_LAS unsigned*)(lds + (bufoff) + ldsw + _i * 8192), 16, 0, 0); } while (0)
; #define PG8_LDA(dst, b, h) do { _Pragma("unroll") for (int m = 0; m < 4; ++m) _Pragma("unroll") for (int k = 0; k < 2; ++k) dst[m][k] = *(const PG8_LAS bf16x8*)(lds + PG8_SA(b, h) + aoff + m * 2048 + k * 1024); } while (0)
; #define PG8_LDB(dst, b, h) do { _Pragma("unroll") for (int n = 0; n < 2; ++n) _Pragma("unroll") for (int k = 0; k < 2; ++k) dst[n][k] = *(const PG8_LAS bf16x8*)(lds + PG8_SB(b, h) + boff + n * 2048 + k * 1024); } while (0)
; #define PG8_MMA(ai, bj, At, Bt) do { __builtin_amdgcn_s_setprio(1); _Pragma("unroll") for (int m = 0; m < 4; ++m) _Pragma("unroll") for (int n = 0; n < 2; ++n) _Pragma("unroll") for (int k = 0; k < 2; ++k) \
;         acc[ai][bj][m][n] = __builtin_amdgcn_mfma_f32_16x16x32_bf16(Bt[n][k], At[m][k], acc[ai][bj][m][n], 0, 0, 0); __builtin_amdgcn_s_setprio(0); } while (0)
; #define PG8_WAIT_V(n) asm volatile("s_waitcnt vmcnt(" #n ")" ::: "memory")
; #define PG8_WAIT_L(n) asm volatile("s_waitcnt lgkmcnt(" #n ")" ::: "memory")
; #define PG8_BAR __builtin_amdgcn_s_barrier()
; #define PG8_SCHED __builtin_amdgcn_sched_barrier(0)
; template <class Epi, class Sched, bool ALIGN_EPI = false, bool SP2 = false>
; __device__ __forceinline__ void gemm_phase(PG8_LAS unsigned char* lds, const Gemm g, const Sched& S, const Epi& E) {
;     ...
;             PG8_WAIT_V(8); PG8_WAIT_L(0); PG8_BAR; PG8_MMA(1, 0, At, B0); PG8_MMA(1, 1, At, B1); PG8_BAR; PG8_SCHED;
;             PG8_LDB(B0, 1, 0); PG8_LDB(B1, 1, 1); PG8_SCHED; PG8_LDA(At, 1, 0); PG8_STAGE(PG8_SA(0, 1), a2 + hstep, voffA);
;             PG8_WAIT_V(8); PG8_WAIT_L(0); PG8_BAR; PG8_MMA(0, 0, At, B0); PG8_MMA(0, 1, At, B1); PG8_BAR; PG8_SCHED;
	s_setprio 1
	s_waitcnt lgkmcnt(0)
	v_mfma_f32_16x16x32_bf16 v[60:63], v[128:131], v[160:163], v[60:63]
	v_mfma_f32_16x16x32_bf16 v[56:59], v[136:139], v[160:163], v[56:59]
	v_mfma_f32_16x16x32_bf16 v[44:47], v[128:131], v[168:171], v[44:47]
	v_mfma_f32_16x16x32_bf16 v[40:43], v[136:139], v[168:171], v[40:43]
	v_mfma_f32_16x16x32_bf16 v[28:31], v[128:131], v[188:191], v[28:31]
	v_mfma_f32_16x16x32_bf16 v[24:27], v[136:139], v[188:191], v[24:27]
	v_mfma_f32_16x16x32_bf16 v[12:15], v[128:131], v[196:199], v[12:15]
	v_mfma_f32_16x16x32_bf16 v[8:11], v[136:139], v[196:199], v[8:11]
	v_mfma_f32_16x16x32_bf16 v[60:63], v[132:135], v[164:167], v[60:63]
	v_mfma_f32_16x16x32_bf16 v[56:59], v[140:143], v[164:167], v[56:59]
	v_mfma_f32_16x16x32_bf16 v[44:47], v[132:135], v[172:175], v[44:47]
	v_mfma_f32_16x16x32_bf16 v[40:43], v[140:143], v[172:175], v[40:43]
	v_mfma_f32_16x16x32_bf16 v[28:31], v[132:135], v[192:195], v[28:31]
	v_mfma_f32_16x16x32_bf16 v[24:27], v[140:143], v[192:195], v[24:27]
	v_mfma_f32_16x16x32_bf16 v[12:15], v[132:135], v[208:211], v[12:15]
	v_mfma_f32_16x16x32_bf16 v[8:11], v[140:143], v[208:211], v[8:11]
	v_mfma_f32_16x16x32_bf16 v[52:55], v[144:147], v[160:163], v[52:55]
	v_mfma_f32_16x16x32_bf16 v[48:51], v[152:155], v[160:163], v[48:51]
	v_mfma_f32_16x16x32_bf16 v[36:39], v[144:147], v[168:171], v[36:39]
	v_mfma_f32_16x16x32_bf16 v[32:35], v[152:155], v[168:171], v[32:35]
	v_mfma_f32_16x16x32_bf16 v[20:23], v[144:147], v[188:191], v[20:23]
	v_mfma_f32_16x16x32_bf16 v[16:19], v[152:155], v[188:191], v[16:19]
	v_mfma_f32_16x16x32_bf16 v[4:7], v[144:147], v[196:199], v[4:7]
	v_mfma_f32_16x16x32_bf16 v[0:3], v[152:155], v[196:199], v[0:3]
	v_mfma_f32_16x16x32_bf16 v[52:55], v[148:151], v[164:167], v[52:55]
	v_mfma_f32_16x16x32_bf16 v[48:51], v[156:159], v[164:167], v[48:51]
	v_mfma_f32_16x16x32_bf16 v[36:39], v[148:151], v[172:175], v[36:39]
	v_mfma_f32_16x16x32_bf16 v[32:35], v[156:159], v[172:175], v[32:35]
	v_mfma_f32_16x16x32_bf16 v[20:23], v[148:151], v[192:195], v[20:23]
	v_mfma_f32_16x16x32_bf16 v[16:19], v[156:159], v[192:195], v[16:19]
	v_mfma_f32_16x16x32_bf16 v[4:7], v[148:151], v[208:211], v[4:7]
	v_mfma_f32_16x16x32_bf16 v[0:3], v[156:159], v[208:211], v[0:3]
	s_setprio 0
	s_barrier
	s_add_i32 s57, 0, 0x18000
	s_add_i32 s58, 0, 0x1c000
	v_add_u32_e32 v140, s57, v201
	v_add_u32_e32 v156, s58, v201
	ds_read_b128 v[128:131], v140
	ds_read_b128 v[132:135], v140 offset:1024
	ds_read_b128 v[136:139], v140 offset:2048
	ds_read_b128 v[140:143], v140 offset:3072
	ds_read_b128 v[144:147], v156
	ds_read_b128 v[148:151], v156 offset:1024
	ds_read_b128 v[152:155], v156 offset:2048
	ds_read_b128 v[156:159], v156 offset:3072
	s_add_u32 s50, s80, 0x160000
	s_addc_u32 s51, s81, 0
	s_mov_b32 m0, s36
	v_lshl_add_u64 v[220:221], s[50:51], 0, v[176:177]
	ds_read_b128 v[160:163], v205 offset:32768
	ds_read_b128 v[164:167], v205 offset:33792
	ds_read_b128 v[168:171], v205 offset:34816
	ds_read_b128 v[172:175], v205 offset:35840
	ds_read_b128 v[188:191], v205 offset:36864
	ds_read_b128 v[192:195], v205 offset:37888
	ds_read_b128 v[196:199], v205 offset:38912
	ds_read_b128 v[208:211], v205 offset:39936
	global_load_lds_dwordx4 v[220:221], off
	v_lshl_add_u64 v[220:221], s[50:51], 0, v[178:179]
	s_mov_b32 m0, s37
	s_nop 0
	global_load_lds_dwordx4 v[220:221], off
	s_waitcnt vmcnt(8)
	s_waitcnt lgkmcnt(0)
	s_barrier
	s_setprio 1
	s_waitcnt lgkmcnt(0)
	v_mfma_f32_16x16x32_bf16 v[124:127], v[128:131], v[160:163], v[124:127]
	v_mfma_f32_16x16x32_bf16 v[120:123], v[136:139], v[160:163], v[120:123]
	v_mfma_f32_16x16x32_bf16 v[108:111], v[128:131], v[168:171], v[108:111]
	v_mfma_f32_16x16x32_bf16 v[104:107], v[136:139], v[168:171], v[104:107]
	v_mfma_f32_16x16x32_bf16 v[92:95], v[128:131], v[188:191], v[92:95]
	v_mfma_f32_16x16x32_bf16 v[88:91], v[136:139], v[188:191], v[88:91]
	v_mfma_f32_16x16x32_bf16 v[76:79], v[128:131], v[196:199], v[76:79]
	v_mfma_f32_16x16x32_bf16 v[72:75], v[136:139], v[196:199], v[72:75]
	v_mfma_f32_16x16x32_bf16 v[124:127], v[132:135], v[164:167], v[124:127]
	v_mfma_f32_16x16x32_bf16 v[120:123], v[140:143], v[164:167], v[120:123]
	v_mfma_f32_16x16x32_bf16 v[108:111], v[132:135], v[172:175], v[108:111]
	v_mfma_f32_16x16x32_bf16 v[104:107], v[140:143], v[172:175], v[104:107]
	v_mfma_f32_16x16x32_bf16 v[92:95], v[132:135], v[192:195], v[92:95]
	v_mfma_f32_16x16x32_bf16 v[88:91], v[140:143], v[192:195], v[88:91]
	v_mfma_f32_16x16x32_bf16 v[76:79], v[132:135], v[208:211], v[76:79]
	v_mfma_f32_16x16x32_bf16 v[72:75], v[140:143], v[208:211], v[72:75]
	v_mfma_f32_16x16x32_bf16 v[116:119], v[144:147], v[160:163], v[116:119]
	v_mfma_f32_16x16x32_bf16 v[112:115], v[152:155], v[160:163], v[112:115]
	v_mfma_f32_16x16x32_bf16 v[100:103], v[144:147], v[168:171], v[100:103]
	v_mfma_f32_16x16x32_bf16 v[96:99], v[152:155], v[168:171], v[96:99]
	v_mfma_f32_16x16x32_bf16 v[84:87], v[144:147], v[188:191], v[84:87]
	v_mfma_f32_16x16x32_bf16 v[80:83], v[152:155], v[188:191], v[80:83]
	v_mfma_f32_16x16x32_bf16 v[68:71], v[144:147], v[196:199], v[68:71]
	v_mfma_f32_16x16x32_bf16 v[64:67], v[152:155], v[196:199], v[64:67]
	v_mfma_f32_16x16x32_bf16 v[116:119], v[148:151], v[164:167], v[116:119]
	v_mfma_f32_16x16x32_bf16 v[112:115], v[156:159], v[164:167], v[112:115]
	v_mfma_f32_16x16x32_bf16 v[100:103], v[148:151], v[172:175], v[100:103]
	v_mfma_f32_16x16x32_bf16 v[96:99], v[156:159], v[172:175], v[96:99]
	v_mfma_f32_16x16x32_bf16 v[84:87], v[148:151], v[192:195], v[84:87]
	v_mfma_f32_16x16x32_bf16 v[80:83], v[156:159], v[192:195], v[80:83]
	v_mfma_f32_16x16x32_bf16 v[68:71], v[148:151], v[208:211], v[68:71]
	v_mfma_f32_16x16x32_bf16 v[64:67], v[156:159], v[208:211], v[64:67]
	s_setprio 0
	s_barrier
; #define PG8_STAGE(bufoff, gbase, voff) do { _Pragma("unroll") for (int _i = 0; _i < 2; ++_i) \
;         __builtin_amdgcn_global_load_lds((const unsigned*)((const char*)(gbase) + (voff)[_i]), (PG8_LAS unsigned*)(lds + (bufoff) + ldsw + _i * 8192), 16, 0, 0); } while (0)
; #define PG8_LDA(dst, b, h) do { _Pragma("unroll") for (int m = 0; m < 4; ++m) _Pragma("unroll") for (int k = 0; k < 2; ++k) dst[m][k] = *(const PG8_LAS bf16x8*)(lds + PG8_SA(b, h) + aoff + m * 2048 + k * 1024); } while (0)
; #define PG8_MMA(ai, bj, At, Bt) do { __builtin_amdgcn_s_setprio(1); _Pragma("unroll") for (int m = 0; m < 4; ++m) _Pragma("unroll") for (int n = 0; n < 2; ++n) _Pragma("unroll") for (int k = 0; k < 2; ++k) \
;         acc[ai][bj][m][n] = __builtin_amdgcn_mfma_f32_16x16x32_bf16(Bt[n][k], At[m][k], acc[ai][bj][m][n], 0, 0, 0); __builtin_amdgcn_s_setprio(0); } while (0)
; #define PG8_WAIT_V(n) asm volatile("s_waitcnt vmcnt(" #n ")" ::: "memory")
; #define PG8_WAIT_L(n) asm volatile("s_waitcnt lgkmcnt(" #n ")" ::: "memory")
; #define PG8_BAR __builtin_amdgcn_s_barrier()
; #define PG8_SCHED __builtin_amdgcn_sched_barrier(0)
; template <class Epi, class Sched, bool ALIGN_EPI = false, bool SP2 = false>
; __device__ __forceinline__ void gemm_phase(PG8_LAS unsigned char* lds, const Gemm g, const Sched& S, const Epi& E) {
;     ...
;             PG8_LDA(At, 1, 1); PG8_STAGE(PG8_SB(1, 0), b3, voffB); PG8_STAGE(PG8_SB(1, 1), b3 + hstep, voffB); PG8_STAGE(PG8_SA(1, 0), a3, voffA);
;             PG8_WAIT_V(8); PG8_WAIT_L(0); PG8_BAR; PG8_MMA(1, 0, At, B0); PG8_MMA(1, 1, At, B1); PG8_BAR; PG8_SCHED;
;     ...
;         if constexpr (ALIGN_EPI) { if (wr == 0) PG8_BAR; }
	s_add_i32 s50, s57, s3
	v_lshl_add_u64 v[212:213], v[212:213], 0, s[14:15]
	s_mov_b32 m0, s50
	ds_read_b128 v[160:163], v205 offset:49152
	ds_read_b128 v[164:167], v205 offset:50176
	ds_read_b128 v[168:171], v205 offset:51200
	ds_read_b128 v[172:175], v205 offset:52224
	ds_read_b128 v[188:191], v205 offset:53248
	ds_read_b128 v[192:195], v205 offset:54272
	ds_read_b128 v[196:199], v205 offset:55296
	ds_read_b128 v[208:211], v205 offset:56320
	global_load_lds_dwordx4 v[212:213], off
	s_add_i32 m0, s50, 0x2000
	s_add_u32 s24, s24, 0x160080
	v_lshl_add_u64 v[212:213], v[214:215], 0, s[14:15]
	s_addc_u32 s25, s25, 0
	s_add_i32 s50, s58, s3
	global_load_lds_dwordx4 v[212:213], off
	v_lshl_add_u64 v[212:213], s[24:25], 0, v[176:177]
	s_mov_b32 m0, s50
	s_nop 0
	global_load_lds_dwordx4 v[212:213], off
	v_lshl_add_u64 v[212:213], s[24:25], 0, v[178:179]
	s_add_i32 m0, s50, 0x2000
	s_nop 0
	global_load_lds_dwordx4 v[212:213], off
	v_lshl_add_u64 v[212:213], v[216:217], 0, s[14:15]
	s_mov_b32 m0, s39
	s_nop 0
	global_load_lds_dwordx4 v[212:213], off
	v_lshl_add_u64 v[212:213], v[218:219], 0, s[14:15]
	s_mov_b32 m0, s40
	s_nop 0
	global_load_lds_dwordx4 v[212:213], off
	s_waitcnt vmcnt(8)
	s_waitcnt lgkmcnt(0)
	s_barrier
	s_setprio 1
	s_waitcnt lgkmcnt(0)
	v_mfma_f32_16x16x32_bf16 v[60:63], v[128:131], v[160:163], v[60:63]
	v_mfma_f32_16x16x32_bf16 v[56:59], v[136:139], v[160:163], v[56:59]
	v_mfma_f32_16x16x32_bf16 v[44:47], v[128:131], v[168:171], v[44:47]
	v_mfma_f32_16x16x32_bf16 v[40:43], v[136:139], v[168:171], v[40:43]
	v_mfma_f32_16x16x32_bf16 v[28:31], v[128:131], v[188:191], v[28:31]
	v_mfma_f32_16x16x32_bf16 v[24:27], v[136:139], v[188:191], v[24:27]
	v_mfma_f32_16x16x32_bf16 v[12:15], v[128:131], v[196:199], v[12:15]
	v_mfma_f32_16x16x32_bf16 v[8:11], v[136:139], v[196:199], v[8:11]
	v_mfma_f32_16x16x32_bf16 v[60:63], v[132:135], v[164:167], v[60:63]
	v_mfma_f32_16x16x32_bf16 v[56:59], v[140:143], v[164:167], v[56:59]
	v_mfma_f32_16x16x32_bf16 v[44:47], v[132:135], v[172:175], v[44:47]
	v_mfma_f32_16x16x32_bf16 v[40:43], v[140:143], v[172:175], v[40:43]
	v_mfma_f32_16x16x32_bf16 v[28:31], v[132:135], v[192:195], v[28:31]
	v_mfma_f32_16x16x32_bf16 v[24:27], v[140:143], v[192:195], v[24:27]
	v_mfma_f32_16x16x32_bf16 v[12:15], v[132:135], v[208:211], v[12:15]
	v_mfma_f32_16x16x32_bf16 v[8:11], v[140:143], v[208:211], v[8:11]
	v_mfma_f32_16x16x32_bf16 v[52:55], v[144:147], v[160:163], v[52:55]
	v_mfma_f32_16x16x32_bf16 v[48:51], v[152:155], v[160:163], v[48:51]
	v_mfma_f32_16x16x32_bf16 v[36:39], v[144:147], v[168:171], v[36:39]
	v_mfma_f32_16x16x32_bf16 v[32:35], v[152:155], v[168:171], v[32:35]
	v_mfma_f32_16x16x32_bf16 v[20:23], v[144:147], v[188:191], v[20:23]
	v_mfma_f32_16x16x32_bf16 v[16:19], v[152:155], v[188:191], v[16:19]
	v_mfma_f32_16x16x32_bf16 v[4:7], v[144:147], v[196:199], v[4:7]
	v_mfma_f32_16x16x32_bf16 v[0:3], v[152:155], v[196:199], v[0:3]
	v_mfma_f32_16x16x32_bf16 v[52:55], v[148:151], v[164:167], v[52:55]
	v_mfma_f32_16x16x32_bf16 v[48:51], v[156:159], v[164:167], v[48:51]
	v_mfma_f32_16x16x32_bf16 v[36:39], v[148:151], v[172:175], v[36:39]
	v_mfma_f32_16x16x32_bf16 v[32:35], v[156:159], v[172:175], v[32:35]
	v_mfma_f32_16x16x32_bf16 v[20:23], v[148:151], v[192:195], v[20:23]
	v_mfma_f32_16x16x32_bf16 v[16:19], v[156:159], v[192:195], v[16:19]
	v_mfma_f32_16x16x32_bf16 v[4:7], v[148:151], v[208:211], v[4:7]
	v_mfma_f32_16x16x32_bf16 v[0:3], v[156:159], v[208:211], v[0:3]
	s_setprio 0
	s_barrier
	s_add_i32 s56, s56, 2
	s_add_u32 s54, s54, 0x100
	s_addc_u32 s55, s55, 0
	s_cmpk_gt_u32 s56, 0x55
	s_mov_b64 s[50:51], s[0:1]
	s_cbranch_scc0 .LBB0_177
	s_and_b64 vcc, exec, s[20:21]
	s_cbranch_vccz .LBB0_180
	s_barrier

; #define PG8_STAGE(bufoff, gbase, voff) do { _Pragma("unroll") for (int _i = 0; _i < 2; ++_i) \
;         __builtin_amdgcn_global_load_lds((const unsigned*)((const char*)(gbase) + (voff)[_i]), (PG8_LAS unsigned*)(lds + (bufoff) + ldsw + _i * 8192), 16, 0, 0); } while (0)
; #define PG8_LDA(dst, b, h) do { _Pragma("unroll") for (int m = 0; m < 4; ++m) _Pragma("unroll") for (int k = 0; k < 2; ++k) dst[m][k] = *(const PG8_LAS bf16x8*)(lds + PG8_SA(b, h) + aoff + m * 2048 + k * 1024); } while (0)
; #define PG8_LDB(dst, b, h) do { _Pragma("unroll") for (int n = 0; n < 2; ++n) _Pragma("unroll") for (int k = 0; k < 2; ++k) dst[n][k] = *(const PG8_LAS bf16x8*)(lds + PG8_SB(b, h) + boff + n * 2048 + k * 1024); } while (0)
; #define PG8_MMA(ai, bj, At, Bt) do { __builtin_amdgcn_s_setprio(1); _Pragma("unroll") for (int m = 0; m < 4; ++m) _Pragma("unroll") for (int n = 0; n < 2; ++n) _Pragma("unroll") for (int k = 0; k < 2; ++k) \
;         acc[ai][bj][m][n] = __builtin_amdgcn_mfma_f32_16x16x32_bf16(Bt[n][k], At[m][k], acc[ai][bj][m][n], 0, 0, 0); __builtin_amdgcn_s_setprio(0); } while (0)
; #define PG8_WAIT_V(n) asm volatile("s_waitcnt vmcnt(" #n ")" ::: "memory")
; #define PG8_WAIT_L(n) asm volatile("s_waitcnt lgkmcnt(" #n ")" ::: "memory")
; #define PG8_BAR __builtin_amdgcn_s_barrier()
; #define PG8_SCHED __builtin_amdgcn_sched_barrier(0)
; template <class Epi, class Sched, bool ALIGN_EPI = false, bool SP2 = false>
; __device__ __forceinline__ void gemm_phase(PG8_LAS unsigned char* lds, const Gemm g, const Sched& S, const Epi& E) {
;     ...
;             PG8_LDB(B0, 0, 0); PG8_LDB(B1, 0, 1); PG8_SCHED; PG8_LDA(At, 0, 0); PG8_STAGE(PG8_SA(1, 1), a1 + hstep, voffA);
;             PG8_WAIT_V(8); PG8_WAIT_L(0); PG8_BAR; PG8_MMA(0, 0, At, B0); PG8_MMA(0, 1, At, B1); PG8_BAR; PG8_SCHED;
;             PG8_LDA(At, 0, 1); PG8_STAGE(PG8_SB(0, 0), b2, voffB); PG8_STAGE(PG8_SB(0, 1), b2 + hstep, voffB); PG8_STAGE(PG8_SA(0, 0), a2, voffA);
.LBB0_263:
	ds_read_b128 v[4:7], v208
	ds_read_b128 v[12:15], v208 offset:1024
	ds_read_b128 v[16:19], v208 offset:2048
	ds_read_b128 v[20:23], v208 offset:3072
	ds_read_b128 v[164:167], v209
	ds_read_b128 v[168:171], v209 offset:1024
	ds_read_b128 v[172:175], v209 offset:2048
	ds_read_b128 v[176:179], v209 offset:3072
	s_add_u32 s0, s4, 0xfff80080
	s_addc_u32 s1, s5, -1
	s_cmp_eq_u32 s17, 28
	s_cselect_b32 s7, s3, s1
	s_cselect_b32 s6, s11, s0
	s_cselect_b32 s1, s12, s16
	s_cselect_b32 s0, s13, s15
	v_lshl_add_u64 v[220:221], s[4:5], 0, v[156:157]
	s_add_i32 m0, s25, 0xc000
	ds_read_b128 v[180:183], v210
	ds_read_b128 v[184:187], v210 offset:1024
	ds_read_b128 v[188:191], v210 offset:2048
	ds_read_b128 v[192:195], v210 offset:3072
	ds_read_b128 v[196:199], v210 offset:4096
	ds_read_b128 v[200:203], v210 offset:5120
	ds_read_b128 v[216:219], v210 offset:6144
	ds_read_b128 v[228:231], v210 offset:7168
	global_load_lds_dwordx4 v[220:221], off
	v_lshl_add_u64 v[220:221], s[4:5], 0, v[158:159]
	s_add_i32 m0, s25, 0xe000
	s_nop 0
	global_load_lds_dwordx4 v[220:221], off
	s_waitcnt vmcnt(8)
	s_waitcnt lgkmcnt(0)
	s_barrier
	s_setprio 1
	s_waitcnt lgkmcnt(0)
	v_mfma_f32_16x16x32_bf16 v[140:143], v[4:7], v[180:183], v[140:143]
	v_mfma_f32_16x16x32_bf16 v[136:139], v[16:19], v[180:183], v[136:139]
	v_mfma_f32_16x16x32_bf16 v[124:127], v[4:7], v[188:191], v[124:127]
	v_mfma_f32_16x16x32_bf16 v[120:123], v[16:19], v[188:191], v[120:123]
	v_mfma_f32_16x16x32_bf16 v[108:111], v[4:7], v[196:199], v[108:111]
	v_mfma_f32_16x16x32_bf16 v[104:107], v[16:19], v[196:199], v[104:107]
	v_mfma_f32_16x16x32_bf16 v[92:95], v[4:7], v[216:219], v[92:95]
	v_mfma_f32_16x16x32_bf16 v[88:91], v[16:19], v[216:219], v[88:91]
	v_mfma_f32_16x16x32_bf16 v[140:143], v[12:15], v[184:187], v[140:143]
	v_mfma_f32_16x16x32_bf16 v[136:139], v[20:23], v[184:187], v[136:139]
	v_mfma_f32_16x16x32_bf16 v[124:127], v[12:15], v[192:195], v[124:127]
	v_mfma_f32_16x16x32_bf16 v[120:123], v[20:23], v[192:195], v[120:123]
	v_mfma_f32_16x16x32_bf16 v[108:111], v[12:15], v[200:203], v[108:111]
	v_mfma_f32_16x16x32_bf16 v[104:107], v[20:23], v[200:203], v[104:107]
	v_mfma_f32_16x16x32_bf16 v[92:95], v[12:15], v[228:231], v[92:95]
	v_mfma_f32_16x16x32_bf16 v[88:91], v[20:23], v[228:231], v[88:91]
	v_mfma_f32_16x16x32_bf16 v[132:135], v[164:167], v[180:183], v[132:135]
	v_mfma_f32_16x16x32_bf16 v[128:131], v[172:175], v[180:183], v[128:131]
	v_mfma_f32_16x16x32_bf16 v[116:119], v[164:167], v[188:191], v[116:119]
	v_mfma_f32_16x16x32_bf16 v[112:115], v[172:175], v[188:191], v[112:115]
	v_mfma_f32_16x16x32_bf16 v[100:103], v[164:167], v[196:199], v[100:103]
	v_mfma_f32_16x16x32_bf16 v[96:99], v[172:175], v[196:199], v[96:99]
	v_mfma_f32_16x16x32_bf16 v[84:87], v[164:167], v[216:219], v[84:87]
	v_mfma_f32_16x16x32_bf16 v[80:83], v[172:175], v[216:219], v[80:83]
	v_mfma_f32_16x16x32_bf16 v[132:135], v[168:171], v[184:187], v[132:135]
	v_mfma_f32_16x16x32_bf16 v[128:131], v[176:179], v[184:187], v[128:131]
	v_mfma_f32_16x16x32_bf16 v[116:119], v[168:171], v[192:195], v[116:119]
	v_mfma_f32_16x16x32_bf16 v[112:115], v[176:179], v[192:195], v[112:115]
	v_mfma_f32_16x16x32_bf16 v[100:103], v[168:171], v[200:203], v[100:103]
	v_mfma_f32_16x16x32_bf16 v[96:99], v[176:179], v[200:203], v[96:99]
	v_mfma_f32_16x16x32_bf16 v[84:87], v[168:171], v[228:231], v[84:87]
	v_mfma_f32_16x16x32_bf16 v[80:83], v[176:179], v[228:231], v[80:83]
	s_setprio 0
	s_barrier
	s_add_i32 s20, s54, s24
	v_lshl_add_u64 v[220:221], s[0:1], 0, v[146:147]
	s_mov_b32 m0, s20
	ds_read_b128 v[180:183], v210 offset:16384
	ds_read_b128 v[184:187], v210 offset:17408
	ds_read_b128 v[188:191], v210 offset:18432
	ds_read_b128 v[192:195], v210 offset:19456
	ds_read_b128 v[196:199], v210 offset:20480
	ds_read_b128 v[200:203], v210 offset:21504
	ds_read_b128 v[216:219], v210 offset:22528
	ds_read_b128 v[228:231], v210 offset:23552
	global_load_lds_dwordx4 v[220:221], off
	s_add_i32 m0, s20, 0x2000
	s_add_u32 s36, s0, 0x80000
	v_lshl_add_u64 v[232:233], s[0:1], 0, v[150:151]
	s_addc_u32 s37, s1, 0
	s_add_i32 s20, s55, s24
	global_load_lds_dwordx4 v[232:233], off
	v_lshl_add_u64 v[234:235], s[36:37], 0, v[146:147]
	s_mov_b32 m0, s20
	v_lshl_add_u64 v[236:237], s[6:7], 0, v[148:149]
	global_load_lds_dwordx4 v[234:235], off
	v_lshl_add_u64 v[234:235], s[36:37], 0, v[150:151]
	s_add_i32 m0, s20, 0x2000
	s_nop 0
	global_load_lds_dwordx4 v[234:235], off
	v_lshl_add_u64 v[234:235], s[6:7], 0, v[144:145]
	s_mov_b32 m0, s25
	s_nop 0
	global_load_lds_dwordx4 v[234:235], off
	s_mov_b32 m0, s35
	s_nop 0
	global_load_lds_dwordx4 v[236:237], off
	s_waitcnt vmcnt(8)
	s_waitcnt lgkmcnt(0)
	s_barrier
; #define PG8_STAGE(bufoff, gbase, voff) do { _Pragma("unroll") for (int _i = 0; _i < 2; ++_i) \
;         __builtin_amdgcn_global_load_lds((const unsigned*)((const char*)(gbase) + (voff)[_i]), (PG8_LAS unsigned*)(lds + (bufoff) + ldsw + _i * 8192), 16, 0, 0); } while (0)
; #define PG8_LDA(dst, b, h) do { _Pragma("unroll") for (int m = 0; m < 4; ++m) _Pragma("unroll") for (int k = 0; k < 2; ++k) dst[m][k] = *(const PG8_LAS bf16x8*)(lds + PG8_SA(b, h) + aoff + m * 2048 + k * 1024); } while (0)
; #define PG8_LDB(dst, b, h) do { _Pragma("unroll") for (int n = 0; n < 2; ++n) _Pragma("unroll") for (int k = 0; k < 2; ++k) dst[n][k] = *(const PG8_LAS bf16x8*)(lds + PG8_SB(b, h) + boff + n * 2048 + k * 1024); } while (0)
; #define PG8_MMA(ai, bj, At, Bt) do { __builtin_amdgcn_s_setprio(1); _Pragma("unroll") for (int m = 0; m < 4; ++m) _Pragma("unroll") for (int n = 0; n < 2; ++n) _Pragma("unroll") for (int k = 0; k < 2; ++k) \
;         acc[ai][bj][m][n] = __builtin_amdgcn_mfma_f32_16x16x32_bf16(Bt[n][k], At[m][k], acc[ai][bj][m][n], 0, 0, 0); __builtin_amdgcn_s_setprio(0); } while (0)
; #define PG8_WAIT_V(n) asm volatile("s_waitcnt vmcnt(" #n ")" ::: "memory")
; #define PG8_WAIT_L(n) asm volatile("s_waitcnt lgkmcnt(" #n ")" ::: "memory")
; #define PG8_BAR __builtin_amdgcn_s_barrier()
; #define PG8_SCHED __builtin_amdgcn_sched_barrier(0)
; template <class Epi, class Sched, bool ALIGN_EPI = false, bool SP2 = false>
; __device__ __forceinline__ void gemm_phase(PG8_LAS unsigned char* lds, const Gemm g, const Sched& S, const Epi& E) {
;     ...
;             PG8_WAIT_V(8); PG8_WAIT_L(0); PG8_BAR; PG8_MMA(1, 0, At, B0); PG8_MMA(1, 1, At, B1); PG8_BAR; PG8_SCHED;
;             PG8_LDB(B0, 1, 0); PG8_LDB(B1, 1, 1); PG8_SCHED; PG8_LDA(At, 1, 0); PG8_STAGE(PG8_SA(0, 1), a2 + hstep, voffA);
;             PG8_WAIT_V(8); PG8_WAIT_L(0); PG8_BAR; PG8_MMA(0, 0, At, B0); PG8_MMA(0, 1, At, B1); PG8_BAR; PG8_SCHED;
	s_setprio 1
	s_waitcnt lgkmcnt(0)
	v_mfma_f32_16x16x32_bf16 v[76:79], v[4:7], v[180:183], v[76:79]
	v_mfma_f32_16x16x32_bf16 v[72:75], v[16:19], v[180:183], v[72:75]
	v_mfma_f32_16x16x32_bf16 v[60:63], v[4:7], v[188:191], v[60:63]
	v_mfma_f32_16x16x32_bf16 v[56:59], v[16:19], v[188:191], v[56:59]
	v_mfma_f32_16x16x32_bf16 v[44:47], v[4:7], v[196:199], v[44:47]
	v_mfma_f32_16x16x32_bf16 v[40:43], v[16:19], v[196:199], v[40:43]
	v_mfma_f32_16x16x32_bf16 v[4:7], v[4:7], v[216:219], v[28:31]
	v_mfma_f32_16x16x32_bf16 v[76:79], v[12:15], v[184:187], v[76:79]
	v_mfma_f32_16x16x32_bf16 v[72:75], v[20:23], v[184:187], v[72:75]
	v_mfma_f32_16x16x32_bf16 v[60:63], v[12:15], v[192:195], v[60:63]
	v_mfma_f32_16x16x32_bf16 v[56:59], v[20:23], v[192:195], v[56:59]
	v_mfma_f32_16x16x32_bf16 v[44:47], v[12:15], v[200:203], v[44:47]
	v_mfma_f32_16x16x32_bf16 v[40:43], v[20:23], v[200:203], v[40:43]
	v_mfma_f32_16x16x32_bf16 v[4:7], v[12:15], v[228:231], v[4:7]
	v_mfma_f32_16x16x32_bf16 v[12:15], v[16:19], v[216:219], v[24:27]
	v_mfma_f32_16x16x32_bf16 v[12:15], v[20:23], v[228:231], v[12:15]
	v_mfma_f32_16x16x32_bf16 v[24:27], v[164:167], v[188:191], v[52:55]
	v_mfma_f32_16x16x32_bf16 v[52:55], v[168:171], v[192:195], v[24:27]
	v_mfma_f32_16x16x32_bf16 v[24:27], v[172:175], v[188:191], v[48:51]
	v_mfma_f32_16x16x32_bf16 v[48:51], v[176:179], v[192:195], v[24:27]
	v_mfma_f32_16x16x32_bf16 v[24:27], v[164:167], v[196:199], v[36:39]
	v_mfma_f32_16x16x32_bf16 v[36:39], v[168:171], v[200:203], v[24:27]
	v_mfma_f32_16x16x32_bf16 v[24:27], v[172:175], v[196:199], v[32:35]
	v_mfma_f32_16x16x32_bf16 v[8:11], v[164:167], v[216:219], v[8:11]
	v_mfma_f32_16x16x32_bf16 v[0:3], v[172:175], v[216:219], v[0:3]
	v_mfma_f32_16x16x32_bf16 v[16:19], v[164:167], v[180:183], v[68:71]
	v_mfma_f32_16x16x32_bf16 v[20:23], v[172:175], v[180:183], v[64:67]
	v_mfma_f32_16x16x32_bf16 v[32:35], v[176:179], v[200:203], v[24:27]
	v_mfma_f32_16x16x32_bf16 v[8:11], v[168:171], v[228:231], v[8:11]
	v_mfma_f32_16x16x32_bf16 v[0:3], v[176:179], v[228:231], v[0:3]
	v_mfma_f32_16x16x32_bf16 v[16:19], v[168:171], v[184:187], v[16:19]
	v_mfma_f32_16x16x32_bf16 v[20:23], v[176:179], v[184:187], v[20:23]
	s_setprio 0
	s_barrier
	s_add_i32 s20, 0, 0x18000
	s_add_i32 s33, 0, 0x1c000
	v_add_u32_e32 v68, s20, v206
	v_add_u32_e32 v152, s33, v206
	ds_read_b128 v[24:27], v68
	ds_read_b128 v[28:31], v68 offset:1024
	ds_read_b128 v[64:67], v68 offset:2048
	ds_read_b128 v[68:71], v68 offset:3072
	ds_read_b128 v[164:167], v152
	ds_read_b128 v[168:171], v152 offset:1024
	ds_read_b128 v[172:175], v152 offset:2048
	ds_read_b128 v[176:179], v152 offset:3072
	s_add_u32 s6, s6, 0x80000
	s_addc_u32 s7, s7, 0
	s_mov_b32 m0, s65
	v_lshl_add_u64 v[238:239], s[6:7], 0, v[144:145]
	ds_read_b128 v[180:183], v210 offset:32768
	ds_read_b128 v[184:187], v210 offset:33792
	ds_read_b128 v[188:191], v210 offset:34816
	ds_read_b128 v[192:195], v210 offset:35840
	ds_read_b128 v[196:199], v210 offset:36864
	ds_read_b128 v[200:203], v210 offset:37888
	ds_read_b128 v[216:219], v210 offset:38912
	ds_read_b128 v[228:231], v210 offset:39936
	global_load_lds_dwordx4 v[238:239], off
	v_lshl_add_u64 v[238:239], s[6:7], 0, v[148:149]
	s_mov_b32 m0, s59
	s_nop 0
	global_load_lds_dwordx4 v[238:239], off
	s_waitcnt vmcnt(8)
	s_waitcnt lgkmcnt(0)
	s_barrier
	s_setprio 1
	s_waitcnt lgkmcnt(0)
	v_mfma_f32_16x16x32_bf16 v[140:143], v[24:27], v[180:183], v[140:143]
	v_mfma_f32_16x16x32_bf16 v[136:139], v[64:67], v[180:183], v[136:139]
	v_mfma_f32_16x16x32_bf16 v[124:127], v[24:27], v[188:191], v[124:127]
	v_mfma_f32_16x16x32_bf16 v[120:123], v[64:67], v[188:191], v[120:123]
	v_mfma_f32_16x16x32_bf16 v[108:111], v[24:27], v[196:199], v[108:111]
	v_mfma_f32_16x16x32_bf16 v[104:107], v[64:67], v[196:199], v[104:107]
	v_mfma_f32_16x16x32_bf16 v[92:95], v[24:27], v[216:219], v[92:95]
	v_mfma_f32_16x16x32_bf16 v[88:91], v[64:67], v[216:219], v[88:91]
	v_mfma_f32_16x16x32_bf16 v[140:143], v[28:31], v[184:187], v[140:143]
	v_mfma_f32_16x16x32_bf16 v[136:139], v[68:71], v[184:187], v[136:139]
	v_mfma_f32_16x16x32_bf16 v[124:127], v[28:31], v[192:195], v[124:127]
	v_mfma_f32_16x16x32_bf16 v[120:123], v[68:71], v[192:195], v[120:123]
	v_mfma_f32_16x16x32_bf16 v[108:111], v[28:31], v[200:203], v[108:111]
	v_mfma_f32_16x16x32_bf16 v[104:107], v[68:71], v[200:203], v[104:107]
	v_mfma_f32_16x16x32_bf16 v[92:95], v[28:31], v[228:231], v[92:95]
	v_mfma_f32_16x16x32_bf16 v[88:91], v[68:71], v[228:231], v[88:91]
	v_mfma_f32_16x16x32_bf16 v[132:135], v[164:167], v[180:183], v[132:135]
	v_mfma_f32_16x16x32_bf16 v[128:131], v[172:175], v[180:183], v[128:131]
	v_mfma_f32_16x16x32_bf16 v[116:119], v[164:167], v[188:191], v[116:119]
	v_mfma_f32_16x16x32_bf16 v[112:115], v[172:175], v[188:191], v[112:115]
	v_mfma_f32_16x16x32_bf16 v[100:103], v[164:167], v[196:199], v[100:103]
	v_mfma_f32_16x16x32_bf16 v[96:99], v[172:175], v[196:199], v[96:99]
	v_mfma_f32_16x16x32_bf16 v[84:87], v[164:167], v[216:219], v[84:87]
	v_mfma_f32_16x16x32_bf16 v[80:83], v[172:175], v[216:219], v[80:83]
	v_mfma_f32_16x16x32_bf16 v[132:135], v[168:171], v[184:187], v[132:135]
	v_mfma_f32_16x16x32_bf16 v[128:131], v[176:179], v[184:187], v[128:131]
	v_mfma_f32_16x16x32_bf16 v[116:119], v[168:171], v[192:195], v[116:119]
	v_mfma_f32_16x16x32_bf16 v[112:115], v[176:179], v[192:195], v[112:115]
	v_mfma_f32_16x16x32_bf16 v[100:103], v[168:171], v[200:203], v[100:103]
	v_mfma_f32_16x16x32_bf16 v[96:99], v[176:179], v[200:203], v[96:99]
	v_mfma_f32_16x16x32_bf16 v[84:87], v[168:171], v[228:231], v[84:87]
	v_mfma_f32_16x16x32_bf16 v[80:83], v[176:179], v[228:231], v[80:83]
	s_setprio 0
	s_barrier
; #define PG8_STAGE(bufoff, gbase, voff) do { _Pragma("unroll") for (int _i = 0; _i < 2; ++_i) \
;         __builtin_amdgcn_global_load_lds((const unsigned*)((const char*)(gbase) + (voff)[_i]), (PG8_LAS unsigned*)(lds + (bufoff) + ldsw + _i * 8192), 16, 0, 0); } while (0)
; #define PG8_LDA(dst, b, h) do { _Pragma("unroll") for (int m = 0; m < 4; ++m) _Pragma("unroll") for (int k = 0; k < 2; ++k) dst[m][k] = *(const PG8_LAS bf16x8*)(lds + PG8_SA(b, h) + aoff + m * 2048 + k * 1024); } while (0)
; #define PG8_MMA(ai, bj, At, Bt) do { __builtin_amdgcn_s_setprio(1); _Pragma("unroll") for (int m = 0; m < 4; ++m) _Pragma("unroll") for (int n = 0; n < 2; ++n) _Pragma("unroll") for (int k = 0; k < 2; ++k) \
;         acc[ai][bj][m][n] = __builtin_amdgcn_mfma_f32_16x16x32_bf16(Bt[n][k], At[m][k], acc[ai][bj][m][n], 0, 0, 0); __builtin_amdgcn_s_setprio(0); } while (0)
; #define PG8_WAIT_V(n) asm volatile("s_waitcnt vmcnt(" #n ")" ::: "memory")
; #define PG8_WAIT_L(n) asm volatile("s_waitcnt lgkmcnt(" #n ")" ::: "memory")
; #define PG8_BAR __builtin_amdgcn_s_barrier()
; #define PG8_SCHED __builtin_amdgcn_sched_barrier(0)
; template <class Epi, class Sched, bool ALIGN_EPI = false, bool SP2 = false>
; __device__ __forceinline__ void gemm_phase(PG8_LAS unsigned char* lds, const Gemm g, const Sched& S, const Epi& E) {
;     ...
;             PG8_LDA(At, 1, 1); PG8_STAGE(PG8_SB(1, 0), b3, voffB); PG8_STAGE(PG8_SB(1, 1), b3 + hstep, voffB); PG8_STAGE(PG8_SA(1, 0), a3, voffA);
;             PG8_WAIT_V(8); PG8_WAIT_L(0); PG8_BAR; PG8_MMA(1, 0, At, B0); PG8_MMA(1, 1, At, B1); PG8_BAR; PG8_SCHED;
;     ...
;         if constexpr (ALIGN_EPI) { if (wr == 0) PG8_BAR; }
	s_add_i32 s6, s20, s24
	v_lshl_add_u64 v[220:221], v[220:221], 0, s[84:85]
	s_mov_b32 m0, s6
	ds_read_b128 v[180:183], v210 offset:49152
	ds_read_b128 v[184:187], v210 offset:50176
	ds_read_b128 v[188:191], v210 offset:51200
	ds_read_b128 v[192:195], v210 offset:52224
	ds_read_b128 v[196:199], v210 offset:53248
	ds_read_b128 v[200:203], v210 offset:54272
	ds_read_b128 v[216:219], v210 offset:55296
	ds_read_b128 v[228:231], v210 offset:56320
	global_load_lds_dwordx4 v[220:221], off
	s_add_i32 m0, s6, 0x2000
	s_add_u32 s0, s0, 0x80080
	v_lshl_add_u64 v[220:221], v[232:233], 0, s[84:85]
	s_addc_u32 s1, s1, 0
	s_add_i32 s6, s33, s24
	global_load_lds_dwordx4 v[220:221], off
	v_lshl_add_u64 v[220:221], s[0:1], 0, v[146:147]
	s_mov_b32 m0, s6
	s_nop 0
	global_load_lds_dwordx4 v[220:221], off
	v_lshl_add_u64 v[220:221], s[0:1], 0, v[150:151]
	s_add_i32 m0, s6, 0x2000
	s_nop 0
	global_load_lds_dwordx4 v[220:221], off
	v_lshl_add_u64 v[220:221], v[234:235], 0, s[84:85]
	s_mov_b32 m0, s67
	s_nop 0
	global_load_lds_dwordx4 v[220:221], off
	v_lshl_add_u64 v[220:221], v[236:237], 0, s[84:85]
	s_mov_b32 m0, s22
	s_nop 0
	global_load_lds_dwordx4 v[220:221], off
	s_waitcnt vmcnt(8)
	s_waitcnt lgkmcnt(0)
	s_barrier
	s_setprio 1
	s_waitcnt lgkmcnt(0)
	v_mfma_f32_16x16x32_bf16 v[76:79], v[24:27], v[180:183], v[76:79]
	v_mfma_f32_16x16x32_bf16 v[60:63], v[24:27], v[188:191], v[60:63]
	v_mfma_f32_16x16x32_bf16 v[44:47], v[24:27], v[196:199], v[44:47]
	v_mfma_f32_16x16x32_bf16 v[4:7], v[24:27], v[216:219], v[4:7]
	v_mfma_f32_16x16x32_bf16 v[76:79], v[28:31], v[184:187], v[76:79]
	v_mfma_f32_16x16x32_bf16 v[72:75], v[64:67], v[180:183], v[72:75]
	v_mfma_f32_16x16x32_bf16 v[60:63], v[28:31], v[192:195], v[60:63]
	v_mfma_f32_16x16x32_bf16 v[56:59], v[64:67], v[188:191], v[56:59]
	v_mfma_f32_16x16x32_bf16 v[44:47], v[28:31], v[200:203], v[44:47]
	v_mfma_f32_16x16x32_bf16 v[40:43], v[64:67], v[196:199], v[40:43]
	v_mfma_f32_16x16x32_bf16 v[28:31], v[28:31], v[228:231], v[4:7]
	v_mfma_f32_16x16x32_bf16 v[4:7], v[64:67], v[216:219], v[12:15]
	v_mfma_f32_16x16x32_bf16 v[72:75], v[68:71], v[184:187], v[72:75]
	v_mfma_f32_16x16x32_bf16 v[56:59], v[68:71], v[192:195], v[56:59]
	v_mfma_f32_16x16x32_bf16 v[40:43], v[68:71], v[200:203], v[40:43]
	v_mfma_f32_16x16x32_bf16 v[24:27], v[68:71], v[228:231], v[4:7]
	v_mfma_f32_16x16x32_bf16 v[4:7], v[164:167], v[180:183], v[16:19]
	v_mfma_f32_16x16x32_bf16 v[68:71], v[168:171], v[184:187], v[4:7]
	v_mfma_f32_16x16x32_bf16 v[4:7], v[172:175], v[180:183], v[20:23]
	v_mfma_f32_16x16x32_bf16 v[64:67], v[176:179], v[184:187], v[4:7]
	v_mfma_f32_16x16x32_bf16 v[4:7], v[164:167], v[188:191], v[52:55]
	v_mfma_f32_16x16x32_bf16 v[52:55], v[168:171], v[192:195], v[4:7]
	v_mfma_f32_16x16x32_bf16 v[4:7], v[172:175], v[188:191], v[48:51]
	v_mfma_f32_16x16x32_bf16 v[48:51], v[176:179], v[192:195], v[4:7]
	v_mfma_f32_16x16x32_bf16 v[4:7], v[164:167], v[196:199], v[36:39]
	v_mfma_f32_16x16x32_bf16 v[36:39], v[168:171], v[200:203], v[4:7]
	v_mfma_f32_16x16x32_bf16 v[4:7], v[172:175], v[196:199], v[32:35]
	v_mfma_f32_16x16x32_bf16 v[32:35], v[176:179], v[200:203], v[4:7]
	v_mfma_f32_16x16x32_bf16 v[4:7], v[164:167], v[216:219], v[8:11]
	v_mfma_f32_16x16x32_bf16 v[0:3], v[172:175], v[216:219], v[0:3]
	v_mfma_f32_16x16x32_bf16 v[8:11], v[168:171], v[228:231], v[4:7]
	v_mfma_f32_16x16x32_bf16 v[0:3], v[176:179], v[228:231], v[0:3]
	s_setprio 0
	s_barrier
	s_add_i32 s17, s17, 2
	s_add_u32 s4, s4, 0x100
	s_addc_u32 s5, s5, 0
	s_add_u32 s15, s15, 0x100
	s_addc_u32 s16, s16, 0
	s_cmp_gt_u32 s17, 29
	s_cbranch_scc0 .LBB0_263
	s_and_b64 vcc, exec, s[86:87]
	s_cbranch_vccz .LBB0_266
	s_barrier

; #define PG8_STAGE(bufoff, gbase, voff) do { _Pragma("unroll") for (int _i = 0; _i < 2; ++_i) \
;         __builtin_amdgcn_global_load_lds((const unsigned*)((const char*)(gbase) + (voff)[_i]), (PG8_LAS unsigned*)(lds + (bufoff) + ldsw + _i * 8192), 16, 0, 0); } while (0)
; #define PG8_LDA(dst, b, h) do { _Pragma("unroll") for (int m = 0; m < 4; ++m) _Pragma("unroll") for (int k = 0; k < 2; ++k) dst[m][k] = *(const PG8_LAS bf16x8*)(lds + PG8_SA(b, h) + aoff + m * 2048 + k * 1024); } while (0)
; #define PG8_LDB(dst, b, h) do { _Pragma("unroll") for (int n = 0; n < 2; ++n) _Pragma("unroll") for (int k = 0; k < 2; ++k) dst[n][k] = *(const PG8_LAS bf16x8*)(lds + PG8_SB(b, h) + boff + n * 2048 + k * 1024); } while (0)
; #define PG8_MMA(ai, bj, At, Bt) do { __builtin_amdgcn_s_setprio(1); _Pragma("unroll") for (int m = 0; m < 4; ++m) _Pragma("unroll") for (int n = 0; n < 2; ++n) _Pragma("unroll") for (int k = 0; k < 2; ++k) \
;         acc[ai][bj][m][n] = __builtin_amdgcn_mfma_f32_16x16x32_bf16(Bt[n][k], At[m][k], acc[ai][bj][m][n], 0, 0, 0); __builtin_amdgcn_s_setprio(0); } while (0)
; #define PG8_WAIT_V(n) asm volatile("s_waitcnt vmcnt(" #n ")" ::: "memory")
; #define PG8_WAIT_L(n) asm volatile("s_waitcnt lgkmcnt(" #n ")" ::: "memory")
; #define PG8_BAR __builtin_amdgcn_s_barrier()
; #define PG8_SCHED __builtin_amdgcn_sched_barrier(0)
; template <class Epi, class Sched, bool ALIGN_EPI = false, bool SP2 = false>
; __device__ __forceinline__ void gemm_phase(PG8_LAS unsigned char* lds, const Gemm g, const Sched& S, const Epi& E) {
;     ...
;             PG8_LDB(B0, 0, 0); PG8_LDB(B1, 0, 1); PG8_SCHED; PG8_LDA(At, 0, 0); PG8_STAGE(PG8_SA(1, 1), a1 + hstep, voffA);
;             PG8_WAIT_V(8); PG8_WAIT_L(0); PG8_BAR; PG8_MMA(0, 0, At, B0); PG8_MMA(0, 1, At, B1); PG8_BAR; PG8_SCHED;
;             PG8_LDA(At, 0, 1); PG8_STAGE(PG8_SB(0, 0), b2, voffB); PG8_STAGE(PG8_SB(0, 1), b2 + hstep, voffB); PG8_STAGE(PG8_SA(0, 0), a2, voffA);
.LBB0_1678:
	ds_read_b128 v[144:147], v157
	ds_read_b128 v[148:151], v157 offset:1024
	ds_read_b128 v[160:163], v157 offset:2048
	ds_read_b128 v[164:167], v157 offset:3072
	ds_read_b128 v[168:171], v158
	ds_read_b128 v[172:175], v158 offset:1024
	ds_read_b128 v[176:179], v158 offset:2048
	ds_read_b128 v[180:183], v158 offset:3072
	s_add_u32 s0, s36, 0xfffc0080
	s_addc_u32 s1, s37, -1
	s_cmp_eq_u32 s55, 12
	s_cselect_b32 s25, s21, s1
	s_cselect_b32 s24, s51, s0
	s_cselect_b32 s1, s19, s54
	s_cselect_b32 s0, s52, s53
	v_lshl_add_u64 v[152:153], s[36:37], 0, v[136:137]
	s_add_i32 m0, s31, 0xc000
	ds_read_b128 v[184:187], v159
	ds_read_b128 v[188:191], v159 offset:1024
	ds_read_b128 v[192:195], v159 offset:2048
	ds_read_b128 v[196:199], v159 offset:3072
	ds_read_b128 v[200:203], v159 offset:4096
	ds_read_b128 v[204:207], v159 offset:5120
	ds_read_b128 v[208:211], v159 offset:6144
	ds_read_b128 v[212:215], v159 offset:7168
	global_load_lds_dwordx4 v[152:153], off
	v_lshl_add_u64 v[152:153], s[36:37], 0, v[138:139]
	s_add_i32 m0, s31, 0xe000
	s_nop 0
	global_load_lds_dwordx4 v[152:153], off
	s_waitcnt vmcnt(8)
	s_waitcnt lgkmcnt(0)
	s_barrier
	s_setprio 1
	s_waitcnt lgkmcnt(0)
	v_mfma_f32_16x16x32_bf16 v[124:127], v[144:147], v[184:187], v[124:127]
	v_mfma_f32_16x16x32_bf16 v[120:123], v[160:163], v[184:187], v[120:123]
	v_mfma_f32_16x16x32_bf16 v[116:119], v[144:147], v[192:195], v[116:119]
	v_mfma_f32_16x16x32_bf16 v[108:111], v[160:163], v[192:195], v[108:111]
	v_mfma_f32_16x16x32_bf16 v[96:99], v[144:147], v[200:203], v[96:99]
	v_mfma_f32_16x16x32_bf16 v[88:91], v[160:163], v[200:203], v[88:91]
	v_mfma_f32_16x16x32_bf16 v[80:83], v[144:147], v[208:211], v[80:83]
	v_mfma_f32_16x16x32_bf16 v[72:75], v[160:163], v[208:211], v[72:75]
	v_mfma_f32_16x16x32_bf16 v[124:127], v[148:151], v[188:191], v[124:127]
	v_mfma_f32_16x16x32_bf16 v[120:123], v[164:167], v[188:191], v[120:123]
	v_mfma_f32_16x16x32_bf16 v[116:119], v[148:151], v[196:199], v[116:119]
	v_mfma_f32_16x16x32_bf16 v[108:111], v[164:167], v[196:199], v[108:111]
	v_mfma_f32_16x16x32_bf16 v[96:99], v[148:151], v[204:207], v[96:99]
	v_mfma_f32_16x16x32_bf16 v[88:91], v[164:167], v[204:207], v[88:91]
	v_mfma_f32_16x16x32_bf16 v[80:83], v[148:151], v[212:215], v[80:83]
	v_mfma_f32_16x16x32_bf16 v[72:75], v[164:167], v[212:215], v[72:75]
	v_mfma_f32_16x16x32_bf16 v[112:115], v[168:171], v[184:187], v[112:115]
	v_mfma_f32_16x16x32_bf16 v[104:107], v[176:179], v[184:187], v[104:107]
	v_mfma_f32_16x16x32_bf16 v[100:103], v[168:171], v[192:195], v[100:103]
	v_mfma_f32_16x16x32_bf16 v[92:95], v[176:179], v[192:195], v[92:95]
	v_mfma_f32_16x16x32_bf16 v[84:87], v[168:171], v[200:203], v[84:87]
	v_mfma_f32_16x16x32_bf16 v[76:79], v[176:179], v[200:203], v[76:79]
	v_mfma_f32_16x16x32_bf16 v[68:71], v[168:171], v[208:211], v[68:71]
	v_mfma_f32_16x16x32_bf16 v[64:67], v[176:179], v[208:211], v[64:67]
	v_mfma_f32_16x16x32_bf16 v[112:115], v[172:175], v[188:191], v[112:115]
	v_mfma_f32_16x16x32_bf16 v[104:107], v[180:183], v[188:191], v[104:107]
	v_mfma_f32_16x16x32_bf16 v[100:103], v[172:175], v[196:199], v[100:103]
	v_mfma_f32_16x16x32_bf16 v[92:95], v[180:183], v[196:199], v[92:95]
	v_mfma_f32_16x16x32_bf16 v[84:87], v[172:175], v[204:207], v[84:87]
	v_mfma_f32_16x16x32_bf16 v[76:79], v[180:183], v[204:207], v[76:79]
	v_mfma_f32_16x16x32_bf16 v[68:71], v[172:175], v[212:215], v[68:71]
	v_mfma_f32_16x16x32_bf16 v[64:67], v[180:183], v[212:215], v[64:67]
	s_setprio 0
	s_barrier
	s_add_i32 s56, s44, s17
	v_lshl_add_u64 v[152:153], s[0:1], 0, v[130:131]
	s_mov_b32 m0, s56
	ds_read_b128 v[184:187], v159 offset:16384
	ds_read_b128 v[188:191], v159 offset:17408
	ds_read_b128 v[192:195], v159 offset:18432
	ds_read_b128 v[196:199], v159 offset:19456
	ds_read_b128 v[200:203], v159 offset:20480
	ds_read_b128 v[204:207], v159 offset:21504
	ds_read_b128 v[208:211], v159 offset:22528
	ds_read_b128 v[212:215], v159 offset:23552
	global_load_lds_dwordx4 v[152:153], off
	s_add_i32 m0, s56, 0x2000
	s_add_u32 s56, s0, 0x40000
	v_lshl_add_u64 v[216:217], s[0:1], 0, v[134:135]
	s_addc_u32 s57, s1, 0
	s_add_i32 s58, s45, s17
	global_load_lds_dwordx4 v[216:217], off
	v_lshl_add_u64 v[218:219], s[56:57], 0, v[130:131]
	s_mov_b32 m0, s58
	v_lshl_add_u64 v[220:221], s[24:25], 0, v[132:133]
	global_load_lds_dwordx4 v[218:219], off
	v_lshl_add_u64 v[218:219], s[56:57], 0, v[134:135]
	s_add_i32 m0, s58, 0x2000
	s_nop 0
	global_load_lds_dwordx4 v[218:219], off
	v_lshl_add_u64 v[218:219], s[24:25], 0, v[128:129]
	s_mov_b32 m0, s31
	s_nop 0
	global_load_lds_dwordx4 v[218:219], off
	s_mov_b32 m0, s33
	s_nop 0
	global_load_lds_dwordx4 v[220:221], off
	s_waitcnt vmcnt(8)
	s_waitcnt lgkmcnt(0)
	s_barrier
; #define PG8_STAGE(bufoff, gbase, voff) do { _Pragma("unroll") for (int _i = 0; _i < 2; ++_i) \
;         __builtin_amdgcn_global_load_lds((const unsigned*)((const char*)(gbase) + (voff)[_i]), (PG8_LAS unsigned*)(lds + (bufoff) + ldsw + _i * 8192), 16, 0, 0); } while (0)
; #define PG8_LDA(dst, b, h) do { _Pragma("unroll") for (int m = 0; m < 4; ++m) _Pragma("unroll") for (int k = 0; k < 2; ++k) dst[m][k] = *(const PG8_LAS bf16x8*)(lds + PG8_SA(b, h) + aoff + m * 2048 + k * 1024); } while (0)
; #define PG8_LDB(dst, b, h) do { _Pragma("unroll") for (int n = 0; n < 2; ++n) _Pragma("unroll") for (int k = 0; k < 2; ++k) dst[n][k] = *(const PG8_LAS bf16x8*)(lds + PG8_SB(b, h) + boff + n * 2048 + k * 1024); } while (0)
; #define PG8_MMA(ai, bj, At, Bt) do { __builtin_amdgcn_s_setprio(1); _Pragma("unroll") for (int m = 0; m < 4; ++m) _Pragma("unroll") for (int n = 0; n < 2; ++n) _Pragma("unroll") for (int k = 0; k < 2; ++k) \
;         acc[ai][bj][m][n] = __builtin_amdgcn_mfma_f32_16x16x32_bf16(Bt[n][k], At[m][k], acc[ai][bj][m][n], 0, 0, 0); __builtin_amdgcn_s_setprio(0); } while (0)
; #define PG8_WAIT_V(n) asm volatile("s_waitcnt vmcnt(" #n ")" ::: "memory")
; #define PG8_WAIT_L(n) asm volatile("s_waitcnt lgkmcnt(" #n ")" ::: "memory")
; #define PG8_BAR __builtin_amdgcn_s_barrier()
; #define PG8_SCHED __builtin_amdgcn_sched_barrier(0)
; template <class Epi, class Sched, bool ALIGN_EPI = false, bool SP2 = false>
; __device__ __forceinline__ void gemm_phase(PG8_LAS unsigned char* lds, const Gemm g, const Sched& S, const Epi& E) {
;     ...
;             PG8_WAIT_V(8); PG8_WAIT_L(0); PG8_BAR; PG8_MMA(1, 0, At, B0); PG8_MMA(1, 1, At, B1); PG8_BAR; PG8_SCHED;
;             PG8_LDB(B0, 1, 0); PG8_LDB(B1, 1, 1); PG8_SCHED; PG8_LDA(At, 1, 0); PG8_STAGE(PG8_SA(0, 1), a2 + hstep, voffA);
;             PG8_WAIT_V(8); PG8_WAIT_L(0); PG8_BAR; PG8_MMA(0, 0, At, B0); PG8_MMA(0, 1, At, B1); PG8_BAR; PG8_SCHED;
	s_setprio 1
	s_waitcnt lgkmcnt(0)
	v_mfma_f32_16x16x32_bf16 v[60:63], v[144:147], v[184:187], v[60:63]
	v_mfma_f32_16x16x32_bf16 v[56:59], v[160:163], v[184:187], v[56:59]
	v_mfma_f32_16x16x32_bf16 v[48:51], v[144:147], v[192:195], v[48:51]
	v_mfma_f32_16x16x32_bf16 v[40:43], v[160:163], v[192:195], v[40:43]
	v_mfma_f32_16x16x32_bf16 v[32:35], v[144:147], v[200:203], v[32:35]
	v_mfma_f32_16x16x32_bf16 v[24:27], v[160:163], v[200:203], v[24:27]
	v_mfma_f32_16x16x32_bf16 v[16:19], v[144:147], v[208:211], v[16:19]
	v_mfma_f32_16x16x32_bf16 v[8:11], v[160:163], v[208:211], v[8:11]
	v_mfma_f32_16x16x32_bf16 v[60:63], v[148:151], v[188:191], v[60:63]
	v_mfma_f32_16x16x32_bf16 v[56:59], v[164:167], v[188:191], v[56:59]
	v_mfma_f32_16x16x32_bf16 v[48:51], v[148:151], v[196:199], v[48:51]
	v_mfma_f32_16x16x32_bf16 v[40:43], v[164:167], v[196:199], v[40:43]
	v_mfma_f32_16x16x32_bf16 v[32:35], v[148:151], v[204:207], v[32:35]
	v_mfma_f32_16x16x32_bf16 v[24:27], v[164:167], v[204:207], v[24:27]
	v_mfma_f32_16x16x32_bf16 v[16:19], v[148:151], v[212:215], v[16:19]
	v_mfma_f32_16x16x32_bf16 v[8:11], v[164:167], v[212:215], v[8:11]
	v_mfma_f32_16x16x32_bf16 v[52:55], v[168:171], v[184:187], v[52:55]
	v_mfma_f32_16x16x32_bf16 v[44:47], v[176:179], v[184:187], v[44:47]
	v_mfma_f32_16x16x32_bf16 v[36:39], v[168:171], v[192:195], v[36:39]
	v_mfma_f32_16x16x32_bf16 v[28:31], v[176:179], v[192:195], v[28:31]
	v_mfma_f32_16x16x32_bf16 v[20:23], v[168:171], v[200:203], v[20:23]
	v_mfma_f32_16x16x32_bf16 v[12:15], v[176:179], v[200:203], v[12:15]
	v_mfma_f32_16x16x32_bf16 v[4:7], v[168:171], v[208:211], v[4:7]
	v_mfma_f32_16x16x32_bf16 v[0:3], v[176:179], v[208:211], v[0:3]
	v_mfma_f32_16x16x32_bf16 v[52:55], v[172:175], v[188:191], v[52:55]
	v_mfma_f32_16x16x32_bf16 v[44:47], v[180:183], v[188:191], v[44:47]
	v_mfma_f32_16x16x32_bf16 v[36:39], v[172:175], v[196:199], v[36:39]
	v_mfma_f32_16x16x32_bf16 v[28:31], v[180:183], v[196:199], v[28:31]
	v_mfma_f32_16x16x32_bf16 v[20:23], v[172:175], v[204:207], v[20:23]
	v_mfma_f32_16x16x32_bf16 v[12:15], v[180:183], v[204:207], v[12:15]
	v_mfma_f32_16x16x32_bf16 v[4:7], v[172:175], v[212:215], v[4:7]
	v_mfma_f32_16x16x32_bf16 v[0:3], v[180:183], v[212:215], v[0:3]
	s_setprio 0
	s_barrier
	s_add_i32 s56, 0, 0x18000
	s_add_i32 s57, 0, 0x1c000
	v_add_u32_e32 v164, s56, v155
	v_add_u32_e32 v180, s57, v155
	ds_read_b128 v[144:147], v164
	ds_read_b128 v[148:151], v164 offset:1024
	ds_read_b128 v[160:163], v164 offset:2048
	ds_read_b128 v[164:167], v164 offset:3072
	ds_read_b128 v[168:171], v180
	ds_read_b128 v[172:175], v180 offset:1024
	ds_read_b128 v[176:179], v180 offset:2048
	ds_read_b128 v[180:183], v180 offset:3072
	s_add_u32 s24, s24, 0x40000
	s_addc_u32 s25, s25, 0
	s_mov_b32 m0, s35
	v_lshl_add_u64 v[228:229], s[24:25], 0, v[128:129]
	ds_read_b128 v[184:187], v159 offset:32768
	ds_read_b128 v[188:191], v159 offset:33792
	ds_read_b128 v[192:195], v159 offset:34816
	ds_read_b128 v[196:199], v159 offset:35840
	ds_read_b128 v[200:203], v159 offset:36864
	ds_read_b128 v[204:207], v159 offset:37888
	ds_read_b128 v[208:211], v159 offset:38912
	ds_read_b128 v[212:215], v159 offset:39936
	global_load_lds_dwordx4 v[228:229], off
	v_lshl_add_u64 v[228:229], s[24:25], 0, v[132:133]
	s_mov_b32 m0, s38
	s_nop 0
	global_load_lds_dwordx4 v[228:229], off
	s_waitcnt vmcnt(8)
	s_waitcnt lgkmcnt(0)
	s_barrier
	s_setprio 1
	s_waitcnt lgkmcnt(0)
	v_mfma_f32_16x16x32_bf16 v[124:127], v[144:147], v[184:187], v[124:127]
	v_mfma_f32_16x16x32_bf16 v[120:123], v[160:163], v[184:187], v[120:123]
	v_mfma_f32_16x16x32_bf16 v[116:119], v[144:147], v[192:195], v[116:119]
	v_mfma_f32_16x16x32_bf16 v[108:111], v[160:163], v[192:195], v[108:111]
	v_mfma_f32_16x16x32_bf16 v[96:99], v[144:147], v[200:203], v[96:99]
	v_mfma_f32_16x16x32_bf16 v[88:91], v[160:163], v[200:203], v[88:91]
	v_mfma_f32_16x16x32_bf16 v[80:83], v[144:147], v[208:211], v[80:83]
	v_mfma_f32_16x16x32_bf16 v[72:75], v[160:163], v[208:211], v[72:75]
	v_mfma_f32_16x16x32_bf16 v[124:127], v[148:151], v[188:191], v[124:127]
	v_mfma_f32_16x16x32_bf16 v[120:123], v[164:167], v[188:191], v[120:123]
	v_mfma_f32_16x16x32_bf16 v[116:119], v[148:151], v[196:199], v[116:119]
	v_mfma_f32_16x16x32_bf16 v[108:111], v[164:167], v[196:199], v[108:111]
	v_mfma_f32_16x16x32_bf16 v[96:99], v[148:151], v[204:207], v[96:99]
	v_mfma_f32_16x16x32_bf16 v[88:91], v[164:167], v[204:207], v[88:91]
	v_mfma_f32_16x16x32_bf16 v[80:83], v[148:151], v[212:215], v[80:83]
	v_mfma_f32_16x16x32_bf16 v[72:75], v[164:167], v[212:215], v[72:75]
	v_mfma_f32_16x16x32_bf16 v[112:115], v[168:171], v[184:187], v[112:115]
	v_mfma_f32_16x16x32_bf16 v[104:107], v[176:179], v[184:187], v[104:107]
	v_mfma_f32_16x16x32_bf16 v[100:103], v[168:171], v[192:195], v[100:103]
	v_mfma_f32_16x16x32_bf16 v[92:95], v[176:179], v[192:195], v[92:95]
	v_mfma_f32_16x16x32_bf16 v[84:87], v[168:171], v[200:203], v[84:87]
	v_mfma_f32_16x16x32_bf16 v[76:79], v[176:179], v[200:203], v[76:79]
	v_mfma_f32_16x16x32_bf16 v[68:71], v[168:171], v[208:211], v[68:71]
	v_mfma_f32_16x16x32_bf16 v[64:67], v[176:179], v[208:211], v[64:67]
	v_mfma_f32_16x16x32_bf16 v[112:115], v[172:175], v[188:191], v[112:115]
	v_mfma_f32_16x16x32_bf16 v[104:107], v[180:183], v[188:191], v[104:107]
	v_mfma_f32_16x16x32_bf16 v[100:103], v[172:175], v[196:199], v[100:103]
	v_mfma_f32_16x16x32_bf16 v[92:95], v[180:183], v[196:199], v[92:95]
	v_mfma_f32_16x16x32_bf16 v[84:87], v[172:175], v[204:207], v[84:87]
	v_mfma_f32_16x16x32_bf16 v[76:79], v[180:183], v[204:207], v[76:79]
	v_mfma_f32_16x16x32_bf16 v[68:71], v[172:175], v[212:215], v[68:71]
	v_mfma_f32_16x16x32_bf16 v[64:67], v[180:183], v[212:215], v[64:67]
	s_setprio 0
	s_barrier
; #define PG8_STAGE(bufoff, gbase, voff) do { _Pragma("unroll") for (int _i = 0; _i < 2; ++_i) \
;         __builtin_amdgcn_global_load_lds((const unsigned*)((const char*)(gbase) + (voff)[_i]), (PG8_LAS unsigned*)(lds + (bufoff) + ldsw + _i * 8192), 16, 0, 0); } while (0)
; #define PG8_LDA(dst, b, h) do { _Pragma("unroll") for (int m = 0; m < 4; ++m) _Pragma("unroll") for (int k = 0; k < 2; ++k) dst[m][k] = *(const PG8_LAS bf16x8*)(lds + PG8_SA(b, h) + aoff + m * 2048 + k * 1024); } while (0)
; #define PG8_MMA(ai, bj, At, Bt) do { __builtin_amdgcn_s_setprio(1); _Pragma("unroll") for (int m = 0; m < 4; ++m) _Pragma("unroll") for (int n = 0; n < 2; ++n) _Pragma("unroll") for (int k = 0; k < 2; ++k) \
;         acc[ai][bj][m][n] = __builtin_amdgcn_mfma_f32_16x16x32_bf16(Bt[n][k], At[m][k], acc[ai][bj][m][n], 0, 0, 0); __builtin_amdgcn_s_setprio(0); } while (0)
; #define PG8_WAIT_V(n) asm volatile("s_waitcnt vmcnt(" #n ")" ::: "memory")
; #define PG8_WAIT_L(n) asm volatile("s_waitcnt lgkmcnt(" #n ")" ::: "memory")
; #define PG8_BAR __builtin_amdgcn_s_barrier()
; #define PG8_SCHED __builtin_amdgcn_sched_barrier(0)
; template <class Epi, class Sched, bool ALIGN_EPI = false, bool SP2 = false>
; __device__ __forceinline__ void gemm_phase(PG8_LAS unsigned char* lds, const Gemm g, const Sched& S, const Epi& E) {
;     ...
;             PG8_LDA(At, 1, 1); PG8_STAGE(PG8_SB(1, 0), b3, voffB); PG8_STAGE(PG8_SB(1, 1), b3 + hstep, voffB); PG8_STAGE(PG8_SA(1, 0), a3, voffA);
;             PG8_WAIT_V(8); PG8_WAIT_L(0); PG8_BAR; PG8_MMA(1, 0, At, B0); PG8_MMA(1, 1, At, B1); PG8_BAR; PG8_SCHED;
;     ...
;         if constexpr (ALIGN_EPI) { if (wr == 0) PG8_BAR; }
	s_add_i32 s24, s56, s17
	v_lshl_add_u64 v[152:153], v[152:153], 0, s[12:13]
	s_mov_b32 m0, s24
	ds_read_b128 v[184:187], v159 offset:49152
	ds_read_b128 v[188:191], v159 offset:50176
	ds_read_b128 v[192:195], v159 offset:51200
	ds_read_b128 v[196:199], v159 offset:52224
	ds_read_b128 v[200:203], v159 offset:53248
	ds_read_b128 v[204:207], v159 offset:54272
	ds_read_b128 v[208:211], v159 offset:55296
	ds_read_b128 v[212:215], v159 offset:56320
	global_load_lds_dwordx4 v[152:153], off
	s_add_i32 m0, s24, 0x2000
	s_add_u32 s0, s0, 0x40080
	v_lshl_add_u64 v[152:153], v[216:217], 0, s[12:13]
	s_addc_u32 s1, s1, 0
	s_add_i32 s24, s57, s17
	global_load_lds_dwordx4 v[152:153], off
	v_lshl_add_u64 v[152:153], s[0:1], 0, v[130:131]
	s_mov_b32 m0, s24
	s_nop 0
	global_load_lds_dwordx4 v[152:153], off
	v_lshl_add_u64 v[152:153], s[0:1], 0, v[134:135]
	s_add_i32 m0, s24, 0x2000
	s_nop 0
	global_load_lds_dwordx4 v[152:153], off
	v_lshl_add_u64 v[152:153], v[218:219], 0, s[12:13]
	s_mov_b32 m0, s40
	s_nop 0
	global_load_lds_dwordx4 v[152:153], off
	v_lshl_add_u64 v[152:153], v[220:221], 0, s[12:13]
	s_mov_b32 m0, s41
	s_nop 0
	global_load_lds_dwordx4 v[152:153], off
	s_waitcnt vmcnt(8)
	s_waitcnt lgkmcnt(0)
	s_barrier
	s_setprio 1
	s_waitcnt lgkmcnt(0)
	v_mfma_f32_16x16x32_bf16 v[60:63], v[144:147], v[184:187], v[60:63]
	v_mfma_f32_16x16x32_bf16 v[56:59], v[160:163], v[184:187], v[56:59]
	v_mfma_f32_16x16x32_bf16 v[48:51], v[144:147], v[192:195], v[48:51]
	v_mfma_f32_16x16x32_bf16 v[40:43], v[160:163], v[192:195], v[40:43]
	v_mfma_f32_16x16x32_bf16 v[32:35], v[144:147], v[200:203], v[32:35]
	v_mfma_f32_16x16x32_bf16 v[24:27], v[160:163], v[200:203], v[24:27]
	v_mfma_f32_16x16x32_bf16 v[16:19], v[144:147], v[208:211], v[16:19]
	v_mfma_f32_16x16x32_bf16 v[8:11], v[160:163], v[208:211], v[8:11]
	v_mfma_f32_16x16x32_bf16 v[60:63], v[148:151], v[188:191], v[60:63]
	v_mfma_f32_16x16x32_bf16 v[56:59], v[164:167], v[188:191], v[56:59]
	v_mfma_f32_16x16x32_bf16 v[48:51], v[148:151], v[196:199], v[48:51]
	v_mfma_f32_16x16x32_bf16 v[40:43], v[164:167], v[196:199], v[40:43]
	v_mfma_f32_16x16x32_bf16 v[32:35], v[148:151], v[204:207], v[32:35]
	v_mfma_f32_16x16x32_bf16 v[24:27], v[164:167], v[204:207], v[24:27]
	v_mfma_f32_16x16x32_bf16 v[16:19], v[148:151], v[212:215], v[16:19]
	v_mfma_f32_16x16x32_bf16 v[8:11], v[164:167], v[212:215], v[8:11]
	v_mfma_f32_16x16x32_bf16 v[52:55], v[168:171], v[184:187], v[52:55]
	v_mfma_f32_16x16x32_bf16 v[44:47], v[176:179], v[184:187], v[44:47]
	v_mfma_f32_16x16x32_bf16 v[36:39], v[168:171], v[192:195], v[36:39]
	v_mfma_f32_16x16x32_bf16 v[28:31], v[176:179], v[192:195], v[28:31]
	v_mfma_f32_16x16x32_bf16 v[20:23], v[168:171], v[200:203], v[20:23]
	v_mfma_f32_16x16x32_bf16 v[12:15], v[176:179], v[200:203], v[12:15]
	v_mfma_f32_16x16x32_bf16 v[4:7], v[168:171], v[208:211], v[4:7]
	v_mfma_f32_16x16x32_bf16 v[0:3], v[176:179], v[208:211], v[0:3]
	v_mfma_f32_16x16x32_bf16 v[52:55], v[172:175], v[188:191], v[52:55]
	v_mfma_f32_16x16x32_bf16 v[44:47], v[180:183], v[188:191], v[44:47]
	v_mfma_f32_16x16x32_bf16 v[36:39], v[172:175], v[196:199], v[36:39]
	v_mfma_f32_16x16x32_bf16 v[28:31], v[180:183], v[196:199], v[28:31]
	v_mfma_f32_16x16x32_bf16 v[20:23], v[172:175], v[204:207], v[20:23]
	v_mfma_f32_16x16x32_bf16 v[12:15], v[180:183], v[204:207], v[12:15]
	v_mfma_f32_16x16x32_bf16 v[4:7], v[172:175], v[212:215], v[4:7]
	v_mfma_f32_16x16x32_bf16 v[0:3], v[180:183], v[212:215], v[0:3]
	s_setprio 0
	s_barrier
	s_add_i32 s55, s55, 2
	s_add_u32 s36, s36, 0x100
	s_addc_u32 s37, s37, 0
	s_add_u32 s53, s53, 0x100
	s_addc_u32 s54, s54, 0
	s_cmp_gt_u32 s55, 13
	s_cbranch_scc0 .LBB0_1678
	s_and_b64 vcc, exec, s[14:15]
	s_cbranch_vccz .LBB0_1681
	s_barrier

; #define PG8_STAGE(bufoff, gbase, voff) do { _Pragma("unroll") for (int _i = 0; _i < 2; ++_i) \
;         __builtin_amdgcn_global_load_lds((const unsigned*)((const char*)(gbase) + (voff)[_i]), (PG8_LAS unsigned*)(lds + (bufoff) + ldsw + _i * 8192), 16, 0, 0); } while (0)
; #define PG8_LDA(dst, b, h) do { _Pragma("unroll") for (int m = 0; m < 4; ++m) _Pragma("unroll") for (int k = 0; k < 2; ++k) dst[m][k] = *(const PG8_LAS bf16x8*)(lds + PG8_SA(b, h) + aoff + m * 2048 + k * 1024); } while (0)
; #define PG8_LDB(dst, b, h) do { _Pragma("unroll") for (int n = 0; n < 2; ++n) _Pragma("unroll") for (int k = 0; k < 2; ++k) dst[n][k] = *(const PG8_LAS bf16x8*)(lds + PG8_SB(b, h) + boff + n * 2048 + k * 1024); } while (0)
; #define PG8_MMA(ai, bj, At, Bt) do { __builtin_amdgcn_s_setprio(1); _Pragma("unroll") for (int m = 0; m < 4; ++m) _Pragma("unroll") for (int n = 0; n < 2; ++n) _Pragma("unroll") for (int k = 0; k < 2; ++k) \
;         acc[ai][bj][m][n] = __builtin_amdgcn_mfma_f32_16x16x32_bf16(Bt[n][k], At[m][k], acc[ai][bj][m][n], 0, 0, 0); __builtin_amdgcn_s_setprio(0); } while (0)
; #define PG8_WAIT_V(n) asm volatile("s_waitcnt vmcnt(" #n ")" ::: "memory")
; #define PG8_WAIT_L(n) asm volatile("s_waitcnt lgkmcnt(" #n ")" ::: "memory")
; #define PG8_BAR __builtin_amdgcn_s_barrier()
; #define PG8_SCHED __builtin_amdgcn_sched_barrier(0)
; template <class Epi, class Sched, bool ALIGN_EPI = false, bool SP2 = false>
; __device__ __forceinline__ void gemm_phase(PG8_LAS unsigned char* lds, const Gemm g, const Sched& S, const Epi& E) {
;     ...
;             PG8_LDB(B0, 0, 0); PG8_LDB(B1, 0, 1); PG8_SCHED; PG8_LDA(At, 0, 0); PG8_STAGE(PG8_SA(1, 1), a1 + hstep, voffA);
;             PG8_WAIT_V(8); PG8_WAIT_L(0); PG8_BAR; PG8_MMA(0, 0, At, B0); PG8_MMA(0, 1, At, B1); PG8_BAR; PG8_SCHED;
;             PG8_LDA(At, 0, 1); PG8_STAGE(PG8_SB(0, 0), b2, voffB); PG8_STAGE(PG8_SB(0, 1), b2 + hstep, voffB); PG8_STAGE(PG8_SA(0, 0), a2, voffA);
.LBB0_1702:
	ds_read_b128 v[128:131], v175
	ds_read_b128 v[132:135], v175 offset:1024
	ds_read_b128 v[136:139], v175 offset:2048
	ds_read_b128 v[156:159], v175 offset:3072
	ds_read_b128 v[160:163], v176
	ds_read_b128 v[164:167], v176 offset:1024
	ds_read_b128 v[168:171], v176 offset:2048
	ds_read_b128 v[178:181], v176 offset:3072
	s_add_u32 s0, s38, 0xfffc0080
	s_addc_u32 s1, s39, -1
	s_cmp_eq_u32 s57, 12
	s_cselect_b32 s25, s23, s1
	s_cselect_b32 s24, s53, s0
	s_cselect_b32 s1, s21, s56
	s_cselect_b32 s0, s54, s55
	v_lshl_add_u64 v[214:215], s[38:39], 0, v[148:149]
	s_add_i32 m0, s33, 0xc000
	ds_read_b128 v[182:185], v177
	ds_read_b128 v[186:189], v177 offset:1024
	ds_read_b128 v[190:193], v177 offset:2048
	ds_read_b128 v[194:197], v177 offset:3072
	ds_read_b128 v[198:201], v177 offset:4096
	ds_read_b128 v[202:205], v177 offset:5120
	ds_read_b128 v[206:209], v177 offset:6144
	ds_read_b128 v[210:213], v177 offset:7168
	global_load_lds_dwordx4 v[214:215], off
	v_lshl_add_u64 v[214:215], s[38:39], 0, v[150:151]
	s_add_i32 m0, s33, 0xe000
	s_nop 0
	global_load_lds_dwordx4 v[214:215], off
	s_waitcnt vmcnt(8)
	s_waitcnt lgkmcnt(0)
	s_barrier
	s_setprio 1
	s_waitcnt lgkmcnt(0)
	v_mfma_f32_16x16x32_bf16 v[124:127], v[128:131], v[182:185], v[124:127]
	v_mfma_f32_16x16x32_bf16 v[120:123], v[136:139], v[182:185], v[120:123]
	v_mfma_f32_16x16x32_bf16 v[108:111], v[128:131], v[190:193], v[108:111]
	v_mfma_f32_16x16x32_bf16 v[104:107], v[136:139], v[190:193], v[104:107]
	v_mfma_f32_16x16x32_bf16 v[92:95], v[128:131], v[198:201], v[92:95]
	v_mfma_f32_16x16x32_bf16 v[88:91], v[136:139], v[198:201], v[88:91]
	v_mfma_f32_16x16x32_bf16 v[76:79], v[128:131], v[206:209], v[76:79]
	v_mfma_f32_16x16x32_bf16 v[72:75], v[136:139], v[206:209], v[72:75]
	v_mfma_f32_16x16x32_bf16 v[124:127], v[132:135], v[186:189], v[124:127]
	v_mfma_f32_16x16x32_bf16 v[120:123], v[156:159], v[186:189], v[120:123]
	v_mfma_f32_16x16x32_bf16 v[108:111], v[132:135], v[194:197], v[108:111]
	v_mfma_f32_16x16x32_bf16 v[104:107], v[156:159], v[194:197], v[104:107]
	v_mfma_f32_16x16x32_bf16 v[92:95], v[132:135], v[202:205], v[92:95]
	v_mfma_f32_16x16x32_bf16 v[88:91], v[156:159], v[202:205], v[88:91]
	v_mfma_f32_16x16x32_bf16 v[76:79], v[132:135], v[210:213], v[76:79]
	v_mfma_f32_16x16x32_bf16 v[72:75], v[156:159], v[210:213], v[72:75]
	v_mfma_f32_16x16x32_bf16 v[116:119], v[160:163], v[182:185], v[116:119]
	v_mfma_f32_16x16x32_bf16 v[112:115], v[168:171], v[182:185], v[112:115]
	v_mfma_f32_16x16x32_bf16 v[100:103], v[160:163], v[190:193], v[100:103]
	v_mfma_f32_16x16x32_bf16 v[96:99], v[168:171], v[190:193], v[96:99]
	v_mfma_f32_16x16x32_bf16 v[84:87], v[160:163], v[198:201], v[84:87]
	v_mfma_f32_16x16x32_bf16 v[80:83], v[168:171], v[198:201], v[80:83]
	v_mfma_f32_16x16x32_bf16 v[68:71], v[160:163], v[206:209], v[68:71]
	v_mfma_f32_16x16x32_bf16 v[64:67], v[168:171], v[206:209], v[64:67]
	v_mfma_f32_16x16x32_bf16 v[116:119], v[164:167], v[186:189], v[116:119]
	v_mfma_f32_16x16x32_bf16 v[112:115], v[178:181], v[186:189], v[112:115]
	v_mfma_f32_16x16x32_bf16 v[100:103], v[164:167], v[194:197], v[100:103]
	v_mfma_f32_16x16x32_bf16 v[96:99], v[178:181], v[194:197], v[96:99]
	v_mfma_f32_16x16x32_bf16 v[84:87], v[164:167], v[202:205], v[84:87]
	v_mfma_f32_16x16x32_bf16 v[80:83], v[178:181], v[202:205], v[80:83]
	v_mfma_f32_16x16x32_bf16 v[68:71], v[164:167], v[210:213], v[68:71]
	v_mfma_f32_16x16x32_bf16 v[64:67], v[178:181], v[210:213], v[64:67]
	s_setprio 0
	s_barrier
	s_add_i32 s58, s50, s19
	v_lshl_add_u64 v[214:215], s[0:1], 0, v[142:143]
	s_mov_b32 m0, s58
	ds_read_b128 v[182:185], v177 offset:16384
	ds_read_b128 v[186:189], v177 offset:17408
	ds_read_b128 v[190:193], v177 offset:18432
	ds_read_b128 v[194:197], v177 offset:19456
	ds_read_b128 v[198:201], v177 offset:20480
	ds_read_b128 v[202:205], v177 offset:21504
	ds_read_b128 v[206:209], v177 offset:22528
	ds_read_b128 v[210:213], v177 offset:23552
	global_load_lds_dwordx4 v[214:215], off
	s_add_i32 m0, s58, 0x2000
	s_add_u32 s58, s0, 0x40000
	v_lshl_add_u64 v[216:217], s[0:1], 0, v[146:147]
	s_addc_u32 s59, s1, 0
	s_add_i32 s65, s51, s19
	global_load_lds_dwordx4 v[216:217], off
	v_lshl_add_u64 v[218:219], s[58:59], 0, v[142:143]
	s_mov_b32 m0, s65
	v_lshl_add_u64 v[220:221], s[24:25], 0, v[144:145]
	global_load_lds_dwordx4 v[218:219], off
	v_lshl_add_u64 v[218:219], s[58:59], 0, v[146:147]
	s_add_i32 m0, s65, 0x2000
	s_nop 0
	global_load_lds_dwordx4 v[218:219], off
	v_lshl_add_u64 v[218:219], s[24:25], 0, v[140:141]
	s_mov_b32 m0, s33
	s_nop 0
	global_load_lds_dwordx4 v[218:219], off
	s_mov_b32 m0, s35
	s_nop 0
	global_load_lds_dwordx4 v[220:221], off
	s_waitcnt vmcnt(8)
	s_waitcnt lgkmcnt(0)
	s_barrier
; #define PG8_STAGE(bufoff, gbase, voff) do { _Pragma("unroll") for (int _i = 0; _i < 2; ++_i) \
;         __builtin_amdgcn_global_load_lds((const unsigned*)((const char*)(gbase) + (voff)[_i]), (PG8_LAS unsigned*)(lds + (bufoff) + ldsw + _i * 8192), 16, 0, 0); } while (0)
; #define PG8_LDA(dst, b, h) do { _Pragma("unroll") for (int m = 0; m < 4; ++m) _Pragma("unroll") for (int k = 0; k < 2; ++k) dst[m][k] = *(const PG8_LAS bf16x8*)(lds + PG8_SA(b, h) + aoff + m * 2048 + k * 1024); } while (0)
; #define PG8_LDB(dst, b, h) do { _Pragma("unroll") for (int n = 0; n < 2; ++n) _Pragma("unroll") for (int k = 0; k < 2; ++k) dst[n][k] = *(const PG8_LAS bf16x8*)(lds + PG8_SB(b, h) + boff + n * 2048 + k * 1024); } while (0)
; #define PG8_MMA(ai, bj, At, Bt) do { __builtin_amdgcn_s_setprio(1); _Pragma("unroll") for (int m = 0; m < 4; ++m) _Pragma("unroll") for (int n = 0; n < 2; ++n) _Pragma("unroll") for (int k = 0; k < 2; ++k) \
;         acc[ai][bj][m][n] = __builtin_amdgcn_mfma_f32_16x16x32_bf16(Bt[n][k], At[m][k], acc[ai][bj][m][n], 0, 0, 0); __builtin_amdgcn_s_setprio(0); } while (0)
; #define PG8_WAIT_V(n) asm volatile("s_waitcnt vmcnt(" #n ")" ::: "memory")
; #define PG8_WAIT_L(n) asm volatile("s_waitcnt lgkmcnt(" #n ")" ::: "memory")
; #define PG8_BAR __builtin_amdgcn_s_barrier()
; #define PG8_SCHED __builtin_amdgcn_sched_barrier(0)
; template <class Epi, class Sched, bool ALIGN_EPI = false, bool SP2 = false>
; __device__ __forceinline__ void gemm_phase(PG8_LAS unsigned char* lds, const Gemm g, const Sched& S, const Epi& E) {
;     ...
;             PG8_WAIT_V(8); PG8_WAIT_L(0); PG8_BAR; PG8_MMA(1, 0, At, B0); PG8_MMA(1, 1, At, B1); PG8_BAR; PG8_SCHED;
;             PG8_LDB(B0, 1, 0); PG8_LDB(B1, 1, 1); PG8_SCHED; PG8_LDA(At, 1, 0); PG8_STAGE(PG8_SA(0, 1), a2 + hstep, voffA);
;             PG8_WAIT_V(8); PG8_WAIT_L(0); PG8_BAR; PG8_MMA(0, 0, At, B0); PG8_MMA(0, 1, At, B1); PG8_BAR; PG8_SCHED;
	s_setprio 1
	s_waitcnt lgkmcnt(0)
	v_mfma_f32_16x16x32_bf16 v[60:63], v[128:131], v[182:185], v[60:63]
	v_mfma_f32_16x16x32_bf16 v[56:59], v[136:139], v[182:185], v[56:59]
	v_mfma_f32_16x16x32_bf16 v[44:47], v[128:131], v[190:193], v[44:47]
	v_mfma_f32_16x16x32_bf16 v[40:43], v[136:139], v[190:193], v[40:43]
	v_mfma_f32_16x16x32_bf16 v[28:31], v[128:131], v[198:201], v[28:31]
	v_mfma_f32_16x16x32_bf16 v[24:27], v[136:139], v[198:201], v[24:27]
	v_mfma_f32_16x16x32_bf16 v[12:15], v[128:131], v[206:209], v[12:15]
	v_mfma_f32_16x16x32_bf16 v[8:11], v[136:139], v[206:209], v[8:11]
	v_mfma_f32_16x16x32_bf16 v[60:63], v[132:135], v[186:189], v[60:63]
	v_mfma_f32_16x16x32_bf16 v[56:59], v[156:159], v[186:189], v[56:59]
	v_mfma_f32_16x16x32_bf16 v[44:47], v[132:135], v[194:197], v[44:47]
	v_mfma_f32_16x16x32_bf16 v[40:43], v[156:159], v[194:197], v[40:43]
	v_mfma_f32_16x16x32_bf16 v[28:31], v[132:135], v[202:205], v[28:31]
	v_mfma_f32_16x16x32_bf16 v[24:27], v[156:159], v[202:205], v[24:27]
	v_mfma_f32_16x16x32_bf16 v[12:15], v[132:135], v[210:213], v[12:15]
	v_mfma_f32_16x16x32_bf16 v[8:11], v[156:159], v[210:213], v[8:11]
	v_mfma_f32_16x16x32_bf16 v[52:55], v[160:163], v[182:185], v[52:55]
	v_mfma_f32_16x16x32_bf16 v[48:51], v[168:171], v[182:185], v[48:51]
	v_mfma_f32_16x16x32_bf16 v[36:39], v[160:163], v[190:193], v[36:39]
	v_mfma_f32_16x16x32_bf16 v[32:35], v[168:171], v[190:193], v[32:35]
	v_mfma_f32_16x16x32_bf16 v[20:23], v[160:163], v[198:201], v[20:23]
	v_mfma_f32_16x16x32_bf16 v[16:19], v[168:171], v[198:201], v[16:19]
	v_mfma_f32_16x16x32_bf16 v[4:7], v[160:163], v[206:209], v[4:7]
	v_mfma_f32_16x16x32_bf16 v[0:3], v[168:171], v[206:209], v[0:3]
	v_mfma_f32_16x16x32_bf16 v[52:55], v[164:167], v[186:189], v[52:55]
	v_mfma_f32_16x16x32_bf16 v[48:51], v[178:181], v[186:189], v[48:51]
	v_mfma_f32_16x16x32_bf16 v[36:39], v[164:167], v[194:197], v[36:39]
	v_mfma_f32_16x16x32_bf16 v[32:35], v[178:181], v[194:197], v[32:35]
	v_mfma_f32_16x16x32_bf16 v[20:23], v[164:167], v[202:205], v[20:23]
	v_mfma_f32_16x16x32_bf16 v[16:19], v[178:181], v[202:205], v[16:19]
	v_mfma_f32_16x16x32_bf16 v[4:7], v[164:167], v[210:213], v[4:7]
	v_mfma_f32_16x16x32_bf16 v[0:3], v[178:181], v[210:213], v[0:3]
	s_setprio 0
	s_barrier
	s_add_i32 s58, 0, 0x18000
	s_add_i32 s59, 0, 0x1c000
	v_add_u32_e32 v156, s58, v173
	v_add_u32_e32 v178, s59, v173
	ds_read_b128 v[128:131], v156
	ds_read_b128 v[132:135], v156 offset:1024
	ds_read_b128 v[136:139], v156 offset:2048
	ds_read_b128 v[156:159], v156 offset:3072
	ds_read_b128 v[160:163], v178
	ds_read_b128 v[164:167], v178 offset:1024
	ds_read_b128 v[168:171], v178 offset:2048
	ds_read_b128 v[178:181], v178 offset:3072
	s_add_u32 s24, s24, 0x40000
	s_addc_u32 s25, s25, 0
	s_mov_b32 m0, s37
	v_lshl_add_u64 v[228:229], s[24:25], 0, v[140:141]
	ds_read_b128 v[182:185], v177 offset:32768
	ds_read_b128 v[186:189], v177 offset:33792
	ds_read_b128 v[190:193], v177 offset:34816
	ds_read_b128 v[194:197], v177 offset:35840
	ds_read_b128 v[198:201], v177 offset:36864
	ds_read_b128 v[202:205], v177 offset:37888
	ds_read_b128 v[206:209], v177 offset:38912
	ds_read_b128 v[210:213], v177 offset:39936
	global_load_lds_dwordx4 v[228:229], off
	v_lshl_add_u64 v[228:229], s[24:25], 0, v[144:145]
	s_mov_b32 m0, s40
	s_nop 0
	global_load_lds_dwordx4 v[228:229], off
	s_waitcnt vmcnt(8)
	s_waitcnt lgkmcnt(0)
	s_barrier
	s_setprio 1
	s_waitcnt lgkmcnt(0)
	v_mfma_f32_16x16x32_bf16 v[124:127], v[128:131], v[182:185], v[124:127]
	v_mfma_f32_16x16x32_bf16 v[120:123], v[136:139], v[182:185], v[120:123]
	v_mfma_f32_16x16x32_bf16 v[108:111], v[128:131], v[190:193], v[108:111]
	v_mfma_f32_16x16x32_bf16 v[104:107], v[136:139], v[190:193], v[104:107]
	v_mfma_f32_16x16x32_bf16 v[92:95], v[128:131], v[198:201], v[92:95]
	v_mfma_f32_16x16x32_bf16 v[88:91], v[136:139], v[198:201], v[88:91]
	v_mfma_f32_16x16x32_bf16 v[76:79], v[128:131], v[206:209], v[76:79]
	v_mfma_f32_16x16x32_bf16 v[72:75], v[136:139], v[206:209], v[72:75]
	v_mfma_f32_16x16x32_bf16 v[124:127], v[132:135], v[186:189], v[124:127]
	v_mfma_f32_16x16x32_bf16 v[120:123], v[156:159], v[186:189], v[120:123]
	v_mfma_f32_16x16x32_bf16 v[108:111], v[132:135], v[194:197], v[108:111]
	v_mfma_f32_16x16x32_bf16 v[104:107], v[156:159], v[194:197], v[104:107]
	v_mfma_f32_16x16x32_bf16 v[92:95], v[132:135], v[202:205], v[92:95]
	v_mfma_f32_16x16x32_bf16 v[88:91], v[156:159], v[202:205], v[88:91]
	v_mfma_f32_16x16x32_bf16 v[76:79], v[132:135], v[210:213], v[76:79]
	v_mfma_f32_16x16x32_bf16 v[72:75], v[156:159], v[210:213], v[72:75]
	v_mfma_f32_16x16x32_bf16 v[116:119], v[160:163], v[182:185], v[116:119]
	v_mfma_f32_16x16x32_bf16 v[112:115], v[168:171], v[182:185], v[112:115]
	v_mfma_f32_16x16x32_bf16 v[100:103], v[160:163], v[190:193], v[100:103]
	v_mfma_f32_16x16x32_bf16 v[96:99], v[168:171], v[190:193], v[96:99]
	v_mfma_f32_16x16x32_bf16 v[84:87], v[160:163], v[198:201], v[84:87]
	v_mfma_f32_16x16x32_bf16 v[80:83], v[168:171], v[198:201], v[80:83]
	v_mfma_f32_16x16x32_bf16 v[68:71], v[160:163], v[206:209], v[68:71]
	v_mfma_f32_16x16x32_bf16 v[64:67], v[168:171], v[206:209], v[64:67]
	v_mfma_f32_16x16x32_bf16 v[116:119], v[164:167], v[186:189], v[116:119]
	v_mfma_f32_16x16x32_bf16 v[112:115], v[178:181], v[186:189], v[112:115]
	v_mfma_f32_16x16x32_bf16 v[100:103], v[164:167], v[194:197], v[100:103]
	v_mfma_f32_16x16x32_bf16 v[96:99], v[178:181], v[194:197], v[96:99]
	v_mfma_f32_16x16x32_bf16 v[84:87], v[164:167], v[202:205], v[84:87]
	v_mfma_f32_16x16x32_bf16 v[80:83], v[178:181], v[202:205], v[80:83]
	v_mfma_f32_16x16x32_bf16 v[68:71], v[164:167], v[210:213], v[68:71]
	v_mfma_f32_16x16x32_bf16 v[64:67], v[178:181], v[210:213], v[64:67]
	s_setprio 0
	s_barrier
; #define PG8_STAGE(bufoff, gbase, voff) do { _Pragma("unroll") for (int _i = 0; _i < 2; ++_i) \
;         __builtin_amdgcn_global_load_lds((const unsigned*)((const char*)(gbase) + (voff)[_i]), (PG8_LAS unsigned*)(lds + (bufoff) + ldsw + _i * 8192), 16, 0, 0); } while (0)
; #define PG8_LDA(dst, b, h) do { _Pragma("unroll") for (int m = 0; m < 4; ++m) _Pragma("unroll") for (int k = 0; k < 2; ++k) dst[m][k] = *(const PG8_LAS bf16x8*)(lds + PG8_SA(b, h) + aoff + m * 2048 + k * 1024); } while (0)
; #define PG8_MMA(ai, bj, At, Bt) do { __builtin_amdgcn_s_setprio(1); _Pragma("unroll") for (int m = 0; m < 4; ++m) _Pragma("unroll") for (int n = 0; n < 2; ++n) _Pragma("unroll") for (int k = 0; k < 2; ++k) \
;         acc[ai][bj][m][n] = __builtin_amdgcn_mfma_f32_16x16x32_bf16(Bt[n][k], At[m][k], acc[ai][bj][m][n], 0, 0, 0); __builtin_amdgcn_s_setprio(0); } while (0)
; #define PG8_WAIT_V(n) asm volatile("s_waitcnt vmcnt(" #n ")" ::: "memory")
; #define PG8_WAIT_L(n) asm volatile("s_waitcnt lgkmcnt(" #n ")" ::: "memory")
; #define PG8_BAR __builtin_amdgcn_s_barrier()
; #define PG8_SCHED __builtin_amdgcn_sched_barrier(0)
; template <class Epi, class Sched, bool ALIGN_EPI = false, bool SP2 = false>
; __device__ __forceinline__ void gemm_phase(PG8_LAS unsigned char* lds, const Gemm g, const Sched& S, const Epi& E) {
;     ...
;             PG8_LDA(At, 1, 1); PG8_STAGE(PG8_SB(1, 0), b3, voffB); PG8_STAGE(PG8_SB(1, 1), b3 + hstep, voffB); PG8_STAGE(PG8_SA(1, 0), a3, voffA);
;             PG8_WAIT_V(8); PG8_WAIT_L(0); PG8_BAR; PG8_MMA(1, 0, At, B0); PG8_MMA(1, 1, At, B1); PG8_BAR; PG8_SCHED;
;     ...
;         if constexpr (ALIGN_EPI) { if (wr == 0) PG8_BAR; }
	s_add_i32 s24, s58, s19
	v_lshl_add_u64 v[214:215], v[214:215], 0, s[14:15]
	s_mov_b32 m0, s24
	ds_read_b128 v[182:185], v177 offset:49152
	ds_read_b128 v[186:189], v177 offset:50176
	ds_read_b128 v[190:193], v177 offset:51200
	ds_read_b128 v[194:197], v177 offset:52224
	ds_read_b128 v[198:201], v177 offset:53248
	ds_read_b128 v[202:205], v177 offset:54272
	ds_read_b128 v[206:209], v177 offset:55296
	ds_read_b128 v[210:213], v177 offset:56320
	global_load_lds_dwordx4 v[214:215], off
	s_add_i32 m0, s24, 0x2000
	s_add_u32 s0, s0, 0x40080
	v_lshl_add_u64 v[214:215], v[216:217], 0, s[14:15]
	s_addc_u32 s1, s1, 0
	s_add_i32 s24, s59, s19
	global_load_lds_dwordx4 v[214:215], off
	v_lshl_add_u64 v[214:215], s[0:1], 0, v[142:143]
	s_mov_b32 m0, s24
	s_nop 0
	global_load_lds_dwordx4 v[214:215], off
	v_lshl_add_u64 v[214:215], s[0:1], 0, v[146:147]
	s_add_i32 m0, s24, 0x2000
	s_nop 0
	global_load_lds_dwordx4 v[214:215], off
	v_lshl_add_u64 v[214:215], v[218:219], 0, s[14:15]
	s_mov_b32 m0, s42
	s_nop 0
	global_load_lds_dwordx4 v[214:215], off
	v_lshl_add_u64 v[214:215], v[220:221], 0, s[14:15]
	s_mov_b32 m0, s43
	s_nop 0
	global_load_lds_dwordx4 v[214:215], off
	s_waitcnt vmcnt(8)
	s_waitcnt lgkmcnt(0)
	s_barrier
	s_setprio 1
	s_waitcnt lgkmcnt(0)
	v_mfma_f32_16x16x32_bf16 v[60:63], v[128:131], v[182:185], v[60:63]
	v_mfma_f32_16x16x32_bf16 v[56:59], v[136:139], v[182:185], v[56:59]
	v_mfma_f32_16x16x32_bf16 v[44:47], v[128:131], v[190:193], v[44:47]
	v_mfma_f32_16x16x32_bf16 v[40:43], v[136:139], v[190:193], v[40:43]
	v_mfma_f32_16x16x32_bf16 v[28:31], v[128:131], v[198:201], v[28:31]
	v_mfma_f32_16x16x32_bf16 v[24:27], v[136:139], v[198:201], v[24:27]
	v_mfma_f32_16x16x32_bf16 v[12:15], v[128:131], v[206:209], v[12:15]
	v_mfma_f32_16x16x32_bf16 v[8:11], v[136:139], v[206:209], v[8:11]
	v_mfma_f32_16x16x32_bf16 v[60:63], v[132:135], v[186:189], v[60:63]
	v_mfma_f32_16x16x32_bf16 v[56:59], v[156:159], v[186:189], v[56:59]
	v_mfma_f32_16x16x32_bf16 v[44:47], v[132:135], v[194:197], v[44:47]
	v_mfma_f32_16x16x32_bf16 v[40:43], v[156:159], v[194:197], v[40:43]
	v_mfma_f32_16x16x32_bf16 v[28:31], v[132:135], v[202:205], v[28:31]
	v_mfma_f32_16x16x32_bf16 v[24:27], v[156:159], v[202:205], v[24:27]
	v_mfma_f32_16x16x32_bf16 v[12:15], v[132:135], v[210:213], v[12:15]
	v_mfma_f32_16x16x32_bf16 v[8:11], v[156:159], v[210:213], v[8:11]
	v_mfma_f32_16x16x32_bf16 v[52:55], v[160:163], v[182:185], v[52:55]
	v_mfma_f32_16x16x32_bf16 v[48:51], v[168:171], v[182:185], v[48:51]
	v_mfma_f32_16x16x32_bf16 v[36:39], v[160:163], v[190:193], v[36:39]
	v_mfma_f32_16x16x32_bf16 v[32:35], v[168:171], v[190:193], v[32:35]
	v_mfma_f32_16x16x32_bf16 v[20:23], v[160:163], v[198:201], v[20:23]
	v_mfma_f32_16x16x32_bf16 v[16:19], v[168:171], v[198:201], v[16:19]
	v_mfma_f32_16x16x32_bf16 v[4:7], v[160:163], v[206:209], v[4:7]
	v_mfma_f32_16x16x32_bf16 v[0:3], v[168:171], v[206:209], v[0:3]
	v_mfma_f32_16x16x32_bf16 v[52:55], v[164:167], v[186:189], v[52:55]
	v_mfma_f32_16x16x32_bf16 v[48:51], v[178:181], v[186:189], v[48:51]
	v_mfma_f32_16x16x32_bf16 v[36:39], v[164:167], v[194:197], v[36:39]
	v_mfma_f32_16x16x32_bf16 v[32:35], v[178:181], v[194:197], v[32:35]
	v_mfma_f32_16x16x32_bf16 v[20:23], v[164:167], v[202:205], v[20:23]
	v_mfma_f32_16x16x32_bf16 v[16:19], v[178:181], v[202:205], v[16:19]
	v_mfma_f32_16x16x32_bf16 v[4:7], v[164:167], v[210:213], v[4:7]
	v_mfma_f32_16x16x32_bf16 v[0:3], v[178:181], v[210:213], v[0:3]
	s_setprio 0
	s_barrier
	s_add_i32 s57, s57, 2
	s_add_u32 s38, s38, 0x100
	s_addc_u32 s39, s39, 0
	s_add_u32 s55, s55, 0x100
	s_addc_u32 s56, s56, 0
	s_cmp_gt_u32 s57, 13
	s_cbranch_scc0 .LBB0_1702
	s_and_b64 vcc, exec, s[16:17]
	s_cbranch_vccz .LBB0_1705
	s_barrier

; #define PG8_STAGE(bufoff, gbase, voff) do { _Pragma("unroll") for (int _i = 0; _i < 2; ++_i) \
;         __builtin_amdgcn_global_load_lds((const unsigned*)((const char*)(gbase) + (voff)[_i]), (PG8_LAS unsigned*)(lds + (bufoff) + ldsw + _i * 8192), 16, 0, 0); } while (0)
; #define PG8_LDA(dst, b, h) do { _Pragma("unroll") for (int m = 0; m < 4; ++m) _Pragma("unroll") for (int k = 0; k < 2; ++k) dst[m][k] = *(const PG8_LAS bf16x8*)(lds + PG8_SA(b, h) + aoff + m * 2048 + k * 1024); } while (0)
; #define PG8_LDB(dst, b, h) do { _Pragma("unroll") for (int n = 0; n < 2; ++n) _Pragma("unroll") for (int k = 0; k < 2; ++k) dst[n][k] = *(const PG8_LAS bf16x8*)(lds + PG8_SB(b, h) + boff + n * 2048 + k * 1024); } while (0)
; #define PG8_MMA(ai, bj, At, Bt) do { __builtin_amdgcn_s_setprio(1); _Pragma("unroll") for (int m = 0; m < 4; ++m) _Pragma("unroll") for (int n = 0; n < 2; ++n) _Pragma("unroll") for (int k = 0; k < 2; ++k) \
;         acc[ai][bj][m][n] = __builtin_amdgcn_mfma_f32_16x16x32_bf16(Bt[n][k], At[m][k], acc[ai][bj][m][n], 0, 0, 0); __builtin_amdgcn_s_setprio(0); } while (0)
; #define PG8_WAIT_V(n) asm volatile("s_waitcnt vmcnt(" #n ")" ::: "memory")
; #define PG8_WAIT_L(n) asm volatile("s_waitcnt lgkmcnt(" #n ")" ::: "memory")
; #define PG8_BAR __builtin_amdgcn_s_barrier()
; #define PG8_SCHED __builtin_amdgcn_sched_barrier(0)
; template <class Epi, class Sched, bool ALIGN_EPI = false, bool SP2 = false>
; __device__ __forceinline__ void gemm_phase(PG8_LAS unsigned char* lds, const Gemm g, const Sched& S, const Epi& E) {
;     ...
;             PG8_LDB(B0, 0, 0); PG8_LDB(B1, 0, 1); PG8_SCHED; PG8_LDA(At, 0, 0); PG8_STAGE(PG8_SA(1, 1), a1 + hstep, voffA);
;             PG8_WAIT_V(8); PG8_WAIT_L(0); PG8_BAR; PG8_MMA(0, 0, At, B0); PG8_MMA(0, 1, At, B1); PG8_BAR; PG8_SCHED;
;             PG8_LDA(At, 0, 1); PG8_STAGE(PG8_SB(0, 0), b2, voffB); PG8_STAGE(PG8_SB(0, 1), b2 + hstep, voffB); PG8_STAGE(PG8_SA(0, 0), a2, voffA);
.LBB0_1798:
	ds_read_b128 v[128:131], v209
	ds_read_b128 v[132:135], v209 offset:1024
	ds_read_b128 v[136:139], v209 offset:2048
	ds_read_b128 v[140:143], v209 offset:3072
	ds_read_b128 v[144:147], v210
	ds_read_b128 v[148:151], v210 offset:1024
	ds_read_b128 v[152:155], v210 offset:2048
	ds_read_b128 v[156:159], v210 offset:3072
	s_add_u32 s0, s40, 0xfff80080
	s_addc_u32 s1, s41, -1
	s_cmp_eq_u32 s56, 28
	s_cselect_b32 s25, s23, s1
	s_cselect_b32 s24, s52, s0
	s_cselect_b32 s1, s21, s55
	s_cselect_b32 s0, s53, s54
	v_lshl_add_u64 v[204:205], s[40:41], 0, v[180:181]
	s_add_i32 m0, s33, 0xc000
	ds_read_b128 v[160:163], v211
	ds_read_b128 v[164:167], v211 offset:1024
	ds_read_b128 v[168:171], v211 offset:2048
	ds_read_b128 v[172:175], v211 offset:3072
	ds_read_b128 v[188:191], v211 offset:4096
	ds_read_b128 v[192:195], v211 offset:5120
	ds_read_b128 v[196:199], v211 offset:6144
	ds_read_b128 v[200:203], v211 offset:7168
	global_load_lds_dwordx4 v[204:205], off
	v_lshl_add_u64 v[204:205], s[40:41], 0, v[182:183]
	s_add_i32 m0, s33, 0xe000
	s_nop 0
	global_load_lds_dwordx4 v[204:205], off
	s_waitcnt vmcnt(8)
	s_waitcnt lgkmcnt(0)
	s_barrier
	s_setprio 1
	s_waitcnt lgkmcnt(0)
	v_mfma_f32_16x16x32_bf16 v[124:127], v[128:131], v[160:163], v[124:127]
	v_mfma_f32_16x16x32_bf16 v[120:123], v[136:139], v[160:163], v[120:123]
	v_mfma_f32_16x16x32_bf16 v[108:111], v[128:131], v[168:171], v[108:111]
	v_mfma_f32_16x16x32_bf16 v[104:107], v[136:139], v[168:171], v[104:107]
	v_mfma_f32_16x16x32_bf16 v[92:95], v[128:131], v[188:191], v[92:95]
	v_mfma_f32_16x16x32_bf16 v[88:91], v[136:139], v[188:191], v[88:91]
	v_mfma_f32_16x16x32_bf16 v[76:79], v[128:131], v[196:199], v[76:79]
	v_mfma_f32_16x16x32_bf16 v[72:75], v[136:139], v[196:199], v[72:75]
	v_mfma_f32_16x16x32_bf16 v[124:127], v[132:135], v[164:167], v[124:127]
	v_mfma_f32_16x16x32_bf16 v[120:123], v[140:143], v[164:167], v[120:123]
	v_mfma_f32_16x16x32_bf16 v[108:111], v[132:135], v[172:175], v[108:111]
	v_mfma_f32_16x16x32_bf16 v[104:107], v[140:143], v[172:175], v[104:107]
	v_mfma_f32_16x16x32_bf16 v[92:95], v[132:135], v[192:195], v[92:95]
	v_mfma_f32_16x16x32_bf16 v[88:91], v[140:143], v[192:195], v[88:91]
	v_mfma_f32_16x16x32_bf16 v[76:79], v[132:135], v[200:203], v[76:79]
	v_mfma_f32_16x16x32_bf16 v[72:75], v[140:143], v[200:203], v[72:75]
	v_mfma_f32_16x16x32_bf16 v[116:119], v[144:147], v[160:163], v[116:119]
	v_mfma_f32_16x16x32_bf16 v[112:115], v[152:155], v[160:163], v[112:115]
	v_mfma_f32_16x16x32_bf16 v[100:103], v[144:147], v[168:171], v[100:103]
	v_mfma_f32_16x16x32_bf16 v[96:99], v[152:155], v[168:171], v[96:99]
	v_mfma_f32_16x16x32_bf16 v[84:87], v[144:147], v[188:191], v[84:87]
	v_mfma_f32_16x16x32_bf16 v[80:83], v[152:155], v[188:191], v[80:83]
	v_mfma_f32_16x16x32_bf16 v[68:71], v[144:147], v[196:199], v[68:71]
	v_mfma_f32_16x16x32_bf16 v[64:67], v[152:155], v[196:199], v[64:67]
	v_mfma_f32_16x16x32_bf16 v[116:119], v[148:151], v[164:167], v[116:119]
	v_mfma_f32_16x16x32_bf16 v[112:115], v[156:159], v[164:167], v[112:115]
	v_mfma_f32_16x16x32_bf16 v[100:103], v[148:151], v[172:175], v[100:103]
	v_mfma_f32_16x16x32_bf16 v[96:99], v[156:159], v[172:175], v[96:99]
	v_mfma_f32_16x16x32_bf16 v[84:87], v[148:151], v[192:195], v[84:87]
	v_mfma_f32_16x16x32_bf16 v[80:83], v[156:159], v[192:195], v[80:83]
	v_mfma_f32_16x16x32_bf16 v[68:71], v[148:151], v[200:203], v[68:71]
	v_mfma_f32_16x16x32_bf16 v[64:67], v[156:159], v[200:203], v[64:67]
	s_setprio 0
	s_barrier
	s_add_i32 s57, s50, s3
	v_lshl_add_u64 v[204:205], s[0:1], 0, v[176:177]
	s_mov_b32 m0, s57
	ds_read_b128 v[160:163], v211 offset:16384
	ds_read_b128 v[164:167], v211 offset:17408
	ds_read_b128 v[168:171], v211 offset:18432
	ds_read_b128 v[172:175], v211 offset:19456
	ds_read_b128 v[188:191], v211 offset:20480
	ds_read_b128 v[192:195], v211 offset:21504
	ds_read_b128 v[196:199], v211 offset:22528
	ds_read_b128 v[200:203], v211 offset:23552
	global_load_lds_dwordx4 v[204:205], off
	s_add_i32 m0, s57, 0x2000
	s_add_u32 s58, s0, 0x80000
	v_lshl_add_u64 v[212:213], s[0:1], 0, v[178:179]
	s_addc_u32 s59, s1, 0
	s_add_i32 s57, s51, s3
	global_load_lds_dwordx4 v[212:213], off
	v_lshl_add_u64 v[214:215], s[58:59], 0, v[176:177]
	s_mov_b32 m0, s57
	v_lshl_add_u64 v[216:217], s[24:25], 0, v[178:179]
	global_load_lds_dwordx4 v[214:215], off
	v_lshl_add_u64 v[214:215], s[58:59], 0, v[178:179]
	s_add_i32 m0, s57, 0x2000
	s_nop 0
	global_load_lds_dwordx4 v[214:215], off
	v_lshl_add_u64 v[214:215], s[24:25], 0, v[176:177]
	s_mov_b32 m0, s33
	s_nop 0
	global_load_lds_dwordx4 v[214:215], off
	s_mov_b32 m0, s35
	s_nop 0
	global_load_lds_dwordx4 v[216:217], off
	s_waitcnt vmcnt(8)
	s_waitcnt lgkmcnt(0)
	s_barrier
; #define PG8_STAGE(bufoff, gbase, voff) do { _Pragma("unroll") for (int _i = 0; _i < 2; ++_i) \
;         __builtin_amdgcn_global_load_lds((const unsigned*)((const char*)(gbase) + (voff)[_i]), (PG8_LAS unsigned*)(lds + (bufoff) + ldsw + _i * 8192), 16, 0, 0); } while (0)
; #define PG8_LDA(dst, b, h) do { _Pragma("unroll") for (int m = 0; m < 4; ++m) _Pragma("unroll") for (int k = 0; k < 2; ++k) dst[m][k] = *(const PG8_LAS bf16x8*)(lds + PG8_SA(b, h) + aoff + m * 2048 + k * 1024); } while (0)
; #define PG8_LDB(dst, b, h) do { _Pragma("unroll") for (int n = 0; n < 2; ++n) _Pragma("unroll") for (int k = 0; k < 2; ++k) dst[n][k] = *(const PG8_LAS bf16x8*)(lds + PG8_SB(b, h) + boff + n * 2048 + k * 1024); } while (0)
; #define PG8_MMA(ai, bj, At, Bt) do { __builtin_amdgcn_s_setprio(1); _Pragma("unroll") for (int m = 0; m < 4; ++m) _Pragma("unroll") for (int n = 0; n < 2; ++n) _Pragma("unroll") for (int k = 0; k < 2; ++k) \
;         acc[ai][bj][m][n] = __builtin_amdgcn_mfma_f32_16x16x32_bf16(Bt[n][k], At[m][k], acc[ai][bj][m][n], 0, 0, 0); __builtin_amdgcn_s_setprio(0); } while (0)
; #define PG8_WAIT_V(n) asm volatile("s_waitcnt vmcnt(" #n ")" ::: "memory")
; #define PG8_WAIT_L(n) asm volatile("s_waitcnt lgkmcnt(" #n ")" ::: "memory")
; #define PG8_BAR __builtin_amdgcn_s_barrier()
; #define PG8_SCHED __builtin_amdgcn_sched_barrier(0)
; template <class Epi, class Sched, bool ALIGN_EPI = false, bool SP2 = false>
; __device__ __forceinline__ void gemm_phase(PG8_LAS unsigned char* lds, const Gemm g, const Sched& S, const Epi& E) {
;     ...
;             PG8_WAIT_V(8); PG8_WAIT_L(0); PG8_BAR; PG8_MMA(1, 0, At, B0); PG8_MMA(1, 1, At, B1); PG8_BAR; PG8_SCHED;
;             PG8_LDB(B0, 1, 0); PG8_LDB(B1, 1, 1); PG8_SCHED; PG8_LDA(At, 1, 0); PG8_STAGE(PG8_SA(0, 1), a2 + hstep, voffA);
;             PG8_WAIT_V(8); PG8_WAIT_L(0); PG8_BAR; PG8_MMA(0, 0, At, B0); PG8_MMA(0, 1, At, B1); PG8_BAR; PG8_SCHED;
	s_setprio 1
	s_waitcnt lgkmcnt(0)
	v_mfma_f32_16x16x32_bf16 v[60:63], v[128:131], v[160:163], v[60:63]
	v_mfma_f32_16x16x32_bf16 v[56:59], v[136:139], v[160:163], v[56:59]
	v_mfma_f32_16x16x32_bf16 v[44:47], v[128:131], v[168:171], v[44:47]
	v_mfma_f32_16x16x32_bf16 v[40:43], v[136:139], v[168:171], v[40:43]
	v_mfma_f32_16x16x32_bf16 v[28:31], v[128:131], v[188:191], v[28:31]
	v_mfma_f32_16x16x32_bf16 v[24:27], v[136:139], v[188:191], v[24:27]
	v_mfma_f32_16x16x32_bf16 v[12:15], v[128:131], v[196:199], v[12:15]
	v_mfma_f32_16x16x32_bf16 v[8:11], v[136:139], v[196:199], v[8:11]
	v_mfma_f32_16x16x32_bf16 v[60:63], v[132:135], v[164:167], v[60:63]
	v_mfma_f32_16x16x32_bf16 v[56:59], v[140:143], v[164:167], v[56:59]
	v_mfma_f32_16x16x32_bf16 v[44:47], v[132:135], v[172:175], v[44:47]
	v_mfma_f32_16x16x32_bf16 v[40:43], v[140:143], v[172:175], v[40:43]
	v_mfma_f32_16x16x32_bf16 v[28:31], v[132:135], v[192:195], v[28:31]
	v_mfma_f32_16x16x32_bf16 v[24:27], v[140:143], v[192:195], v[24:27]
	v_mfma_f32_16x16x32_bf16 v[12:15], v[132:135], v[200:203], v[12:15]
	v_mfma_f32_16x16x32_bf16 v[8:11], v[140:143], v[200:203], v[8:11]
	v_mfma_f32_16x16x32_bf16 v[52:55], v[144:147], v[160:163], v[52:55]
	v_mfma_f32_16x16x32_bf16 v[48:51], v[152:155], v[160:163], v[48:51]
	v_mfma_f32_16x16x32_bf16 v[36:39], v[144:147], v[168:171], v[36:39]
	v_mfma_f32_16x16x32_bf16 v[32:35], v[152:155], v[168:171], v[32:35]
	v_mfma_f32_16x16x32_bf16 v[20:23], v[144:147], v[188:191], v[20:23]
	v_mfma_f32_16x16x32_bf16 v[16:19], v[152:155], v[188:191], v[16:19]
	v_mfma_f32_16x16x32_bf16 v[4:7], v[144:147], v[196:199], v[4:7]
	v_mfma_f32_16x16x32_bf16 v[0:3], v[152:155], v[196:199], v[0:3]
	v_mfma_f32_16x16x32_bf16 v[52:55], v[148:151], v[164:167], v[52:55]
	v_mfma_f32_16x16x32_bf16 v[48:51], v[156:159], v[164:167], v[48:51]
	v_mfma_f32_16x16x32_bf16 v[36:39], v[148:151], v[172:175], v[36:39]
	v_mfma_f32_16x16x32_bf16 v[32:35], v[156:159], v[172:175], v[32:35]
	v_mfma_f32_16x16x32_bf16 v[20:23], v[148:151], v[192:195], v[20:23]
	v_mfma_f32_16x16x32_bf16 v[16:19], v[156:159], v[192:195], v[16:19]
	v_mfma_f32_16x16x32_bf16 v[4:7], v[148:151], v[200:203], v[4:7]
	v_mfma_f32_16x16x32_bf16 v[0:3], v[156:159], v[200:203], v[0:3]
	s_setprio 0
	s_barrier
	s_add_i32 s57, 0, 0x18000
	s_add_i32 s58, 0, 0x1c000
	v_add_u32_e32 v140, s57, v207
	v_add_u32_e32 v156, s58, v207
	ds_read_b128 v[128:131], v140
	ds_read_b128 v[132:135], v140 offset:1024
	ds_read_b128 v[136:139], v140 offset:2048
	ds_read_b128 v[140:143], v140 offset:3072
	ds_read_b128 v[144:147], v156
	ds_read_b128 v[148:151], v156 offset:1024
	ds_read_b128 v[152:155], v156 offset:2048
	ds_read_b128 v[156:159], v156 offset:3072
	s_add_u32 s24, s24, 0x80000
	s_addc_u32 s25, s25, 0
	s_mov_b32 m0, s37
	v_lshl_add_u64 v[218:219], s[24:25], 0, v[176:177]
	ds_read_b128 v[160:163], v211 offset:32768
	ds_read_b128 v[164:167], v211 offset:33792
	ds_read_b128 v[168:171], v211 offset:34816
	ds_read_b128 v[172:175], v211 offset:35840
	ds_read_b128 v[188:191], v211 offset:36864
	ds_read_b128 v[192:195], v211 offset:37888
	ds_read_b128 v[196:199], v211 offset:38912
	ds_read_b128 v[200:203], v211 offset:39936
	global_load_lds_dwordx4 v[218:219], off
	v_lshl_add_u64 v[218:219], s[24:25], 0, v[178:179]
	s_mov_b32 m0, s39
	s_nop 0
	global_load_lds_dwordx4 v[218:219], off
	s_waitcnt vmcnt(8)
	s_waitcnt lgkmcnt(0)
	s_barrier
	s_setprio 1
	s_waitcnt lgkmcnt(0)
	v_mfma_f32_16x16x32_bf16 v[124:127], v[128:131], v[160:163], v[124:127]
	v_mfma_f32_16x16x32_bf16 v[120:123], v[136:139], v[160:163], v[120:123]
	v_mfma_f32_16x16x32_bf16 v[108:111], v[128:131], v[168:171], v[108:111]
	v_mfma_f32_16x16x32_bf16 v[104:107], v[136:139], v[168:171], v[104:107]
	v_mfma_f32_16x16x32_bf16 v[92:95], v[128:131], v[188:191], v[92:95]
	v_mfma_f32_16x16x32_bf16 v[88:91], v[136:139], v[188:191], v[88:91]
	v_mfma_f32_16x16x32_bf16 v[76:79], v[128:131], v[196:199], v[76:79]
	v_mfma_f32_16x16x32_bf16 v[72:75], v[136:139], v[196:199], v[72:75]
	v_mfma_f32_16x16x32_bf16 v[124:127], v[132:135], v[164:167], v[124:127]
	v_mfma_f32_16x16x32_bf16 v[120:123], v[140:143], v[164:167], v[120:123]
	v_mfma_f32_16x16x32_bf16 v[108:111], v[132:135], v[172:175], v[108:111]
	v_mfma_f32_16x16x32_bf16 v[104:107], v[140:143], v[172:175], v[104:107]
	v_mfma_f32_16x16x32_bf16 v[92:95], v[132:135], v[192:195], v[92:95]
	v_mfma_f32_16x16x32_bf16 v[88:91], v[140:143], v[192:195], v[88:91]
	v_mfma_f32_16x16x32_bf16 v[76:79], v[132:135], v[200:203], v[76:79]
	v_mfma_f32_16x16x32_bf16 v[72:75], v[140:143], v[200:203], v[72:75]
	v_mfma_f32_16x16x32_bf16 v[116:119], v[144:147], v[160:163], v[116:119]
	v_mfma_f32_16x16x32_bf16 v[112:115], v[152:155], v[160:163], v[112:115]
	v_mfma_f32_16x16x32_bf16 v[100:103], v[144:147], v[168:171], v[100:103]
	v_mfma_f32_16x16x32_bf16 v[96:99], v[152:155], v[168:171], v[96:99]
	v_mfma_f32_16x16x32_bf16 v[84:87], v[144:147], v[188:191], v[84:87]
	v_mfma_f32_16x16x32_bf16 v[80:83], v[152:155], v[188:191], v[80:83]
	v_mfma_f32_16x16x32_bf16 v[68:71], v[144:147], v[196:199], v[68:71]
	v_mfma_f32_16x16x32_bf16 v[64:67], v[152:155], v[196:199], v[64:67]
	v_mfma_f32_16x16x32_bf16 v[116:119], v[148:151], v[164:167], v[116:119]
	v_mfma_f32_16x16x32_bf16 v[112:115], v[156:159], v[164:167], v[112:115]
	v_mfma_f32_16x16x32_bf16 v[100:103], v[148:151], v[172:175], v[100:103]
	v_mfma_f32_16x16x32_bf16 v[96:99], v[156:159], v[172:175], v[96:99]
	v_mfma_f32_16x16x32_bf16 v[84:87], v[148:151], v[192:195], v[84:87]
	v_mfma_f32_16x16x32_bf16 v[80:83], v[156:159], v[192:195], v[80:83]
	v_mfma_f32_16x16x32_bf16 v[68:71], v[148:151], v[200:203], v[68:71]
	v_mfma_f32_16x16x32_bf16 v[64:67], v[156:159], v[200:203], v[64:67]
	s_setprio 0
	s_barrier
; #define PG8_STAGE(bufoff, gbase, voff) do { _Pragma("unroll") for (int _i = 0; _i < 2; ++_i) \
;         __builtin_amdgcn_global_load_lds((const unsigned*)((const char*)(gbase) + (voff)[_i]), (PG8_LAS unsigned*)(lds + (bufoff) + ldsw + _i * 8192), 16, 0, 0); } while (0)
; #define PG8_LDA(dst, b, h) do { _Pragma("unroll") for (int m = 0; m < 4; ++m) _Pragma("unroll") for (int k = 0; k < 2; ++k) dst[m][k] = *(const PG8_LAS bf16x8*)(lds + PG8_SA(b, h) + aoff + m * 2048 + k * 1024); } while (0)
; #define PG8_MMA(ai, bj, At, Bt) do { __builtin_amdgcn_s_setprio(1); _Pragma("unroll") for (int m = 0; m < 4; ++m) _Pragma("unroll") for (int n = 0; n < 2; ++n) _Pragma("unroll") for (int k = 0; k < 2; ++k) \
;         acc[ai][bj][m][n] = __builtin_amdgcn_mfma_f32_16x16x32_bf16(Bt[n][k], At[m][k], acc[ai][bj][m][n], 0, 0, 0); __builtin_amdgcn_s_setprio(0); } while (0)
; #define PG8_WAIT_V(n) asm volatile("s_waitcnt vmcnt(" #n ")" ::: "memory")
; #define PG8_WAIT_L(n) asm volatile("s_waitcnt lgkmcnt(" #n ")" ::: "memory")
; #define PG8_BAR __builtin_amdgcn_s_barrier()
; #define PG8_SCHED __builtin_amdgcn_sched_barrier(0)
; template <class Epi, class Sched, bool ALIGN_EPI = false, bool SP2 = false>
; __device__ __forceinline__ void gemm_phase(PG8_LAS unsigned char* lds, const Gemm g, const Sched& S, const Epi& E) {
;     ...
;             PG8_LDA(At, 1, 1); PG8_STAGE(PG8_SB(1, 0), b3, voffB); PG8_STAGE(PG8_SB(1, 1), b3 + hstep, voffB); PG8_STAGE(PG8_SA(1, 0), a3, voffA);
;             PG8_WAIT_V(8); PG8_WAIT_L(0); PG8_BAR; PG8_MMA(1, 0, At, B0); PG8_MMA(1, 1, At, B1); PG8_BAR; PG8_SCHED;
;     ...
;         if constexpr (ALIGN_EPI) { if (wr == 0) PG8_BAR; }
	s_add_i32 s24, s57, s3
	v_lshl_add_u64 v[204:205], v[204:205], 0, s[16:17]
	s_mov_b32 m0, s24
	ds_read_b128 v[160:163], v211 offset:49152
	ds_read_b128 v[164:167], v211 offset:50176
	ds_read_b128 v[168:171], v211 offset:51200
	ds_read_b128 v[172:175], v211 offset:52224
	ds_read_b128 v[188:191], v211 offset:53248
	ds_read_b128 v[192:195], v211 offset:54272
	ds_read_b128 v[196:199], v211 offset:55296
	ds_read_b128 v[200:203], v211 offset:56320
	global_load_lds_dwordx4 v[204:205], off
	s_add_i32 m0, s24, 0x2000
	s_add_u32 s0, s0, 0x80080
	v_lshl_add_u64 v[204:205], v[212:213], 0, s[16:17]
	s_addc_u32 s1, s1, 0
	s_add_i32 s24, s58, s3
	global_load_lds_dwordx4 v[204:205], off
	v_lshl_add_u64 v[204:205], s[0:1], 0, v[176:177]
	s_mov_b32 m0, s24
	s_nop 0
	global_load_lds_dwordx4 v[204:205], off
	v_lshl_add_u64 v[204:205], s[0:1], 0, v[178:179]
	s_add_i32 m0, s24, 0x2000
	s_nop 0
	global_load_lds_dwordx4 v[204:205], off
	v_lshl_add_u64 v[204:205], v[214:215], 0, s[16:17]
	s_mov_b32 m0, s43
	s_nop 0
	global_load_lds_dwordx4 v[204:205], off
	v_lshl_add_u64 v[204:205], v[216:217], 0, s[16:17]
	s_mov_b32 m0, s44
	s_nop 0
	global_load_lds_dwordx4 v[204:205], off
	s_waitcnt vmcnt(8)
	s_waitcnt lgkmcnt(0)
	s_barrier
	s_setprio 1
	s_waitcnt lgkmcnt(0)
	v_mfma_f32_16x16x32_bf16 v[60:63], v[128:131], v[160:163], v[60:63]
	v_mfma_f32_16x16x32_bf16 v[56:59], v[136:139], v[160:163], v[56:59]
	v_mfma_f32_16x16x32_bf16 v[44:47], v[128:131], v[168:171], v[44:47]
	v_mfma_f32_16x16x32_bf16 v[40:43], v[136:139], v[168:171], v[40:43]
	v_mfma_f32_16x16x32_bf16 v[28:31], v[128:131], v[188:191], v[28:31]
	v_mfma_f32_16x16x32_bf16 v[24:27], v[136:139], v[188:191], v[24:27]
	v_mfma_f32_16x16x32_bf16 v[12:15], v[128:131], v[196:199], v[12:15]
	v_mfma_f32_16x16x32_bf16 v[8:11], v[136:139], v[196:199], v[8:11]
	v_mfma_f32_16x16x32_bf16 v[60:63], v[132:135], v[164:167], v[60:63]
	v_mfma_f32_16x16x32_bf16 v[56:59], v[140:143], v[164:167], v[56:59]
	v_mfma_f32_16x16x32_bf16 v[44:47], v[132:135], v[172:175], v[44:47]
	v_mfma_f32_16x16x32_bf16 v[40:43], v[140:143], v[172:175], v[40:43]
	v_mfma_f32_16x16x32_bf16 v[28:31], v[132:135], v[192:195], v[28:31]
	v_mfma_f32_16x16x32_bf16 v[24:27], v[140:143], v[192:195], v[24:27]
	v_mfma_f32_16x16x32_bf16 v[12:15], v[132:135], v[200:203], v[12:15]
	v_mfma_f32_16x16x32_bf16 v[8:11], v[140:143], v[200:203], v[8:11]
	v_mfma_f32_16x16x32_bf16 v[52:55], v[144:147], v[160:163], v[52:55]
	v_mfma_f32_16x16x32_bf16 v[48:51], v[152:155], v[160:163], v[48:51]
	v_mfma_f32_16x16x32_bf16 v[36:39], v[144:147], v[168:171], v[36:39]
	v_mfma_f32_16x16x32_bf16 v[32:35], v[152:155], v[168:171], v[32:35]
	v_mfma_f32_16x16x32_bf16 v[20:23], v[144:147], v[188:191], v[20:23]
	v_mfma_f32_16x16x32_bf16 v[16:19], v[152:155], v[188:191], v[16:19]
	v_mfma_f32_16x16x32_bf16 v[4:7], v[144:147], v[196:199], v[4:7]
	v_mfma_f32_16x16x32_bf16 v[0:3], v[152:155], v[196:199], v[0:3]
	v_mfma_f32_16x16x32_bf16 v[52:55], v[148:151], v[164:167], v[52:55]
	v_mfma_f32_16x16x32_bf16 v[48:51], v[156:159], v[164:167], v[48:51]
	v_mfma_f32_16x16x32_bf16 v[36:39], v[148:151], v[172:175], v[36:39]
	v_mfma_f32_16x16x32_bf16 v[32:35], v[156:159], v[172:175], v[32:35]
	v_mfma_f32_16x16x32_bf16 v[20:23], v[148:151], v[192:195], v[20:23]
	v_mfma_f32_16x16x32_bf16 v[16:19], v[156:159], v[192:195], v[16:19]
	v_mfma_f32_16x16x32_bf16 v[4:7], v[148:151], v[200:203], v[4:7]
	v_mfma_f32_16x16x32_bf16 v[0:3], v[156:159], v[200:203], v[0:3]
	s_setprio 0
	s_barrier
	s_add_i32 s56, s56, 2
	s_add_u32 s40, s40, 0x100
	s_addc_u32 s41, s41, 0
	s_add_u32 s54, s54, 0x100
	s_addc_u32 s55, s55, 0
	s_cmp_gt_u32 s56, 29
	s_cbranch_scc0 .LBB0_1798
	s_and_b64 vcc, exec, s[18:19]
	s_cbranch_vccz .LBB0_1801
	s_barrier

; #define PG8_STAGE(bufoff, gbase, voff) do { _Pragma("unroll") for (int _i = 0; _i < 2; ++_i) \
;         __builtin_amdgcn_global_load_lds((const unsigned*)((const char*)(gbase) + (voff)[_i]), (PG8_LAS unsigned*)(lds + (bufoff) + ldsw + _i * 8192), 16, 0, 0); } while (0)
; #define PG8_LDA(dst, b, h) do { _Pragma("unroll") for (int m = 0; m < 4; ++m) _Pragma("unroll") for (int k = 0; k < 2; ++k) dst[m][k] = *(const PG8_LAS bf16x8*)(lds + PG8_SA(b, h) + aoff + m * 2048 + k * 1024); } while (0)
; #define PG8_LDB(dst, b, h) do { _Pragma("unroll") for (int n = 0; n < 2; ++n) _Pragma("unroll") for (int k = 0; k < 2; ++k) dst[n][k] = *(const PG8_LAS bf16x8*)(lds + PG8_SB(b, h) + boff + n * 2048 + k * 1024); } while (0)
; #define PG8_MMA(ai, bj, At, Bt) do { __builtin_amdgcn_s_setprio(1); _Pragma("unroll") for (int m = 0; m < 4; ++m) _Pragma("unroll") for (int n = 0; n < 2; ++n) _Pragma("unroll") for (int k = 0; k < 2; ++k) \
;         acc[ai][bj][m][n] = __builtin_amdgcn_mfma_f32_16x16x32_bf16(Bt[n][k], At[m][k], acc[ai][bj][m][n], 0, 0, 0); __builtin_amdgcn_s_setprio(0); } while (0)
; #define PG8_WAIT_V(n) asm volatile("s_waitcnt vmcnt(" #n ")" ::: "memory")
; #define PG8_WAIT_L(n) asm volatile("s_waitcnt lgkmcnt(" #n ")" ::: "memory")
; template <class Epi, class Sched, bool ALIGN_EPI = false, bool SP2 = false>
; __device__ __forceinline__ void gemm_phase(PG8_LAS unsigned char* lds, const Gemm g, const Sched& S, const Epi& E) {
;     ...
;             const bool last = (t == nt - 2);
;             const char* a1 = cA + (size_t)(t + 1) * kstep;
;             const char* a2 = last ? nA : cA + (size_t)(t + 2) * kstep; const char* b2 = last ? nB : cB + (size_t)(t + 2) * kstep;
;             const char* a3 = a2 + kstep; const char* b3 = b2 + kstep;
;             if (last && has_next) S.a_ready(nxt);
;             if constexpr (SP2) {
;             PG8_LDB(B0, 0, 0); PG8_LDB(B1, 0, 1); PG8_SCHED; PG8_LDA(At, 0, 0); PG8_STAGE(PG8_SA(1, 1), a1 + hstep, voffA);
;             PG8_WAIT_V(8); PG8_WAIT_L(0); PG8_BAR; PG8_MMA(0, 0, At, B0); PG8_MMA(0, 1, At, B1); PG8_BAR; PG8_SCHED;
;             PG8_LDA(At, 0, 1); PG8_STAGE(PG8_SB(0, 0), b2, voffB); PG8_STAGE(PG8_SB(0, 1), b2 + hstep, voffB); PG8_STAGE(PG8_SA(0, 0), a2, voffA);
;             PG8_WAIT_V(8); PG8_WAIT_L(0); PG8_BAR; PG8_MMA(1, 0, At, B0); PG8_MMA(1, 1, At, B1); PG8_BAR; PG8_SCHED;
.LBB0_1882:
	ds_read_b128 v[144:147], v155
	ds_read_b128 v[148:151], v155 offset:1024
	ds_read_b128 v[160:163], v155 offset:2048
	ds_read_b128 v[164:167], v155 offset:3072
	ds_read_b128 v[168:171], v156
	ds_read_b128 v[172:175], v156 offset:1024
	ds_read_b128 v[176:179], v156 offset:2048
	ds_read_b128 v[180:183], v156 offset:3072
	s_add_u32 s0, s30, 0xfff80080
	s_addc_u32 s1, s31, -1
	s_cmp_eq_u32 s55, 28
	s_cselect_b32 s25, s21, s1
	s_cselect_b32 s24, s51, s0
	s_cselect_b32 s1, s19, s54
	s_cselect_b32 s0, s52, s53
	v_lshl_add_u64 v[216:217], s[30:31], 0, v[136:137]
	s_add_i32 m0, s36, 0xc000
	ds_read_b128 v[184:187], v157
	ds_read_b128 v[188:191], v157 offset:1024
	ds_read_b128 v[192:195], v157 offset:2048
	ds_read_b128 v[196:199], v157 offset:3072
	ds_read_b128 v[200:203], v157 offset:4096
	ds_read_b128 v[204:207], v157 offset:5120
	ds_read_b128 v[208:211], v157 offset:6144
	ds_read_b128 v[212:215], v157 offset:7168
	global_load_lds_dwordx4 v[216:217], off
	v_lshl_add_u64 v[216:217], s[30:31], 0, v[138:139]
	s_add_i32 m0, s36, 0xe000
	s_nop 0
	global_load_lds_dwordx4 v[216:217], off
	s_waitcnt vmcnt(8)
	s_waitcnt lgkmcnt(0)
	s_barrier
	s_setprio 1
	s_waitcnt lgkmcnt(0)
	v_mfma_f32_16x16x32_bf16 v[124:127], v[144:147], v[184:187], v[124:127]
	v_mfma_f32_16x16x32_bf16 v[120:123], v[160:163], v[184:187], v[120:123]
	v_mfma_f32_16x16x32_bf16 v[108:111], v[144:147], v[192:195], v[108:111]
	v_mfma_f32_16x16x32_bf16 v[104:107], v[160:163], v[192:195], v[104:107]
	v_mfma_f32_16x16x32_bf16 v[92:95], v[144:147], v[200:203], v[92:95]
	v_mfma_f32_16x16x32_bf16 v[88:91], v[160:163], v[200:203], v[88:91]
	v_mfma_f32_16x16x32_bf16 v[76:79], v[144:147], v[208:211], v[76:79]
	v_mfma_f32_16x16x32_bf16 v[72:75], v[160:163], v[208:211], v[72:75]
	v_mfma_f32_16x16x32_bf16 v[124:127], v[148:151], v[188:191], v[124:127]
	v_mfma_f32_16x16x32_bf16 v[120:123], v[164:167], v[188:191], v[120:123]
	v_mfma_f32_16x16x32_bf16 v[108:111], v[148:151], v[196:199], v[108:111]
	v_mfma_f32_16x16x32_bf16 v[104:107], v[164:167], v[196:199], v[104:107]
	v_mfma_f32_16x16x32_bf16 v[92:95], v[148:151], v[204:207], v[92:95]
	v_mfma_f32_16x16x32_bf16 v[88:91], v[164:167], v[204:207], v[88:91]
	v_mfma_f32_16x16x32_bf16 v[76:79], v[148:151], v[212:215], v[76:79]
	v_mfma_f32_16x16x32_bf16 v[72:75], v[164:167], v[212:215], v[72:75]
	v_mfma_f32_16x16x32_bf16 v[116:119], v[168:171], v[184:187], v[116:119]
	v_mfma_f32_16x16x32_bf16 v[112:115], v[176:179], v[184:187], v[112:115]
	v_mfma_f32_16x16x32_bf16 v[100:103], v[168:171], v[192:195], v[100:103]
	v_mfma_f32_16x16x32_bf16 v[96:99], v[176:179], v[192:195], v[96:99]
	v_mfma_f32_16x16x32_bf16 v[84:87], v[168:171], v[200:203], v[84:87]
	v_mfma_f32_16x16x32_bf16 v[80:83], v[176:179], v[200:203], v[80:83]
	v_mfma_f32_16x16x32_bf16 v[68:71], v[168:171], v[208:211], v[68:71]
	v_mfma_f32_16x16x32_bf16 v[64:67], v[176:179], v[208:211], v[64:67]
	v_mfma_f32_16x16x32_bf16 v[116:119], v[172:175], v[188:191], v[116:119]
	v_mfma_f32_16x16x32_bf16 v[112:115], v[180:183], v[188:191], v[112:115]
	v_mfma_f32_16x16x32_bf16 v[100:103], v[172:175], v[196:199], v[100:103]
	v_mfma_f32_16x16x32_bf16 v[96:99], v[180:183], v[196:199], v[96:99]
	v_mfma_f32_16x16x32_bf16 v[84:87], v[172:175], v[204:207], v[84:87]
	v_mfma_f32_16x16x32_bf16 v[80:83], v[180:183], v[204:207], v[80:83]
	v_mfma_f32_16x16x32_bf16 v[68:71], v[172:175], v[212:215], v[68:71]
	v_mfma_f32_16x16x32_bf16 v[64:67], v[180:183], v[212:215], v[64:67]
	s_setprio 0
	s_barrier
	s_add_i32 s56, s45, s3
	v_lshl_add_u64 v[216:217], s[0:1], 0, v[132:133]
	s_mov_b32 m0, s56
	ds_read_b128 v[184:187], v157 offset:16384
	ds_read_b128 v[188:191], v157 offset:17408
	ds_read_b128 v[192:195], v157 offset:18432
	ds_read_b128 v[196:199], v157 offset:19456
	ds_read_b128 v[200:203], v157 offset:20480
	ds_read_b128 v[204:207], v157 offset:21504
	ds_read_b128 v[208:211], v157 offset:22528
	ds_read_b128 v[212:215], v157 offset:23552
	global_load_lds_dwordx4 v[216:217], off
	s_add_i32 m0, s56, 0x2000
	s_add_u32 s56, s0, 0x80000
	v_lshl_add_u64 v[218:219], s[0:1], 0, v[128:129]
	s_addc_u32 s57, s1, 0
	s_add_i32 s58, s46, s3
	global_load_lds_dwordx4 v[218:219], off
	v_lshl_add_u64 v[220:221], s[56:57], 0, v[132:133]
	s_mov_b32 m0, s58
	v_lshl_add_u64 v[224:225], s[24:25], 0, v[130:131]
	global_load_lds_dwordx4 v[220:221], off
	v_lshl_add_u64 v[220:221], s[56:57], 0, v[128:129]
	s_add_i32 m0, s58, 0x2000
	s_nop 0
	global_load_lds_dwordx4 v[220:221], off
	v_lshl_add_u64 v[220:221], s[24:25], 0, v[134:135]
	s_mov_b32 m0, s36
	s_nop 0
	global_load_lds_dwordx4 v[220:221], off
	s_mov_b32 m0, s37
	s_nop 0
	global_load_lds_dwordx4 v[224:225], off
	s_waitcnt vmcnt(8)
	s_waitcnt lgkmcnt(0)
	s_barrier
; #define PG8_STAGE(bufoff, gbase, voff) do { _Pragma("unroll") for (int _i = 0; _i < 2; ++_i) \
;         __builtin_amdgcn_global_load_lds((const unsigned*)((const char*)(gbase) + (voff)[_i]), (PG8_LAS unsigned*)(lds + (bufoff) + ldsw + _i * 8192), 16, 0, 0); } while (0)
; #define PG8_LDA(dst, b, h) do { _Pragma("unroll") for (int m = 0; m < 4; ++m) _Pragma("unroll") for (int k = 0; k < 2; ++k) dst[m][k] = *(const PG8_LAS bf16x8*)(lds + PG8_SA(b, h) + aoff + m * 2048 + k * 1024); } while (0)
; #define PG8_LDB(dst, b, h) do { _Pragma("unroll") for (int n = 0; n < 2; ++n) _Pragma("unroll") for (int k = 0; k < 2; ++k) dst[n][k] = *(const PG8_LAS bf16x8*)(lds + PG8_SB(b, h) + boff + n * 2048 + k * 1024); } while (0)
; #define PG8_MMA(ai, bj, At, Bt) do { __builtin_amdgcn_s_setprio(1); _Pragma("unroll") for (int m = 0; m < 4; ++m) _Pragma("unroll") for (int n = 0; n < 2; ++n) _Pragma("unroll") for (int k = 0; k < 2; ++k) \
;         acc[ai][bj][m][n] = __builtin_amdgcn_mfma_f32_16x16x32_bf16(Bt[n][k], At[m][k], acc[ai][bj][m][n], 0, 0, 0); __builtin_amdgcn_s_setprio(0); } while (0)
; #define PG8_WAIT_V(n) asm volatile("s_waitcnt vmcnt(" #n ")" ::: "memory")
; #define PG8_WAIT_L(n) asm volatile("s_waitcnt lgkmcnt(" #n ")" ::: "memory")
; #define PG8_BAR __builtin_amdgcn_s_barrier()
; #define PG8_SCHED __builtin_amdgcn_sched_barrier(0)
; template <class Epi, class Sched, bool ALIGN_EPI = false, bool SP2 = false>
; __device__ __forceinline__ void gemm_phase(PG8_LAS unsigned char* lds, const Gemm g, const Sched& S, const Epi& E) {
;     ...
;             PG8_WAIT_V(8); PG8_WAIT_L(0); PG8_BAR; PG8_MMA(1, 0, At, B0); PG8_MMA(1, 1, At, B1); PG8_BAR; PG8_SCHED;
;             PG8_LDB(B0, 1, 0); PG8_LDB(B1, 1, 1); PG8_SCHED; PG8_LDA(At, 1, 0); PG8_STAGE(PG8_SA(0, 1), a2 + hstep, voffA);
;             PG8_WAIT_V(8); PG8_WAIT_L(0); PG8_BAR; PG8_MMA(0, 0, At, B0); PG8_MMA(0, 1, At, B1); PG8_BAR; PG8_SCHED;
	s_setprio 1
	s_waitcnt lgkmcnt(0)
	v_mfma_f32_16x16x32_bf16 v[60:63], v[144:147], v[184:187], v[60:63]
	v_mfma_f32_16x16x32_bf16 v[56:59], v[160:163], v[184:187], v[56:59]
	v_mfma_f32_16x16x32_bf16 v[44:47], v[144:147], v[192:195], v[44:47]
	v_mfma_f32_16x16x32_bf16 v[40:43], v[160:163], v[192:195], v[40:43]
	v_mfma_f32_16x16x32_bf16 v[28:31], v[144:147], v[200:203], v[28:31]
	v_mfma_f32_16x16x32_bf16 v[24:27], v[160:163], v[200:203], v[24:27]
	v_mfma_f32_16x16x32_bf16 v[12:15], v[144:147], v[208:211], v[12:15]
	v_mfma_f32_16x16x32_bf16 v[8:11], v[160:163], v[208:211], v[8:11]
	v_mfma_f32_16x16x32_bf16 v[60:63], v[148:151], v[188:191], v[60:63]
	v_mfma_f32_16x16x32_bf16 v[56:59], v[164:167], v[188:191], v[56:59]
	v_mfma_f32_16x16x32_bf16 v[44:47], v[148:151], v[196:199], v[44:47]
	v_mfma_f32_16x16x32_bf16 v[40:43], v[164:167], v[196:199], v[40:43]
	v_mfma_f32_16x16x32_bf16 v[28:31], v[148:151], v[204:207], v[28:31]
	v_mfma_f32_16x16x32_bf16 v[24:27], v[164:167], v[204:207], v[24:27]
	v_mfma_f32_16x16x32_bf16 v[12:15], v[148:151], v[212:215], v[12:15]
	v_mfma_f32_16x16x32_bf16 v[8:11], v[164:167], v[212:215], v[8:11]
	v_mfma_f32_16x16x32_bf16 v[52:55], v[168:171], v[184:187], v[52:55]
	v_mfma_f32_16x16x32_bf16 v[48:51], v[176:179], v[184:187], v[48:51]
	v_mfma_f32_16x16x32_bf16 v[36:39], v[168:171], v[192:195], v[36:39]
	v_mfma_f32_16x16x32_bf16 v[32:35], v[176:179], v[192:195], v[32:35]
	v_mfma_f32_16x16x32_bf16 v[20:23], v[168:171], v[200:203], v[20:23]
	v_mfma_f32_16x16x32_bf16 v[16:19], v[176:179], v[200:203], v[16:19]
	v_mfma_f32_16x16x32_bf16 v[4:7], v[168:171], v[208:211], v[4:7]
	v_mfma_f32_16x16x32_bf16 v[0:3], v[176:179], v[208:211], v[0:3]
	v_mfma_f32_16x16x32_bf16 v[52:55], v[172:175], v[188:191], v[52:55]
	v_mfma_f32_16x16x32_bf16 v[48:51], v[180:183], v[188:191], v[48:51]
	v_mfma_f32_16x16x32_bf16 v[36:39], v[172:175], v[196:199], v[36:39]
	v_mfma_f32_16x16x32_bf16 v[32:35], v[180:183], v[196:199], v[32:35]
	v_mfma_f32_16x16x32_bf16 v[20:23], v[172:175], v[204:207], v[20:23]
	v_mfma_f32_16x16x32_bf16 v[16:19], v[180:183], v[204:207], v[16:19]
	v_mfma_f32_16x16x32_bf16 v[4:7], v[172:175], v[212:215], v[4:7]
	v_mfma_f32_16x16x32_bf16 v[0:3], v[180:183], v[212:215], v[0:3]
	s_setprio 0
	s_barrier
	s_add_i32 s56, 0, 0x18000
	s_add_i32 s57, 0, 0x1c000
	v_add_u32_e32 v164, s56, v153
	v_add_u32_e32 v180, s57, v153
	ds_read_b128 v[144:147], v164
	ds_read_b128 v[148:151], v164 offset:1024
	ds_read_b128 v[160:163], v164 offset:2048
	ds_read_b128 v[164:167], v164 offset:3072
	ds_read_b128 v[168:171], v180
	ds_read_b128 v[172:175], v180 offset:1024
	ds_read_b128 v[176:179], v180 offset:2048
	ds_read_b128 v[180:183], v180 offset:3072
	s_add_u32 s24, s24, 0x80000
	s_addc_u32 s25, s25, 0
	s_mov_b32 m0, s38
	v_lshl_add_u64 v[228:229], s[24:25], 0, v[134:135]
	ds_read_b128 v[184:187], v157 offset:32768
	ds_read_b128 v[188:191], v157 offset:33792
	ds_read_b128 v[192:195], v157 offset:34816
	ds_read_b128 v[196:199], v157 offset:35840
	ds_read_b128 v[200:203], v157 offset:36864
	ds_read_b128 v[204:207], v157 offset:37888
	ds_read_b128 v[208:211], v157 offset:38912
	ds_read_b128 v[212:215], v157 offset:39936
	global_load_lds_dwordx4 v[228:229], off
	v_lshl_add_u64 v[228:229], s[24:25], 0, v[130:131]
	s_mov_b32 m0, s39
	s_nop 0
	global_load_lds_dwordx4 v[228:229], off
	s_waitcnt vmcnt(8)
	s_waitcnt lgkmcnt(0)
	s_barrier
	s_setprio 1
	s_waitcnt lgkmcnt(0)
	v_mfma_f32_16x16x32_bf16 v[124:127], v[144:147], v[184:187], v[124:127]
	v_mfma_f32_16x16x32_bf16 v[120:123], v[160:163], v[184:187], v[120:123]
	v_mfma_f32_16x16x32_bf16 v[108:111], v[144:147], v[192:195], v[108:111]
	v_mfma_f32_16x16x32_bf16 v[104:107], v[160:163], v[192:195], v[104:107]
	v_mfma_f32_16x16x32_bf16 v[92:95], v[144:147], v[200:203], v[92:95]
	v_mfma_f32_16x16x32_bf16 v[88:91], v[160:163], v[200:203], v[88:91]
	v_mfma_f32_16x16x32_bf16 v[76:79], v[144:147], v[208:211], v[76:79]
	v_mfma_f32_16x16x32_bf16 v[72:75], v[160:163], v[208:211], v[72:75]
	v_mfma_f32_16x16x32_bf16 v[124:127], v[148:151], v[188:191], v[124:127]
	v_mfma_f32_16x16x32_bf16 v[120:123], v[164:167], v[188:191], v[120:123]
	v_mfma_f32_16x16x32_bf16 v[108:111], v[148:151], v[196:199], v[108:111]
	v_mfma_f32_16x16x32_bf16 v[104:107], v[164:167], v[196:199], v[104:107]
	v_mfma_f32_16x16x32_bf16 v[92:95], v[148:151], v[204:207], v[92:95]
	v_mfma_f32_16x16x32_bf16 v[88:91], v[164:167], v[204:207], v[88:91]
	v_mfma_f32_16x16x32_bf16 v[76:79], v[148:151], v[212:215], v[76:79]
	v_mfma_f32_16x16x32_bf16 v[72:75], v[164:167], v[212:215], v[72:75]
	v_mfma_f32_16x16x32_bf16 v[116:119], v[168:171], v[184:187], v[116:119]
	v_mfma_f32_16x16x32_bf16 v[112:115], v[176:179], v[184:187], v[112:115]
	v_mfma_f32_16x16x32_bf16 v[100:103], v[168:171], v[192:195], v[100:103]
	v_mfma_f32_16x16x32_bf16 v[96:99], v[176:179], v[192:195], v[96:99]
	v_mfma_f32_16x16x32_bf16 v[84:87], v[168:171], v[200:203], v[84:87]
	v_mfma_f32_16x16x32_bf16 v[80:83], v[176:179], v[200:203], v[80:83]
	v_mfma_f32_16x16x32_bf16 v[68:71], v[168:171], v[208:211], v[68:71]
	v_mfma_f32_16x16x32_bf16 v[64:67], v[176:179], v[208:211], v[64:67]
	v_mfma_f32_16x16x32_bf16 v[116:119], v[172:175], v[188:191], v[116:119]
	v_mfma_f32_16x16x32_bf16 v[112:115], v[180:183], v[188:191], v[112:115]
	v_mfma_f32_16x16x32_bf16 v[100:103], v[172:175], v[196:199], v[100:103]
	v_mfma_f32_16x16x32_bf16 v[96:99], v[180:183], v[196:199], v[96:99]
	v_mfma_f32_16x16x32_bf16 v[84:87], v[172:175], v[204:207], v[84:87]
	v_mfma_f32_16x16x32_bf16 v[80:83], v[180:183], v[204:207], v[80:83]
	v_mfma_f32_16x16x32_bf16 v[68:71], v[172:175], v[212:215], v[68:71]
	v_mfma_f32_16x16x32_bf16 v[64:67], v[180:183], v[212:215], v[64:67]
	s_setprio 0
	s_barrier
; #define PG8_STAGE(bufoff, gbase, voff) do { _Pragma("unroll") for (int _i = 0; _i < 2; ++_i) \
;         __builtin_amdgcn_global_load_lds((const unsigned*)((const char*)(gbase) + (voff)[_i]), (PG8_LAS unsigned*)(lds + (bufoff) + ldsw + _i * 8192), 16, 0, 0); } while (0)
; #define PG8_LDA(dst, b, h) do { _Pragma("unroll") for (int m = 0; m < 4; ++m) _Pragma("unroll") for (int k = 0; k < 2; ++k) dst[m][k] = *(const PG8_LAS bf16x8*)(lds + PG8_SA(b, h) + aoff + m * 2048 + k * 1024); } while (0)
; #define PG8_MMA(ai, bj, At, Bt) do { __builtin_amdgcn_s_setprio(1); _Pragma("unroll") for (int m = 0; m < 4; ++m) _Pragma("unroll") for (int n = 0; n < 2; ++n) _Pragma("unroll") for (int k = 0; k < 2; ++k) \
;         acc[ai][bj][m][n] = __builtin_amdgcn_mfma_f32_16x16x32_bf16(Bt[n][k], At[m][k], acc[ai][bj][m][n], 0, 0, 0); __builtin_amdgcn_s_setprio(0); } while (0)
; #define PG8_WAIT_V(n) asm volatile("s_waitcnt vmcnt(" #n ")" ::: "memory")
; #define PG8_WAIT_L(n) asm volatile("s_waitcnt lgkmcnt(" #n ")" ::: "memory")
; #define PG8_BAR __builtin_amdgcn_s_barrier()
; #define PG8_SCHED __builtin_amdgcn_sched_barrier(0)
; template <class Epi, class Sched, bool ALIGN_EPI = false, bool SP2 = false>
; __device__ __forceinline__ void gemm_phase(PG8_LAS unsigned char* lds, const Gemm g, const Sched& S, const Epi& E) {
;     ...
;             PG8_LDA(At, 1, 1); PG8_STAGE(PG8_SB(1, 0), b3, voffB); PG8_STAGE(PG8_SB(1, 1), b3 + hstep, voffB); PG8_STAGE(PG8_SA(1, 0), a3, voffA);
;             PG8_WAIT_V(8); PG8_WAIT_L(0); PG8_BAR; PG8_MMA(1, 0, At, B0); PG8_MMA(1, 1, At, B1); PG8_BAR; PG8_SCHED;
;     ...
;         if constexpr (ALIGN_EPI) { if (wr == 0) PG8_BAR; }
	s_add_i32 s24, s56, s3
	v_lshl_add_u64 v[216:217], v[216:217], 0, s[14:15]
	s_mov_b32 m0, s24
	ds_read_b128 v[184:187], v157 offset:49152
	ds_read_b128 v[188:191], v157 offset:50176
	ds_read_b128 v[192:195], v157 offset:51200
	ds_read_b128 v[196:199], v157 offset:52224
	ds_read_b128 v[200:203], v157 offset:53248
	ds_read_b128 v[204:207], v157 offset:54272
	ds_read_b128 v[208:211], v157 offset:55296
	ds_read_b128 v[212:215], v157 offset:56320
	global_load_lds_dwordx4 v[216:217], off
	s_add_i32 m0, s24, 0x2000
	s_add_u32 s0, s0, 0x80080
	v_lshl_add_u64 v[216:217], v[218:219], 0, s[14:15]
	s_addc_u32 s1, s1, 0
	s_add_i32 s24, s57, s3
	global_load_lds_dwordx4 v[216:217], off
	v_lshl_add_u64 v[216:217], s[0:1], 0, v[132:133]
	s_mov_b32 m0, s24
	s_nop 0
	global_load_lds_dwordx4 v[216:217], off
	v_lshl_add_u64 v[216:217], s[0:1], 0, v[128:129]
	s_add_i32 m0, s24, 0x2000
	s_nop 0
	global_load_lds_dwordx4 v[216:217], off
	v_lshl_add_u64 v[216:217], v[220:221], 0, s[14:15]
	s_mov_b32 m0, s41
	s_nop 0
	global_load_lds_dwordx4 v[216:217], off
	v_lshl_add_u64 v[216:217], v[224:225], 0, s[14:15]
	s_mov_b32 m0, s42
	s_nop 0
	global_load_lds_dwordx4 v[216:217], off
	s_waitcnt vmcnt(8)
	s_waitcnt lgkmcnt(0)
	s_barrier
	s_setprio 1
	s_waitcnt lgkmcnt(0)
	v_mfma_f32_16x16x32_bf16 v[60:63], v[144:147], v[184:187], v[60:63]
	v_mfma_f32_16x16x32_bf16 v[56:59], v[160:163], v[184:187], v[56:59]
	v_mfma_f32_16x16x32_bf16 v[44:47], v[144:147], v[192:195], v[44:47]
	v_mfma_f32_16x16x32_bf16 v[40:43], v[160:163], v[192:195], v[40:43]
	v_mfma_f32_16x16x32_bf16 v[28:31], v[144:147], v[200:203], v[28:31]
	v_mfma_f32_16x16x32_bf16 v[24:27], v[160:163], v[200:203], v[24:27]
	v_mfma_f32_16x16x32_bf16 v[12:15], v[144:147], v[208:211], v[12:15]
	v_mfma_f32_16x16x32_bf16 v[8:11], v[160:163], v[208:211], v[8:11]
	v_mfma_f32_16x16x32_bf16 v[60:63], v[148:151], v[188:191], v[60:63]
	v_mfma_f32_16x16x32_bf16 v[56:59], v[164:167], v[188:191], v[56:59]
	v_mfma_f32_16x16x32_bf16 v[44:47], v[148:151], v[196:199], v[44:47]
	v_mfma_f32_16x16x32_bf16 v[40:43], v[164:167], v[196:199], v[40:43]
	v_mfma_f32_16x16x32_bf16 v[28:31], v[148:151], v[204:207], v[28:31]
	v_mfma_f32_16x16x32_bf16 v[24:27], v[164:167], v[204:207], v[24:27]
	v_mfma_f32_16x16x32_bf16 v[12:15], v[148:151], v[212:215], v[12:15]
	v_mfma_f32_16x16x32_bf16 v[8:11], v[164:167], v[212:215], v[8:11]
	v_mfma_f32_16x16x32_bf16 v[52:55], v[168:171], v[184:187], v[52:55]
	v_mfma_f32_16x16x32_bf16 v[48:51], v[176:179], v[184:187], v[48:51]
	v_mfma_f32_16x16x32_bf16 v[36:39], v[168:171], v[192:195], v[36:39]
	v_mfma_f32_16x16x32_bf16 v[32:35], v[176:179], v[192:195], v[32:35]
	v_mfma_f32_16x16x32_bf16 v[20:23], v[168:171], v[200:203], v[20:23]
	v_mfma_f32_16x16x32_bf16 v[16:19], v[176:179], v[200:203], v[16:19]
	v_mfma_f32_16x16x32_bf16 v[4:7], v[168:171], v[208:211], v[4:7]
	v_mfma_f32_16x16x32_bf16 v[0:3], v[176:179], v[208:211], v[0:3]
	v_mfma_f32_16x16x32_bf16 v[52:55], v[172:175], v[188:191], v[52:55]
	v_mfma_f32_16x16x32_bf16 v[48:51], v[180:183], v[188:191], v[48:51]
	v_mfma_f32_16x16x32_bf16 v[36:39], v[172:175], v[196:199], v[36:39]
	v_mfma_f32_16x16x32_bf16 v[32:35], v[180:183], v[196:199], v[32:35]
	v_mfma_f32_16x16x32_bf16 v[20:23], v[172:175], v[204:207], v[20:23]
	v_mfma_f32_16x16x32_bf16 v[16:19], v[180:183], v[204:207], v[16:19]
	v_mfma_f32_16x16x32_bf16 v[4:7], v[172:175], v[212:215], v[4:7]
	v_mfma_f32_16x16x32_bf16 v[0:3], v[180:183], v[212:215], v[0:3]
	s_setprio 0
	s_barrier
	s_add_i32 s55, s55, 2
	s_add_u32 s30, s30, 0x100
	s_addc_u32 s31, s31, 0
	s_add_u32 s53, s53, 0x100
	s_addc_u32 s54, s54, 0
	s_cmp_gt_u32 s55, 29
	s_cbranch_scc0 .LBB0_1882
	s_and_b64 vcc, exec, s[16:17]
	s_cbranch_vccz .LBB0_1885
	s_barrier

; #define PG8_STAGE(bufoff, gbase, voff) do { _Pragma("unroll") for (int _i = 0; _i < 2; ++_i) \
;         __builtin_amdgcn_global_load_lds((const unsigned*)((const char*)(gbase) + (voff)[_i]), (PG8_LAS unsigned*)(lds + (bufoff) + ldsw + _i * 8192), 16, 0, 0); } while (0)
; #define PG8_LDA(dst, b, h) do { _Pragma("unroll") for (int m = 0; m < 4; ++m) _Pragma("unroll") for (int k = 0; k < 2; ++k) dst[m][k] = *(const PG8_LAS bf16x8*)(lds + PG8_SA(b, h) + aoff + m * 2048 + k * 1024); } while (0)
; #define PG8_LDB(dst, b, h) do { _Pragma("unroll") for (int n = 0; n < 2; ++n) _Pragma("unroll") for (int k = 0; k < 2; ++k) dst[n][k] = *(const PG8_LAS bf16x8*)(lds + PG8_SB(b, h) + boff + n * 2048 + k * 1024); } while (0)
; #define PG8_MMA(ai, bj, At, Bt) do { __builtin_amdgcn_s_setprio(1); _Pragma("unroll") for (int m = 0; m < 4; ++m) _Pragma("unroll") for (int n = 0; n < 2; ++n) _Pragma("unroll") for (int k = 0; k < 2; ++k) \
;         acc[ai][bj][m][n] = __builtin_amdgcn_mfma_f32_16x16x32_bf16(Bt[n][k], At[m][k], acc[ai][bj][m][n], 0, 0, 0); __builtin_amdgcn_s_setprio(0); } while (0)
; #define PG8_WAIT_V(n) asm volatile("s_waitcnt vmcnt(" #n ")" ::: "memory")
; #define PG8_WAIT_L(n) asm volatile("s_waitcnt lgkmcnt(" #n ")" ::: "memory")
; template <class Epi, class Sched, bool ALIGN_EPI = false, bool SP2 = false>
; __device__ __forceinline__ void gemm_phase(PG8_LAS unsigned char* lds, const Gemm g, const Sched& S, const Epi& E) {
;     ...
;             const bool last = (t == nt - 2);
;             const char* a1 = cA + (size_t)(t + 1) * kstep;
;             const char* a2 = last ? nA : cA + (size_t)(t + 2) * kstep; const char* b2 = last ? nB : cB + (size_t)(t + 2) * kstep;
;             const char* a3 = a2 + kstep; const char* b3 = b2 + kstep;
;             if (last && has_next) S.a_ready(nxt);
;             if constexpr (SP2) {
;             PG8_LDB(B0, 0, 0); PG8_LDB(B1, 0, 1); PG8_SCHED; PG8_LDA(At, 0, 0); PG8_STAGE(PG8_SA(1, 1), a1 + hstep, voffA);
;             PG8_WAIT_V(8); PG8_WAIT_L(0); PG8_BAR; PG8_MMA(0, 0, At, B0); PG8_MMA(0, 1, At, B1); PG8_BAR; PG8_SCHED;
;             PG8_LDA(At, 0, 1); PG8_STAGE(PG8_SB(0, 0), b2, voffB); PG8_STAGE(PG8_SB(0, 1), b2 + hstep, voffB); PG8_STAGE(PG8_SA(0, 0), a2, voffA);
;             PG8_WAIT_V(8); PG8_WAIT_L(0); PG8_BAR; PG8_MMA(1, 0, At, B0); PG8_MMA(1, 1, At, B1); PG8_BAR; PG8_SCHED;
.LBB0_1965:
	ds_read_b128 v[128:131], v209
	ds_read_b128 v[132:135], v209 offset:1024
	ds_read_b128 v[136:139], v209 offset:2048
	ds_read_b128 v[140:143], v209 offset:3072
	ds_read_b128 v[144:147], v210
	ds_read_b128 v[148:151], v210 offset:1024
	ds_read_b128 v[152:155], v210 offset:2048
	ds_read_b128 v[156:159], v210 offset:3072
	s_add_u32 s0, s22, 0x100
	s_addc_u32 s1, s23, 0
	s_cmpk_eq_i32 s50, 0x54
	s_cselect_b32 s29, s7, s1
	s_cselect_b32 s28, s6, s0
	s_cselect_b32 s25, s21, s49
	s_cselect_b32 s24, s20, s48
	v_lshl_add_u64 v[204:205], s[22:23], 0, v[180:181]
	s_add_i32 m0, s30, 0xc000
	ds_read_b128 v[160:163], v211
	ds_read_b128 v[164:167], v211 offset:1024
	ds_read_b128 v[168:171], v211 offset:2048
	ds_read_b128 v[172:175], v211 offset:3072
	ds_read_b128 v[188:191], v211 offset:4096
	ds_read_b128 v[192:195], v211 offset:5120
	ds_read_b128 v[196:199], v211 offset:6144
	ds_read_b128 v[200:203], v211 offset:7168
	global_load_lds_dwordx4 v[204:205], off
	v_lshl_add_u64 v[204:205], s[22:23], 0, v[182:183]
	s_add_i32 m0, s30, 0xe000
	s_nop 0
	global_load_lds_dwordx4 v[204:205], off
	s_waitcnt vmcnt(8)
	s_waitcnt lgkmcnt(0)
	s_barrier
	s_setprio 1
	s_waitcnt lgkmcnt(0)
	v_mfma_f32_16x16x32_bf16 v[124:127], v[128:131], v[160:163], v[124:127]
	v_mfma_f32_16x16x32_bf16 v[120:123], v[136:139], v[160:163], v[120:123]
	v_mfma_f32_16x16x32_bf16 v[108:111], v[128:131], v[168:171], v[108:111]
	v_mfma_f32_16x16x32_bf16 v[104:107], v[136:139], v[168:171], v[104:107]
	v_mfma_f32_16x16x32_bf16 v[92:95], v[128:131], v[188:191], v[92:95]
	v_mfma_f32_16x16x32_bf16 v[88:91], v[136:139], v[188:191], v[88:91]
	v_mfma_f32_16x16x32_bf16 v[76:79], v[128:131], v[196:199], v[76:79]
	v_mfma_f32_16x16x32_bf16 v[72:75], v[136:139], v[196:199], v[72:75]
	v_mfma_f32_16x16x32_bf16 v[124:127], v[132:135], v[164:167], v[124:127]
	v_mfma_f32_16x16x32_bf16 v[120:123], v[140:143], v[164:167], v[120:123]
	v_mfma_f32_16x16x32_bf16 v[108:111], v[132:135], v[172:175], v[108:111]
	v_mfma_f32_16x16x32_bf16 v[104:107], v[140:143], v[172:175], v[104:107]
	v_mfma_f32_16x16x32_bf16 v[92:95], v[132:135], v[192:195], v[92:95]
	v_mfma_f32_16x16x32_bf16 v[88:91], v[140:143], v[192:195], v[88:91]
	v_mfma_f32_16x16x32_bf16 v[76:79], v[132:135], v[200:203], v[76:79]
	v_mfma_f32_16x16x32_bf16 v[72:75], v[140:143], v[200:203], v[72:75]
	v_mfma_f32_16x16x32_bf16 v[116:119], v[144:147], v[160:163], v[116:119]
	v_mfma_f32_16x16x32_bf16 v[112:115], v[152:155], v[160:163], v[112:115]
	v_mfma_f32_16x16x32_bf16 v[100:103], v[144:147], v[168:171], v[100:103]
	v_mfma_f32_16x16x32_bf16 v[96:99], v[152:155], v[168:171], v[96:99]
	v_mfma_f32_16x16x32_bf16 v[84:87], v[144:147], v[188:191], v[84:87]
	v_mfma_f32_16x16x32_bf16 v[80:83], v[152:155], v[188:191], v[80:83]
	v_mfma_f32_16x16x32_bf16 v[68:71], v[144:147], v[196:199], v[68:71]
	v_mfma_f32_16x16x32_bf16 v[64:67], v[152:155], v[196:199], v[64:67]
	v_mfma_f32_16x16x32_bf16 v[116:119], v[148:151], v[164:167], v[116:119]
	v_mfma_f32_16x16x32_bf16 v[112:115], v[156:159], v[164:167], v[112:115]
	v_mfma_f32_16x16x32_bf16 v[100:103], v[148:151], v[172:175], v[100:103]
	v_mfma_f32_16x16x32_bf16 v[96:99], v[156:159], v[172:175], v[96:99]
	v_mfma_f32_16x16x32_bf16 v[84:87], v[148:151], v[192:195], v[84:87]
	v_mfma_f32_16x16x32_bf16 v[80:83], v[156:159], v[192:195], v[80:83]
	v_mfma_f32_16x16x32_bf16 v[68:71], v[148:151], v[200:203], v[68:71]
	v_mfma_f32_16x16x32_bf16 v[64:67], v[156:159], v[200:203], v[64:67]
	s_setprio 0
	s_barrier
	s_add_i32 s22, s42, s3
	v_lshl_add_u64 v[204:205], s[24:25], 0, v[176:177]
	s_mov_b32 m0, s22
	ds_read_b128 v[160:163], v211 offset:16384
	ds_read_b128 v[164:167], v211 offset:17408
	ds_read_b128 v[168:171], v211 offset:18432
	ds_read_b128 v[172:175], v211 offset:19456
	ds_read_b128 v[188:191], v211 offset:20480
	ds_read_b128 v[192:195], v211 offset:21504
	ds_read_b128 v[196:199], v211 offset:22528
	ds_read_b128 v[200:203], v211 offset:23552
	global_load_lds_dwordx4 v[204:205], off
	s_add_i32 m0, s22, 0x2000
	s_add_u32 s22, s24, 0x160000
	v_lshl_add_u64 v[212:213], s[24:25], 0, v[178:179]
	s_addc_u32 s23, s25, 0
	s_add_i32 s51, s43, s3
	global_load_lds_dwordx4 v[212:213], off
	v_lshl_add_u64 v[214:215], s[22:23], 0, v[176:177]
	s_mov_b32 m0, s51
	v_lshl_add_u64 v[216:217], s[28:29], 0, v[178:179]
	global_load_lds_dwordx4 v[214:215], off
	v_lshl_add_u64 v[214:215], s[22:23], 0, v[178:179]
	s_add_i32 m0, s51, 0x2000
	s_nop 0
	global_load_lds_dwordx4 v[214:215], off
	v_lshl_add_u64 v[214:215], s[28:29], 0, v[176:177]
	s_mov_b32 m0, s30
	s_nop 0
	global_load_lds_dwordx4 v[214:215], off
	s_mov_b32 m0, s31
	s_nop 0
	global_load_lds_dwordx4 v[216:217], off
	s_waitcnt vmcnt(8)
	s_waitcnt lgkmcnt(0)
	s_barrier
; #define PG8_STAGE(bufoff, gbase, voff) do { _Pragma("unroll") for (int _i = 0; _i < 2; ++_i) \
;         __builtin_amdgcn_global_load_lds((const unsigned*)((const char*)(gbase) + (voff)[_i]), (PG8_LAS unsigned*)(lds + (bufoff) + ldsw + _i * 8192), 16, 0, 0); } while (0)
; #define PG8_LDA(dst, b, h) do { _Pragma("unroll") for (int m = 0; m < 4; ++m) _Pragma("unroll") for (int k = 0; k < 2; ++k) dst[m][k] = *(const PG8_LAS bf16x8*)(lds + PG8_SA(b, h) + aoff + m * 2048 + k * 1024); } while (0)
; #define PG8_LDB(dst, b, h) do { _Pragma("unroll") for (int n = 0; n < 2; ++n) _Pragma("unroll") for (int k = 0; k < 2; ++k) dst[n][k] = *(const PG8_LAS bf16x8*)(lds + PG8_SB(b, h) + boff + n * 2048 + k * 1024); } while (0)
; #define PG8_MMA(ai, bj, At, Bt) do { __builtin_amdgcn_s_setprio(1); _Pragma("unroll") for (int m = 0; m < 4; ++m) _Pragma("unroll") for (int n = 0; n < 2; ++n) _Pragma("unroll") for (int k = 0; k < 2; ++k) \
;         acc[ai][bj][m][n] = __builtin_amdgcn_mfma_f32_16x16x32_bf16(Bt[n][k], At[m][k], acc[ai][bj][m][n], 0, 0, 0); __builtin_amdgcn_s_setprio(0); } while (0)
; #define PG8_WAIT_V(n) asm volatile("s_waitcnt vmcnt(" #n ")" ::: "memory")
; #define PG8_WAIT_L(n) asm volatile("s_waitcnt lgkmcnt(" #n ")" ::: "memory")
; #define PG8_BAR __builtin_amdgcn_s_barrier()
; #define PG8_SCHED __builtin_amdgcn_sched_barrier(0)
; template <class Epi, class Sched, bool ALIGN_EPI = false, bool SP2 = false>
; __device__ __forceinline__ void gemm_phase(PG8_LAS unsigned char* lds, const Gemm g, const Sched& S, const Epi& E) {
;     ...
;             PG8_WAIT_V(8); PG8_WAIT_L(0); PG8_BAR; PG8_MMA(1, 0, At, B0); PG8_MMA(1, 1, At, B1); PG8_BAR; PG8_SCHED;
;             PG8_LDB(B0, 1, 0); PG8_LDB(B1, 1, 1); PG8_SCHED; PG8_LDA(At, 1, 0); PG8_STAGE(PG8_SA(0, 1), a2 + hstep, voffA);
;             PG8_WAIT_V(8); PG8_WAIT_L(0); PG8_BAR; PG8_MMA(0, 0, At, B0); PG8_MMA(0, 1, At, B1); PG8_BAR; PG8_SCHED;
	s_setprio 1
	s_waitcnt lgkmcnt(0)
	v_mfma_f32_16x16x32_bf16 v[60:63], v[128:131], v[160:163], v[60:63]
	v_mfma_f32_16x16x32_bf16 v[56:59], v[136:139], v[160:163], v[56:59]
	v_mfma_f32_16x16x32_bf16 v[44:47], v[128:131], v[168:171], v[44:47]
	v_mfma_f32_16x16x32_bf16 v[40:43], v[136:139], v[168:171], v[40:43]
	v_mfma_f32_16x16x32_bf16 v[28:31], v[128:131], v[188:191], v[28:31]
	v_mfma_f32_16x16x32_bf16 v[24:27], v[136:139], v[188:191], v[24:27]
	v_mfma_f32_16x16x32_bf16 v[12:15], v[128:131], v[196:199], v[12:15]
	v_mfma_f32_16x16x32_bf16 v[8:11], v[136:139], v[196:199], v[8:11]
	v_mfma_f32_16x16x32_bf16 v[60:63], v[132:135], v[164:167], v[60:63]
	v_mfma_f32_16x16x32_bf16 v[56:59], v[140:143], v[164:167], v[56:59]
	v_mfma_f32_16x16x32_bf16 v[44:47], v[132:135], v[172:175], v[44:47]
	v_mfma_f32_16x16x32_bf16 v[40:43], v[140:143], v[172:175], v[40:43]
	v_mfma_f32_16x16x32_bf16 v[28:31], v[132:135], v[192:195], v[28:31]
	v_mfma_f32_16x16x32_bf16 v[24:27], v[140:143], v[192:195], v[24:27]
	v_mfma_f32_16x16x32_bf16 v[12:15], v[132:135], v[200:203], v[12:15]
	v_mfma_f32_16x16x32_bf16 v[8:11], v[140:143], v[200:203], v[8:11]
	v_mfma_f32_16x16x32_bf16 v[52:55], v[144:147], v[160:163], v[52:55]
	v_mfma_f32_16x16x32_bf16 v[48:51], v[152:155], v[160:163], v[48:51]
	v_mfma_f32_16x16x32_bf16 v[36:39], v[144:147], v[168:171], v[36:39]
	v_mfma_f32_16x16x32_bf16 v[32:35], v[152:155], v[168:171], v[32:35]
	v_mfma_f32_16x16x32_bf16 v[20:23], v[144:147], v[188:191], v[20:23]
	v_mfma_f32_16x16x32_bf16 v[16:19], v[152:155], v[188:191], v[16:19]
	v_mfma_f32_16x16x32_bf16 v[4:7], v[144:147], v[196:199], v[4:7]
	v_mfma_f32_16x16x32_bf16 v[0:3], v[152:155], v[196:199], v[0:3]
	v_mfma_f32_16x16x32_bf16 v[52:55], v[148:151], v[164:167], v[52:55]
	v_mfma_f32_16x16x32_bf16 v[48:51], v[156:159], v[164:167], v[48:51]
	v_mfma_f32_16x16x32_bf16 v[36:39], v[148:151], v[172:175], v[36:39]
	v_mfma_f32_16x16x32_bf16 v[32:35], v[156:159], v[172:175], v[32:35]
	v_mfma_f32_16x16x32_bf16 v[20:23], v[148:151], v[192:195], v[20:23]
	v_mfma_f32_16x16x32_bf16 v[16:19], v[156:159], v[192:195], v[16:19]
	v_mfma_f32_16x16x32_bf16 v[4:7], v[148:151], v[200:203], v[4:7]
	v_mfma_f32_16x16x32_bf16 v[0:3], v[156:159], v[200:203], v[0:3]
	s_setprio 0
	s_barrier
	s_add_i32 s51, 0, 0x18000
	s_add_i32 s52, 0, 0x1c000
	v_add_u32_e32 v140, s51, v207
	v_add_u32_e32 v156, s52, v207
	ds_read_b128 v[128:131], v140
	ds_read_b128 v[132:135], v140 offset:1024
	ds_read_b128 v[136:139], v140 offset:2048
	ds_read_b128 v[140:143], v140 offset:3072
	ds_read_b128 v[144:147], v156
	ds_read_b128 v[148:151], v156 offset:1024
	ds_read_b128 v[152:155], v156 offset:2048
	ds_read_b128 v[156:159], v156 offset:3072
	s_add_u32 s22, s28, 0x160000
	s_addc_u32 s23, s29, 0
	s_mov_b32 m0, s33
	v_lshl_add_u64 v[218:219], s[22:23], 0, v[176:177]
	ds_read_b128 v[160:163], v211 offset:32768
	ds_read_b128 v[164:167], v211 offset:33792
	ds_read_b128 v[168:171], v211 offset:34816
	ds_read_b128 v[172:175], v211 offset:35840
	ds_read_b128 v[188:191], v211 offset:36864
	ds_read_b128 v[192:195], v211 offset:37888
	ds_read_b128 v[196:199], v211 offset:38912
	ds_read_b128 v[200:203], v211 offset:39936
	global_load_lds_dwordx4 v[218:219], off
	v_lshl_add_u64 v[218:219], s[22:23], 0, v[178:179]
	s_mov_b32 m0, s35
	s_nop 0
	global_load_lds_dwordx4 v[218:219], off
	s_waitcnt vmcnt(8)
	s_waitcnt lgkmcnt(0)
	s_barrier
	s_setprio 1
	s_waitcnt lgkmcnt(0)
	v_mfma_f32_16x16x32_bf16 v[124:127], v[128:131], v[160:163], v[124:127]
	v_mfma_f32_16x16x32_bf16 v[120:123], v[136:139], v[160:163], v[120:123]
	v_mfma_f32_16x16x32_bf16 v[108:111], v[128:131], v[168:171], v[108:111]
	v_mfma_f32_16x16x32_bf16 v[104:107], v[136:139], v[168:171], v[104:107]
	v_mfma_f32_16x16x32_bf16 v[92:95], v[128:131], v[188:191], v[92:95]
	v_mfma_f32_16x16x32_bf16 v[88:91], v[136:139], v[188:191], v[88:91]
	v_mfma_f32_16x16x32_bf16 v[76:79], v[128:131], v[196:199], v[76:79]
	v_mfma_f32_16x16x32_bf16 v[72:75], v[136:139], v[196:199], v[72:75]
	v_mfma_f32_16x16x32_bf16 v[124:127], v[132:135], v[164:167], v[124:127]
	v_mfma_f32_16x16x32_bf16 v[120:123], v[140:143], v[164:167], v[120:123]
	v_mfma_f32_16x16x32_bf16 v[108:111], v[132:135], v[172:175], v[108:111]
	v_mfma_f32_16x16x32_bf16 v[104:107], v[140:143], v[172:175], v[104:107]
	v_mfma_f32_16x16x32_bf16 v[92:95], v[132:135], v[192:195], v[92:95]
	v_mfma_f32_16x16x32_bf16 v[88:91], v[140:143], v[192:195], v[88:91]
	v_mfma_f32_16x16x32_bf16 v[76:79], v[132:135], v[200:203], v[76:79]
	v_mfma_f32_16x16x32_bf16 v[72:75], v[140:143], v[200:203], v[72:75]
	v_mfma_f32_16x16x32_bf16 v[116:119], v[144:147], v[160:163], v[116:119]
	v_mfma_f32_16x16x32_bf16 v[112:115], v[152:155], v[160:163], v[112:115]
	v_mfma_f32_16x16x32_bf16 v[100:103], v[144:147], v[168:171], v[100:103]
	v_mfma_f32_16x16x32_bf16 v[96:99], v[152:155], v[168:171], v[96:99]
	v_mfma_f32_16x16x32_bf16 v[84:87], v[144:147], v[188:191], v[84:87]
	v_mfma_f32_16x16x32_bf16 v[80:83], v[152:155], v[188:191], v[80:83]
	v_mfma_f32_16x16x32_bf16 v[68:71], v[144:147], v[196:199], v[68:71]
	v_mfma_f32_16x16x32_bf16 v[64:67], v[152:155], v[196:199], v[64:67]
	v_mfma_f32_16x16x32_bf16 v[116:119], v[148:151], v[164:167], v[116:119]
	v_mfma_f32_16x16x32_bf16 v[112:115], v[156:159], v[164:167], v[112:115]
	v_mfma_f32_16x16x32_bf16 v[100:103], v[148:151], v[172:175], v[100:103]
	v_mfma_f32_16x16x32_bf16 v[96:99], v[156:159], v[172:175], v[96:99]
	v_mfma_f32_16x16x32_bf16 v[84:87], v[148:151], v[192:195], v[84:87]
	v_mfma_f32_16x16x32_bf16 v[80:83], v[156:159], v[192:195], v[80:83]
	v_mfma_f32_16x16x32_bf16 v[68:71], v[148:151], v[200:203], v[68:71]
	v_mfma_f32_16x16x32_bf16 v[64:67], v[156:159], v[200:203], v[64:67]
	s_setprio 0
	s_barrier
; #define PG8_STAGE(bufoff, gbase, voff) do { _Pragma("unroll") for (int _i = 0; _i < 2; ++_i) \
;         __builtin_amdgcn_global_load_lds((const unsigned*)((const char*)(gbase) + (voff)[_i]), (PG8_LAS unsigned*)(lds + (bufoff) + ldsw + _i * 8192), 16, 0, 0); } while (0)
; #define PG8_LDA(dst, b, h) do { _Pragma("unroll") for (int m = 0; m < 4; ++m) _Pragma("unroll") for (int k = 0; k < 2; ++k) dst[m][k] = *(const PG8_LAS bf16x8*)(lds + PG8_SA(b, h) + aoff + m * 2048 + k * 1024); } while (0)
; #define PG8_MMA(ai, bj, At, Bt) do { __builtin_amdgcn_s_setprio(1); _Pragma("unroll") for (int m = 0; m < 4; ++m) _Pragma("unroll") for (int n = 0; n < 2; ++n) _Pragma("unroll") for (int k = 0; k < 2; ++k) \
;         acc[ai][bj][m][n] = __builtin_amdgcn_mfma_f32_16x16x32_bf16(Bt[n][k], At[m][k], acc[ai][bj][m][n], 0, 0, 0); __builtin_amdgcn_s_setprio(0); } while (0)
; #define PG8_WAIT_V(n) asm volatile("s_waitcnt vmcnt(" #n ")" ::: "memory")
; #define PG8_WAIT_L(n) asm volatile("s_waitcnt lgkmcnt(" #n ")" ::: "memory")
; #define PG8_BAR __builtin_amdgcn_s_barrier()
; #define PG8_SCHED __builtin_amdgcn_sched_barrier(0)
; template <class Epi, class Sched, bool ALIGN_EPI = false, bool SP2 = false>
; __device__ __forceinline__ void gemm_phase(PG8_LAS unsigned char* lds, const Gemm g, const Sched& S, const Epi& E) {
;     ...
;             PG8_LDA(At, 1, 1); PG8_STAGE(PG8_SB(1, 0), b3, voffB); PG8_STAGE(PG8_SB(1, 1), b3 + hstep, voffB); PG8_STAGE(PG8_SA(1, 0), a3, voffA);
;             PG8_WAIT_V(8); PG8_WAIT_L(0); PG8_BAR; PG8_MMA(1, 0, At, B0); PG8_MMA(1, 1, At, B1); PG8_BAR; PG8_SCHED;
;     ...
;         if constexpr (ALIGN_EPI) { if (wr == 0) PG8_BAR; }
	s_add_i32 s22, s51, s3
	v_lshl_add_u64 v[204:205], v[204:205], 0, s[16:17]
	s_mov_b32 m0, s22
	ds_read_b128 v[160:163], v211 offset:49152
	ds_read_b128 v[164:167], v211 offset:50176
	ds_read_b128 v[168:171], v211 offset:51200
	ds_read_b128 v[172:175], v211 offset:52224
	ds_read_b128 v[188:191], v211 offset:53248
	ds_read_b128 v[192:195], v211 offset:54272
	ds_read_b128 v[196:199], v211 offset:55296
	ds_read_b128 v[200:203], v211 offset:56320
	global_load_lds_dwordx4 v[204:205], off
	s_add_i32 m0, s22, 0x2000
	s_add_u32 s22, s24, 0x160080
	v_lshl_add_u64 v[204:205], v[212:213], 0, s[16:17]
	s_addc_u32 s23, s25, 0
	s_add_i32 s24, s52, s3
	global_load_lds_dwordx4 v[204:205], off
	v_lshl_add_u64 v[204:205], s[22:23], 0, v[176:177]
	s_mov_b32 m0, s24
	s_nop 0
	global_load_lds_dwordx4 v[204:205], off
	v_lshl_add_u64 v[204:205], s[22:23], 0, v[178:179]
	s_add_i32 m0, s24, 0x2000
	s_nop 0
	global_load_lds_dwordx4 v[204:205], off
	v_lshl_add_u64 v[204:205], v[214:215], 0, s[16:17]
	s_mov_b32 m0, s37
	s_nop 0
	global_load_lds_dwordx4 v[204:205], off
	v_lshl_add_u64 v[204:205], v[216:217], 0, s[16:17]
	s_mov_b32 m0, s38
	s_nop 0
	global_load_lds_dwordx4 v[204:205], off
	s_waitcnt vmcnt(8)
	s_waitcnt lgkmcnt(0)
	s_barrier
	s_setprio 1
	s_waitcnt lgkmcnt(0)
	v_mfma_f32_16x16x32_bf16 v[60:63], v[128:131], v[160:163], v[60:63]
	v_mfma_f32_16x16x32_bf16 v[56:59], v[136:139], v[160:163], v[56:59]
	v_mfma_f32_16x16x32_bf16 v[44:47], v[128:131], v[168:171], v[44:47]
	v_mfma_f32_16x16x32_bf16 v[40:43], v[136:139], v[168:171], v[40:43]
	v_mfma_f32_16x16x32_bf16 v[28:31], v[128:131], v[188:191], v[28:31]
	v_mfma_f32_16x16x32_bf16 v[24:27], v[136:139], v[188:191], v[24:27]
	v_mfma_f32_16x16x32_bf16 v[12:15], v[128:131], v[196:199], v[12:15]
	v_mfma_f32_16x16x32_bf16 v[8:11], v[136:139], v[196:199], v[8:11]
	v_mfma_f32_16x16x32_bf16 v[60:63], v[132:135], v[164:167], v[60:63]
	v_mfma_f32_16x16x32_bf16 v[56:59], v[140:143], v[164:167], v[56:59]
	v_mfma_f32_16x16x32_bf16 v[44:47], v[132:135], v[172:175], v[44:47]
	v_mfma_f32_16x16x32_bf16 v[40:43], v[140:143], v[172:175], v[40:43]
	v_mfma_f32_16x16x32_bf16 v[28:31], v[132:135], v[192:195], v[28:31]
	v_mfma_f32_16x16x32_bf16 v[24:27], v[140:143], v[192:195], v[24:27]
	v_mfma_f32_16x16x32_bf16 v[12:15], v[132:135], v[200:203], v[12:15]
	v_mfma_f32_16x16x32_bf16 v[8:11], v[140:143], v[200:203], v[8:11]
	v_mfma_f32_16x16x32_bf16 v[52:55], v[144:147], v[160:163], v[52:55]
	v_mfma_f32_16x16x32_bf16 v[48:51], v[152:155], v[160:163], v[48:51]
	v_mfma_f32_16x16x32_bf16 v[36:39], v[144:147], v[168:171], v[36:39]
	v_mfma_f32_16x16x32_bf16 v[32:35], v[152:155], v[168:171], v[32:35]
	v_mfma_f32_16x16x32_bf16 v[20:23], v[144:147], v[188:191], v[20:23]
	v_mfma_f32_16x16x32_bf16 v[16:19], v[152:155], v[188:191], v[16:19]
	v_mfma_f32_16x16x32_bf16 v[4:7], v[144:147], v[196:199], v[4:7]
	v_mfma_f32_16x16x32_bf16 v[0:3], v[152:155], v[196:199], v[0:3]
	v_mfma_f32_16x16x32_bf16 v[52:55], v[148:151], v[164:167], v[52:55]
	v_mfma_f32_16x16x32_bf16 v[48:51], v[156:159], v[164:167], v[48:51]
	v_mfma_f32_16x16x32_bf16 v[36:39], v[148:151], v[172:175], v[36:39]
	v_mfma_f32_16x16x32_bf16 v[32:35], v[156:159], v[172:175], v[32:35]
	v_mfma_f32_16x16x32_bf16 v[20:23], v[148:151], v[192:195], v[20:23]
	v_mfma_f32_16x16x32_bf16 v[16:19], v[156:159], v[192:195], v[16:19]
	v_mfma_f32_16x16x32_bf16 v[4:7], v[148:151], v[200:203], v[4:7]
	v_mfma_f32_16x16x32_bf16 v[0:3], v[156:159], v[200:203], v[0:3]
	s_setprio 0
	s_barrier
	s_add_i32 s50, s50, 2
	s_add_u32 s48, s48, 0x100
	s_addc_u32 s49, s49, 0
	s_cmpk_gt_u32 s50, 0x55
	s_mov_b64 s[22:23], s[0:1]
	s_cbranch_scc0 .LBB0_1965
	s_and_b64 vcc, exec, s[18:19]
	s_cbranch_vccz .LBB0_1968
	s_barrier

; #define PG8_STAGE(bufoff, gbase, voff) do { _Pragma("unroll") for (int _i = 0; _i < 2; ++_i) \
;         __builtin_amdgcn_global_load_lds((const unsigned*)((const char*)(gbase) + (voff)[_i]), (PG8_LAS unsigned*)(lds + (bufoff) + ldsw + _i * 8192), 16, 0, 0); } while (0)
; #define PG8_LDA(dst, b, h) do { _Pragma("unroll") for (int m = 0; m < 4; ++m) _Pragma("unroll") for (int k = 0; k < 2; ++k) dst[m][k] = *(const PG8_LAS bf16x8*)(lds + PG8_SA(b, h) + aoff + m * 2048 + k * 1024); } while (0)
; #define PG8_LDB(dst, b, h) do { _Pragma("unroll") for (int n = 0; n < 2; ++n) _Pragma("unroll") for (int k = 0; k < 2; ++k) dst[n][k] = *(const PG8_LAS bf16x8*)(lds + PG8_SB(b, h) + boff + n * 2048 + k * 1024); } while (0)
; #define PG8_MMA(ai, bj, At, Bt) do { __builtin_amdgcn_s_setprio(1); _Pragma("unroll") for (int m = 0; m < 4; ++m) _Pragma("unroll") for (int n = 0; n < 2; ++n) _Pragma("unroll") for (int k = 0; k < 2; ++k) \
;         acc[ai][bj][m][n] = __builtin_amdgcn_mfma_f32_16x16x32_bf16(Bt[n][k], At[m][k], acc[ai][bj][m][n], 0, 0, 0); __builtin_amdgcn_s_setprio(0); } while (0)
; #define PG8_WAIT_V(n) asm volatile("s_waitcnt vmcnt(" #n ")" ::: "memory")
; #define PG8_WAIT_L(n) asm volatile("s_waitcnt lgkmcnt(" #n ")" ::: "memory")
; template <class Epi, class Sched, bool ALIGN_EPI = false, bool SP2 = false>
; __device__ __forceinline__ void gemm_phase(PG8_LAS unsigned char* lds, const Gemm g, const Sched& S, const Epi& E) {
;     ...
;             const bool last = (t == nt - 2);
;             const char* a1 = cA + (size_t)(t + 1) * kstep;
;             const char* a2 = last ? nA : cA + (size_t)(t + 2) * kstep; const char* b2 = last ? nB : cB + (size_t)(t + 2) * kstep;
;             const char* a3 = a2 + kstep; const char* b3 = b2 + kstep;
;             if (last && has_next) S.a_ready(nxt);
;             if constexpr (SP2) {
;             PG8_LDB(B0, 0, 0); PG8_LDB(B1, 0, 1); PG8_SCHED; PG8_LDA(At, 0, 0); PG8_STAGE(PG8_SA(1, 1), a1 + hstep, voffA);
;             PG8_WAIT_V(8); PG8_WAIT_L(0); PG8_BAR; PG8_MMA(0, 0, At, B0); PG8_MMA(0, 1, At, B1); PG8_BAR; PG8_SCHED;
;             PG8_LDA(At, 0, 1); PG8_STAGE(PG8_SB(0, 0), b2, voffB); PG8_STAGE(PG8_SB(0, 1), b2 + hstep, voffB); PG8_STAGE(PG8_SA(0, 0), a2, voffA);
;             PG8_WAIT_V(8); PG8_WAIT_L(0); PG8_BAR; PG8_MMA(1, 0, At, B0); PG8_MMA(1, 1, At, B1); PG8_BAR; PG8_SCHED;
.LBB0_2053:
	ds_read_b128 v[128:131], v225
	ds_read_b128 v[132:135], v225 offset:1024
	ds_read_b128 v[136:139], v225 offset:2048
	ds_read_b128 v[140:143], v225 offset:3072
	ds_read_b128 v[144:147], v228
	ds_read_b128 v[148:151], v228 offset:1024
	ds_read_b128 v[152:155], v228 offset:2048
	ds_read_b128 v[156:159], v228 offset:3072
	s_add_u32 s24, s22, 0x100
	s_addc_u32 s25, s23, 0
	s_cmpk_eq_i32 s55, 0x54
	s_cselect_b32 s31, s21, s25
	s_cselect_b32 s30, s20, s24
	s_cselect_b32 s29, s9, s7
	s_cselect_b32 s28, s8, s6
	s_mov_b32 m0, s43
	v_lshl_add_u64 v[204:205], s[22:23], 0, v[184:185]
	ds_read_b128 v[160:163], v229
	ds_read_b128 v[164:167], v229 offset:1024
	ds_read_b128 v[168:171], v229 offset:2048
	ds_read_b128 v[172:175], v229 offset:3072
	ds_read_b128 v[188:191], v229 offset:4096
	ds_read_b128 v[192:195], v229 offset:5120
	ds_read_b128 v[196:199], v229 offset:6144
	ds_read_b128 v[200:203], v229 offset:7168
	global_load_lds_dwordx4 v[204:205], off
	v_lshl_add_u64 v[204:205], s[22:23], 0, v[186:187]
	s_mov_b32 m0, s44
	s_nop 0
	global_load_lds_dwordx4 v[204:205], off
	s_waitcnt vmcnt(8)
	s_waitcnt lgkmcnt(0)
	s_barrier
	s_setprio 1
	s_waitcnt lgkmcnt(0)
	v_mfma_f32_16x16x32_bf16 v[124:127], v[128:131], v[160:163], v[124:127]
	v_mfma_f32_16x16x32_bf16 v[120:123], v[136:139], v[160:163], v[120:123]
	v_mfma_f32_16x16x32_bf16 v[108:111], v[128:131], v[168:171], v[108:111]
	v_mfma_f32_16x16x32_bf16 v[104:107], v[136:139], v[168:171], v[104:107]
	v_mfma_f32_16x16x32_bf16 v[96:99], v[128:131], v[188:191], v[96:99]
	v_mfma_f32_16x16x32_bf16 v[88:91], v[136:139], v[188:191], v[88:91]
	v_mfma_f32_16x16x32_bf16 v[80:83], v[128:131], v[196:199], v[80:83]
	v_mfma_f32_16x16x32_bf16 v[72:75], v[136:139], v[196:199], v[72:75]
	v_mfma_f32_16x16x32_bf16 v[124:127], v[132:135], v[164:167], v[124:127]
	v_mfma_f32_16x16x32_bf16 v[120:123], v[140:143], v[164:167], v[120:123]
	v_mfma_f32_16x16x32_bf16 v[108:111], v[132:135], v[172:175], v[108:111]
	v_mfma_f32_16x16x32_bf16 v[104:107], v[140:143], v[172:175], v[104:107]
	v_mfma_f32_16x16x32_bf16 v[96:99], v[132:135], v[192:195], v[96:99]
	v_mfma_f32_16x16x32_bf16 v[88:91], v[140:143], v[192:195], v[88:91]
	v_mfma_f32_16x16x32_bf16 v[80:83], v[132:135], v[200:203], v[80:83]
	v_mfma_f32_16x16x32_bf16 v[72:75], v[140:143], v[200:203], v[72:75]
	v_mfma_f32_16x16x32_bf16 v[116:119], v[144:147], v[160:163], v[116:119]
	v_mfma_f32_16x16x32_bf16 v[112:115], v[152:155], v[160:163], v[112:115]
	v_mfma_f32_16x16x32_bf16 v[100:103], v[144:147], v[168:171], v[100:103]
	v_mfma_f32_16x16x32_bf16 v[92:95], v[152:155], v[168:171], v[92:95]
	v_mfma_f32_16x16x32_bf16 v[84:87], v[144:147], v[188:191], v[84:87]
	v_mfma_f32_16x16x32_bf16 v[76:79], v[152:155], v[188:191], v[76:79]
	v_mfma_f32_16x16x32_bf16 v[68:71], v[144:147], v[196:199], v[68:71]
	v_mfma_f32_16x16x32_bf16 v[64:67], v[152:155], v[196:199], v[64:67]
	v_mfma_f32_16x16x32_bf16 v[116:119], v[148:151], v[164:167], v[116:119]
	v_mfma_f32_16x16x32_bf16 v[112:115], v[156:159], v[164:167], v[112:115]
	v_mfma_f32_16x16x32_bf16 v[100:103], v[148:151], v[172:175], v[100:103]
	v_mfma_f32_16x16x32_bf16 v[92:95], v[156:159], v[172:175], v[92:95]
	v_mfma_f32_16x16x32_bf16 v[84:87], v[148:151], v[192:195], v[84:87]
	v_mfma_f32_16x16x32_bf16 v[76:79], v[156:159], v[192:195], v[76:79]
	v_mfma_f32_16x16x32_bf16 v[68:71], v[148:151], v[200:203], v[68:71]
	v_mfma_f32_16x16x32_bf16 v[64:67], v[156:159], v[200:203], v[64:67]
	s_setprio 0
	s_barrier
	s_mov_b32 m0, s45
	v_lshl_add_u64 v[204:205], s[28:29], 0, v[176:177]
	s_add_u32 s22, s28, 0x160000
	ds_read_b128 v[160:163], v229 offset:16384
	ds_read_b128 v[164:167], v229 offset:17408
	ds_read_b128 v[168:171], v229 offset:18432
	ds_read_b128 v[172:175], v229 offset:19456
	ds_read_b128 v[188:191], v229 offset:20480
	ds_read_b128 v[192:195], v229 offset:21504
	ds_read_b128 v[196:199], v229 offset:22528
	ds_read_b128 v[200:203], v229 offset:23552
	global_load_lds_dwordx4 v[204:205], off
	v_lshl_add_u64 v[206:207], s[28:29], 0, v[178:179]
	s_mov_b32 m0, s46
	s_addc_u32 s23, s29, 0
	global_load_lds_dwordx4 v[206:207], off
	v_lshl_add_u64 v[208:209], s[22:23], 0, v[176:177]
	s_mov_b32 m0, s47
	v_lshl_add_u64 v[210:211], s[30:31], 0, v[178:179]
	global_load_lds_dwordx4 v[208:209], off
	v_lshl_add_u64 v[208:209], s[22:23], 0, v[178:179]
	s_mov_b32 m0, s48
	s_nop 0
	global_load_lds_dwordx4 v[208:209], off
	v_lshl_add_u64 v[208:209], s[30:31], 0, v[176:177]
	s_mov_b32 m0, s34
	s_nop 0
	global_load_lds_dwordx4 v[208:209], off
	s_mov_b32 m0, s35
	s_nop 0
	global_load_lds_dwordx4 v[210:211], off
	s_waitcnt vmcnt(8)
	s_waitcnt lgkmcnt(0)
	s_barrier
; #define PG8_STAGE(bufoff, gbase, voff) do { _Pragma("unroll") for (int _i = 0; _i < 2; ++_i) \
;         __builtin_amdgcn_global_load_lds((const unsigned*)((const char*)(gbase) + (voff)[_i]), (PG8_LAS unsigned*)(lds + (bufoff) + ldsw + _i * 8192), 16, 0, 0); } while (0)
; #define PG8_LDA(dst, b, h) do { _Pragma("unroll") for (int m = 0; m < 4; ++m) _Pragma("unroll") for (int k = 0; k < 2; ++k) dst[m][k] = *(const PG8_LAS bf16x8*)(lds + PG8_SA(b, h) + aoff + m * 2048 + k * 1024); } while (0)
; #define PG8_LDB(dst, b, h) do { _Pragma("unroll") for (int n = 0; n < 2; ++n) _Pragma("unroll") for (int k = 0; k < 2; ++k) dst[n][k] = *(const PG8_LAS bf16x8*)(lds + PG8_SB(b, h) + boff + n * 2048 + k * 1024); } while (0)
; #define PG8_MMA(ai, bj, At, Bt) do { __builtin_amdgcn_s_setprio(1); _Pragma("unroll") for (int m = 0; m < 4; ++m) _Pragma("unroll") for (int n = 0; n < 2; ++n) _Pragma("unroll") for (int k = 0; k < 2; ++k) \
;         acc[ai][bj][m][n] = __builtin_amdgcn_mfma_f32_16x16x32_bf16(Bt[n][k], At[m][k], acc[ai][bj][m][n], 0, 0, 0); __builtin_amdgcn_s_setprio(0); } while (0)
; #define PG8_WAIT_V(n) asm volatile("s_waitcnt vmcnt(" #n ")" ::: "memory")
; #define PG8_WAIT_L(n) asm volatile("s_waitcnt lgkmcnt(" #n ")" ::: "memory")
; #define PG8_BAR __builtin_amdgcn_s_barrier()
; #define PG8_SCHED __builtin_amdgcn_sched_barrier(0)
; template <class Epi, class Sched, bool ALIGN_EPI = false, bool SP2 = false>
; __device__ __forceinline__ void gemm_phase(PG8_LAS unsigned char* lds, const Gemm g, const Sched& S, const Epi& E) {
;     ...
;             PG8_WAIT_V(8); PG8_WAIT_L(0); PG8_BAR; PG8_MMA(1, 0, At, B0); PG8_MMA(1, 1, At, B1); PG8_BAR; PG8_SCHED;
;             PG8_LDB(B0, 1, 0); PG8_LDB(B1, 1, 1); PG8_SCHED; PG8_LDA(At, 1, 0); PG8_STAGE(PG8_SA(0, 1), a2 + hstep, voffA);
;             PG8_WAIT_V(8); PG8_WAIT_L(0); PG8_BAR; PG8_MMA(0, 0, At, B0); PG8_MMA(0, 1, At, B1); PG8_BAR; PG8_SCHED;
	s_setprio 1
	s_waitcnt lgkmcnt(0)
	v_mfma_f32_16x16x32_bf16 v[60:63], v[128:131], v[160:163], v[60:63]
	v_mfma_f32_16x16x32_bf16 v[56:59], v[136:139], v[160:163], v[56:59]
	v_mfma_f32_16x16x32_bf16 v[44:47], v[128:131], v[168:171], v[44:47]
	v_mfma_f32_16x16x32_bf16 v[40:43], v[136:139], v[168:171], v[40:43]
	v_mfma_f32_16x16x32_bf16 v[32:35], v[128:131], v[188:191], v[32:35]
	v_mfma_f32_16x16x32_bf16 v[24:27], v[136:139], v[188:191], v[24:27]
	v_mfma_f32_16x16x32_bf16 v[16:19], v[128:131], v[196:199], v[16:19]
	v_mfma_f32_16x16x32_bf16 v[8:11], v[136:139], v[196:199], v[8:11]
	v_mfma_f32_16x16x32_bf16 v[60:63], v[132:135], v[164:167], v[60:63]
	v_mfma_f32_16x16x32_bf16 v[56:59], v[140:143], v[164:167], v[56:59]
	v_mfma_f32_16x16x32_bf16 v[44:47], v[132:135], v[172:175], v[44:47]
	v_mfma_f32_16x16x32_bf16 v[40:43], v[140:143], v[172:175], v[40:43]
	v_mfma_f32_16x16x32_bf16 v[32:35], v[132:135], v[192:195], v[32:35]
	v_mfma_f32_16x16x32_bf16 v[24:27], v[140:143], v[192:195], v[24:27]
	v_mfma_f32_16x16x32_bf16 v[16:19], v[132:135], v[200:203], v[16:19]
	v_mfma_f32_16x16x32_bf16 v[8:11], v[140:143], v[200:203], v[8:11]
	v_mfma_f32_16x16x32_bf16 v[52:55], v[144:147], v[160:163], v[52:55]
	v_mfma_f32_16x16x32_bf16 v[48:51], v[152:155], v[160:163], v[48:51]
	v_mfma_f32_16x16x32_bf16 v[36:39], v[144:147], v[168:171], v[36:39]
	v_mfma_f32_16x16x32_bf16 v[28:31], v[152:155], v[168:171], v[28:31]
	v_mfma_f32_16x16x32_bf16 v[20:23], v[144:147], v[188:191], v[20:23]
	v_mfma_f32_16x16x32_bf16 v[12:15], v[152:155], v[188:191], v[12:15]
	v_mfma_f32_16x16x32_bf16 v[4:7], v[144:147], v[196:199], v[4:7]
	v_mfma_f32_16x16x32_bf16 v[0:3], v[152:155], v[196:199], v[0:3]
	v_mfma_f32_16x16x32_bf16 v[52:55], v[148:151], v[164:167], v[52:55]
	v_mfma_f32_16x16x32_bf16 v[48:51], v[156:159], v[164:167], v[48:51]
	v_mfma_f32_16x16x32_bf16 v[36:39], v[148:151], v[172:175], v[36:39]
	v_mfma_f32_16x16x32_bf16 v[28:31], v[156:159], v[172:175], v[28:31]
	v_mfma_f32_16x16x32_bf16 v[20:23], v[148:151], v[192:195], v[20:23]
	v_mfma_f32_16x16x32_bf16 v[12:15], v[156:159], v[192:195], v[12:15]
	v_mfma_f32_16x16x32_bf16 v[4:7], v[148:151], v[200:203], v[4:7]
	v_mfma_f32_16x16x32_bf16 v[0:3], v[156:159], v[200:203], v[0:3]
	s_setprio 0
	s_barrier
	ds_read_b128 v[128:131], v232
	ds_read_b128 v[132:135], v232 offset:1024
	ds_read_b128 v[136:139], v232 offset:2048
	ds_read_b128 v[140:143], v232 offset:3072
	ds_read_b128 v[144:147], v233
	ds_read_b128 v[148:151], v233 offset:1024
	ds_read_b128 v[152:155], v233 offset:2048
	ds_read_b128 v[156:159], v233 offset:3072
	s_add_u32 s22, s30, 0x160000
	s_addc_u32 s23, s31, 0
	s_mov_b32 m0, s36
	v_lshl_add_u64 v[212:213], s[22:23], 0, v[176:177]
	ds_read_b128 v[160:163], v229 offset:32768
	ds_read_b128 v[164:167], v229 offset:33792
	ds_read_b128 v[168:171], v229 offset:34816
	ds_read_b128 v[172:175], v229 offset:35840
	ds_read_b128 v[188:191], v229 offset:36864
	ds_read_b128 v[192:195], v229 offset:37888
	ds_read_b128 v[196:199], v229 offset:38912
	ds_read_b128 v[200:203], v229 offset:39936
	global_load_lds_dwordx4 v[212:213], off
	v_lshl_add_u64 v[212:213], s[22:23], 0, v[178:179]
	s_mov_b32 m0, s37
	s_nop 0
	global_load_lds_dwordx4 v[212:213], off
	s_waitcnt vmcnt(8)
	s_waitcnt lgkmcnt(0)
	s_barrier
	s_setprio 1
	s_waitcnt lgkmcnt(0)
	v_mfma_f32_16x16x32_bf16 v[124:127], v[128:131], v[160:163], v[124:127]
	v_mfma_f32_16x16x32_bf16 v[120:123], v[136:139], v[160:163], v[120:123]
	v_mfma_f32_16x16x32_bf16 v[108:111], v[128:131], v[168:171], v[108:111]
	v_mfma_f32_16x16x32_bf16 v[104:107], v[136:139], v[168:171], v[104:107]
	v_mfma_f32_16x16x32_bf16 v[96:99], v[128:131], v[188:191], v[96:99]
	v_mfma_f32_16x16x32_bf16 v[88:91], v[136:139], v[188:191], v[88:91]
	v_mfma_f32_16x16x32_bf16 v[80:83], v[128:131], v[196:199], v[80:83]
	v_mfma_f32_16x16x32_bf16 v[72:75], v[136:139], v[196:199], v[72:75]
	v_mfma_f32_16x16x32_bf16 v[124:127], v[132:135], v[164:167], v[124:127]
	v_mfma_f32_16x16x32_bf16 v[120:123], v[140:143], v[164:167], v[120:123]
	v_mfma_f32_16x16x32_bf16 v[108:111], v[132:135], v[172:175], v[108:111]
	v_mfma_f32_16x16x32_bf16 v[104:107], v[140:143], v[172:175], v[104:107]
	v_mfma_f32_16x16x32_bf16 v[96:99], v[132:135], v[192:195], v[96:99]
	v_mfma_f32_16x16x32_bf16 v[88:91], v[140:143], v[192:195], v[88:91]
	v_mfma_f32_16x16x32_bf16 v[80:83], v[132:135], v[200:203], v[80:83]
	v_mfma_f32_16x16x32_bf16 v[72:75], v[140:143], v[200:203], v[72:75]
	v_mfma_f32_16x16x32_bf16 v[116:119], v[144:147], v[160:163], v[116:119]
	v_mfma_f32_16x16x32_bf16 v[112:115], v[152:155], v[160:163], v[112:115]
	v_mfma_f32_16x16x32_bf16 v[100:103], v[144:147], v[168:171], v[100:103]
	v_mfma_f32_16x16x32_bf16 v[92:95], v[152:155], v[168:171], v[92:95]
	v_mfma_f32_16x16x32_bf16 v[84:87], v[144:147], v[188:191], v[84:87]
	v_mfma_f32_16x16x32_bf16 v[76:79], v[152:155], v[188:191], v[76:79]
	v_mfma_f32_16x16x32_bf16 v[68:71], v[144:147], v[196:199], v[68:71]
	v_mfma_f32_16x16x32_bf16 v[64:67], v[152:155], v[196:199], v[64:67]
	v_mfma_f32_16x16x32_bf16 v[116:119], v[148:151], v[164:167], v[116:119]
	v_mfma_f32_16x16x32_bf16 v[112:115], v[156:159], v[164:167], v[112:115]
	v_mfma_f32_16x16x32_bf16 v[100:103], v[148:151], v[172:175], v[100:103]
	v_mfma_f32_16x16x32_bf16 v[92:95], v[156:159], v[172:175], v[92:95]
	v_mfma_f32_16x16x32_bf16 v[84:87], v[148:151], v[192:195], v[84:87]
	v_mfma_f32_16x16x32_bf16 v[76:79], v[156:159], v[192:195], v[76:79]
	v_mfma_f32_16x16x32_bf16 v[68:71], v[148:151], v[200:203], v[68:71]
	v_mfma_f32_16x16x32_bf16 v[64:67], v[156:159], v[200:203], v[64:67]
	s_setprio 0
	s_barrier
; #define PG8_STAGE(bufoff, gbase, voff) do { _Pragma("unroll") for (int _i = 0; _i < 2; ++_i) \
;         __builtin_amdgcn_global_load_lds((const unsigned*)((const char*)(gbase) + (voff)[_i]), (PG8_LAS unsigned*)(lds + (bufoff) + ldsw + _i * 8192), 16, 0, 0); } while (0)
; #define PG8_LDA(dst, b, h) do { _Pragma("unroll") for (int m = 0; m < 4; ++m) _Pragma("unroll") for (int k = 0; k < 2; ++k) dst[m][k] = *(const PG8_LAS bf16x8*)(lds + PG8_SA(b, h) + aoff + m * 2048 + k * 1024); } while (0)
; #define PG8_MMA(ai, bj, At, Bt) do { __builtin_amdgcn_s_setprio(1); _Pragma("unroll") for (int m = 0; m < 4; ++m) _Pragma("unroll") for (int n = 0; n < 2; ++n) _Pragma("unroll") for (int k = 0; k < 2; ++k) \
;         acc[ai][bj][m][n] = __builtin_amdgcn_mfma_f32_16x16x32_bf16(Bt[n][k], At[m][k], acc[ai][bj][m][n], 0, 0, 0); __builtin_amdgcn_s_setprio(0); } while (0)
; #define PG8_WAIT_V(n) asm volatile("s_waitcnt vmcnt(" #n ")" ::: "memory")
; #define PG8_WAIT_L(n) asm volatile("s_waitcnt lgkmcnt(" #n ")" ::: "memory")
; #define PG8_BAR __builtin_amdgcn_s_barrier()
; #define PG8_SCHED __builtin_amdgcn_sched_barrier(0)
; template <class Epi, class Sched, bool ALIGN_EPI = false, bool SP2 = false>
; __device__ __forceinline__ void gemm_phase(PG8_LAS unsigned char* lds, const Gemm g, const Sched& S, const Epi& E) {
;     ...
;             PG8_LDA(At, 1, 1); PG8_STAGE(PG8_SB(1, 0), b3, voffB); PG8_STAGE(PG8_SB(1, 1), b3 + hstep, voffB); PG8_STAGE(PG8_SA(1, 0), a3, voffA);
;             PG8_WAIT_V(8); PG8_WAIT_L(0); PG8_BAR; PG8_MMA(1, 0, At, B0); PG8_MMA(1, 1, At, B1); PG8_BAR; PG8_SCHED;
;     ...
;         if constexpr (ALIGN_EPI) { if (wr == 0) PG8_BAR; }
	s_mov_b32 m0, s49
	v_lshl_add_u64 v[204:205], v[204:205], 0, s[14:15]
	s_add_u32 s22, s28, 0x160080
	ds_read_b128 v[160:163], v229 offset:49152
	ds_read_b128 v[164:167], v229 offset:50176
	ds_read_b128 v[168:171], v229 offset:51200
	ds_read_b128 v[172:175], v229 offset:52224
	ds_read_b128 v[188:191], v229 offset:53248
	ds_read_b128 v[192:195], v229 offset:54272
	ds_read_b128 v[196:199], v229 offset:55296
	ds_read_b128 v[200:203], v229 offset:56320
	global_load_lds_dwordx4 v[204:205], off
	v_lshl_add_u64 v[204:205], v[206:207], 0, s[14:15]
	s_mov_b32 m0, s50
	s_addc_u32 s23, s29, 0
	global_load_lds_dwordx4 v[204:205], off
	v_lshl_add_u64 v[204:205], s[22:23], 0, v[176:177]
	s_mov_b32 m0, s51
	s_nop 0
	global_load_lds_dwordx4 v[204:205], off
	v_lshl_add_u64 v[204:205], s[22:23], 0, v[178:179]
	s_mov_b32 m0, s52
	s_nop 0
	global_load_lds_dwordx4 v[204:205], off
	v_lshl_add_u64 v[204:205], v[208:209], 0, s[14:15]
	s_mov_b32 m0, s38
	s_nop 0
	global_load_lds_dwordx4 v[204:205], off
	v_lshl_add_u64 v[204:205], v[210:211], 0, s[14:15]
	s_mov_b32 m0, s39
	s_nop 0
	global_load_lds_dwordx4 v[204:205], off
	s_waitcnt vmcnt(8)
	s_waitcnt lgkmcnt(0)
	s_barrier
	s_setprio 1
	s_waitcnt lgkmcnt(0)
	v_mfma_f32_16x16x32_bf16 v[60:63], v[128:131], v[160:163], v[60:63]
	v_mfma_f32_16x16x32_bf16 v[56:59], v[136:139], v[160:163], v[56:59]
	v_mfma_f32_16x16x32_bf16 v[44:47], v[128:131], v[168:171], v[44:47]
	v_mfma_f32_16x16x32_bf16 v[40:43], v[136:139], v[168:171], v[40:43]
	v_mfma_f32_16x16x32_bf16 v[32:35], v[128:131], v[188:191], v[32:35]
	v_mfma_f32_16x16x32_bf16 v[24:27], v[136:139], v[188:191], v[24:27]
	v_mfma_f32_16x16x32_bf16 v[16:19], v[128:131], v[196:199], v[16:19]
	v_mfma_f32_16x16x32_bf16 v[8:11], v[136:139], v[196:199], v[8:11]
	v_mfma_f32_16x16x32_bf16 v[60:63], v[132:135], v[164:167], v[60:63]
	v_mfma_f32_16x16x32_bf16 v[56:59], v[140:143], v[164:167], v[56:59]
	v_mfma_f32_16x16x32_bf16 v[44:47], v[132:135], v[172:175], v[44:47]
	v_mfma_f32_16x16x32_bf16 v[40:43], v[140:143], v[172:175], v[40:43]
	v_mfma_f32_16x16x32_bf16 v[32:35], v[132:135], v[192:195], v[32:35]
	v_mfma_f32_16x16x32_bf16 v[24:27], v[140:143], v[192:195], v[24:27]
	v_mfma_f32_16x16x32_bf16 v[16:19], v[132:135], v[200:203], v[16:19]
	v_mfma_f32_16x16x32_bf16 v[8:11], v[140:143], v[200:203], v[8:11]
	v_mfma_f32_16x16x32_bf16 v[52:55], v[144:147], v[160:163], v[52:55]
	v_mfma_f32_16x16x32_bf16 v[48:51], v[152:155], v[160:163], v[48:51]
	v_mfma_f32_16x16x32_bf16 v[36:39], v[144:147], v[168:171], v[36:39]
	v_mfma_f32_16x16x32_bf16 v[28:31], v[152:155], v[168:171], v[28:31]
	v_mfma_f32_16x16x32_bf16 v[20:23], v[144:147], v[188:191], v[20:23]
	v_mfma_f32_16x16x32_bf16 v[12:15], v[152:155], v[188:191], v[12:15]
	v_mfma_f32_16x16x32_bf16 v[4:7], v[144:147], v[196:199], v[4:7]
	v_mfma_f32_16x16x32_bf16 v[0:3], v[152:155], v[196:199], v[0:3]
	v_mfma_f32_16x16x32_bf16 v[52:55], v[148:151], v[164:167], v[52:55]
	v_mfma_f32_16x16x32_bf16 v[48:51], v[156:159], v[164:167], v[48:51]
	v_mfma_f32_16x16x32_bf16 v[36:39], v[148:151], v[172:175], v[36:39]
	v_mfma_f32_16x16x32_bf16 v[28:31], v[156:159], v[172:175], v[28:31]
	v_mfma_f32_16x16x32_bf16 v[20:23], v[148:151], v[192:195], v[20:23]
	v_mfma_f32_16x16x32_bf16 v[12:15], v[156:159], v[192:195], v[12:15]
	v_mfma_f32_16x16x32_bf16 v[4:7], v[148:151], v[200:203], v[4:7]
	v_mfma_f32_16x16x32_bf16 v[0:3], v[156:159], v[200:203], v[0:3]
	s_setprio 0
	s_barrier
	s_add_i32 s55, s55, 2
	s_add_u32 s6, s6, 0x100
	s_addc_u32 s7, s7, 0
	s_cmpk_gt_u32 s55, 0x55
	s_mov_b64 s[22:23], s[24:25]
	s_cbranch_scc0 .LBB0_2053
	s_and_b64 vcc, exec, s[16:17]
	s_cbranch_vccz .LBB0_2056
	s_barrier
